# GEMM K-loops: half of the LDS-DMA loads use scalar-base + lane-offset addressing (8 vector 64-bit adds per iteration removed)
# speedup vs baseline: 1.0110x; 1.0110x over previous
; #define PG8_STAGE(bufoff, gbase, voff) do { _Pragma("unroll") for (int _i = 0; _i < 2; ++_i) \
;     __builtin_amdgcn_global_load_lds((const unsigned*)((const char*)(gbase) + (voff)[_i]), (PG8_LAS unsigned*)(lds + (bufoff) + ldsw + _i * 8192), 16, 0, 0); } while (0)
; #define PG8_LDA(dst, b, h) do { _Pragma("unroll") for (int m = 0; m < 4; ++m) _Pragma("unroll") for (int k = 0; k < 2; ++k) dst[m][k] = *(const PG8_LAS bf16x8*)(lds + PG8_SA(b, h) + aoff + m * 2048 + k * 1024); } while (0)
; #define PG8_LDB(dst, b, h) do { _Pragma("unroll") for (int n = 0; n < 2; ++n) _Pragma("unroll") for (int k = 0; k < 2; ++k) dst[n][k] = *(const PG8_LAS bf16x8*)(lds + PG8_SB(b, h) + boff + n * 2048 + k * 1024); } while (0)
; #define PG8_MMA(ai, bj, At, Bt) do { __builtin_amdgcn_s_setprio(1); _Pragma("unroll") for (int m = 0; m < 4; ++m) _Pragma("unroll") for (int n = 0; n < 2; ++n) _Pragma("unroll") for (int k = 0; k < 2; ++k) \
;     acc[ai][bj][m][n] = __builtin_amdgcn_mfma_f32_16x16x32_bf16(Bt[n][k], At[m][k], acc[ai][bj][m][n], 0, 0, 0); __builtin_amdgcn_s_setprio(0); } while (0)
; #define PG8_WAIT_V(n) asm volatile("s_waitcnt vmcnt(" #n ")" ::: "memory")
; #define PG8_WAIT_L(n) asm volatile("s_waitcnt lgkmcnt(" #n ")" ::: "memory")
; #define PG8_BAR __builtin_amdgcn_s_barrier()
; #define PG8_SCHED __builtin_amdgcn_sched_barrier(0)
; template <class Epi, class Sched>
; DI void gemm_phase(PG8_LAS unsigned char* lds, const Gemm g, const Sched& S, const Epi& E) {
;     ...
;     for (int t = 0; t < nt; t += 2) {
;       const bool last = (t == nt - 2);
;       const char* a1 = cA + (size_t)(t + 1) * kstep;
;       const char* a2 = last ? nA : cA + (size_t)(t + 2) * kstep; const char* b2 = last ? nB : cB + (size_t)(t + 2) * kstep;
;       const char* a3 = a2 + kstep; const char* b3 = b2 + kstep;
;       PG8_LDB(B0, 0, 0); PG8_LDB(B1, 0, 1); PG8_SCHED; PG8_LDA(At, 0, 0); PG8_STAGE(PG8_SA(1, 1), a1 + hstepA, voffA);
;       PG8_WAIT_V(8); PG8_WAIT_L(0); PG8_BAR; PG8_MMA(0, 0, At, B0); PG8_MMA(0, 1, At, B1); PG8_BAR; PG8_SCHED;
;       PG8_LDA(At, 0, 1); PG8_STAGE(PG8_SB(0, 0), b2, voffB); PG8_STAGE(PG8_SB(0, 1), b2 + hstepB, voffB); PG8_STAGE(PG8_SA(0, 0), a2, voffA);
;       PG8_WAIT_V(8); PG8_WAIT_L(0); PG8_BAR; PG8_MMA(1, 0, At, B0); PG8_MMA(1, 1, At, B1); PG8_BAR; PG8_SCHED;
.LBB0_286:
	ds_read_b128 v[146:149], v180
	ds_read_b128 v[150:153], v180 offset:1024
	ds_read_b128 v[154:157], v180 offset:2048
	ds_read_b128 v[158:161], v180 offset:3072
	ds_read_b128 v[162:165], v181
	ds_read_b128 v[166:169], v181 offset:1024
	ds_read_b128 v[170:173], v181 offset:2048
	ds_read_b128 v[174:177], v181 offset:3072
	s_add_u32 s16, s6, 0xfffc0080
	s_addc_u32 s30, s7, -1
	s_cmp_eq_u32 s69, 12
	s_cselect_b32 s35, s1, s30
	s_cselect_b32 s34, s5, s16
	s_cselect_b32 s31, s21, s68
	s_cselect_b32 s30, s23, s67
	s_add_i32 m0, s3, 0xc000
	ds_read_b128 v[186:189], v182
	ds_read_b128 v[190:193], v182 offset:1024
	ds_read_b128 v[194:197], v182 offset:2048
	ds_read_b128 v[198:201], v182 offset:3072
	ds_read_b128 v[202:205], v182 offset:4096
	ds_read_b128 v[206:209], v182 offset:5120
	ds_read_b128 v[214:217], v182 offset:6144
	ds_read_b128 v[218:221], v182 offset:7168
	global_load_lds_dwordx4 v140, s[6:7]
	s_add_i32 m0, s3, 0xe000
	s_nop 0
	global_load_lds_dwordx4 v142, s[6:7]
	s_waitcnt vmcnt(8)
	s_waitcnt lgkmcnt(0)
	s_barrier
	s_setprio 1
	s_waitcnt lgkmcnt(0)
	v_mfma_f32_16x16x32_bf16 v[122:125], v[146:149], v[186:189], v[122:125]
	v_mfma_f32_16x16x32_bf16 v[126:129], v[154:157], v[186:189], v[126:129]
	v_mfma_f32_16x16x32_bf16 v[106:109], v[146:149], v[194:197], v[106:109]
	v_mfma_f32_16x16x32_bf16 v[110:113], v[154:157], v[194:197], v[110:113]
	v_mfma_f32_16x16x32_bf16 v[90:93], v[146:149], v[202:205], v[90:93]
	v_mfma_f32_16x16x32_bf16 v[94:97], v[154:157], v[202:205], v[94:97]
	v_mfma_f32_16x16x32_bf16 v[74:77], v[146:149], v[214:217], v[74:77]
	v_mfma_f32_16x16x32_bf16 v[78:81], v[154:157], v[214:217], v[78:81]
	v_mfma_f32_16x16x32_bf16 v[122:125], v[150:153], v[190:193], v[122:125]
	v_mfma_f32_16x16x32_bf16 v[126:129], v[158:161], v[190:193], v[126:129]
	v_mfma_f32_16x16x32_bf16 v[106:109], v[150:153], v[198:201], v[106:109]
	v_mfma_f32_16x16x32_bf16 v[110:113], v[158:161], v[198:201], v[110:113]
	v_mfma_f32_16x16x32_bf16 v[90:93], v[150:153], v[206:209], v[90:93]
	v_mfma_f32_16x16x32_bf16 v[94:97], v[158:161], v[206:209], v[94:97]
	v_mfma_f32_16x16x32_bf16 v[74:77], v[150:153], v[218:221], v[74:77]
	v_mfma_f32_16x16x32_bf16 v[78:81], v[158:161], v[218:221], v[78:81]
	s_setprio 0
	s_setprio 1
	v_mfma_f32_16x16x32_bf16 v[114:117], v[162:165], v[186:189], v[114:117]
	v_mfma_f32_16x16x32_bf16 v[118:121], v[170:173], v[186:189], v[118:121]
	v_mfma_f32_16x16x32_bf16 v[98:101], v[162:165], v[194:197], v[98:101]
	v_mfma_f32_16x16x32_bf16 v[102:105], v[170:173], v[194:197], v[102:105]
	v_mfma_f32_16x16x32_bf16 v[82:85], v[162:165], v[202:205], v[82:85]
	v_mfma_f32_16x16x32_bf16 v[86:89], v[170:173], v[202:205], v[86:89]
	v_mfma_f32_16x16x32_bf16 v[66:69], v[162:165], v[214:217], v[66:69]
	v_mfma_f32_16x16x32_bf16 v[70:73], v[170:173], v[214:217], v[70:73]
	v_mfma_f32_16x16x32_bf16 v[114:117], v[166:169], v[190:193], v[114:117]
	v_mfma_f32_16x16x32_bf16 v[118:121], v[174:177], v[190:193], v[118:121]
	v_mfma_f32_16x16x32_bf16 v[98:101], v[166:169], v[198:201], v[98:101]
	v_mfma_f32_16x16x32_bf16 v[102:105], v[174:177], v[198:201], v[102:105]
	v_mfma_f32_16x16x32_bf16 v[82:85], v[166:169], v[206:209], v[82:85]
	v_mfma_f32_16x16x32_bf16 v[86:89], v[174:177], v[206:209], v[86:89]
	v_mfma_f32_16x16x32_bf16 v[66:69], v[166:169], v[218:221], v[66:69]
	v_mfma_f32_16x16x32_bf16 v[70:73], v[174:177], v[218:221], v[70:73]
	s_setprio 0
	s_barrier
	s_add_i32 s16, s40, s2
	v_lshl_add_u64 v[178:179], s[30:31], 0, v[132:133]
	s_mov_b32 m0, s16
	ds_read_b128 v[186:189], v182 offset:16384
	ds_read_b128 v[190:193], v182 offset:17408
	ds_read_b128 v[194:197], v182 offset:18432
	ds_read_b128 v[198:201], v182 offset:19456
	ds_read_b128 v[202:205], v182 offset:20480
	ds_read_b128 v[206:209], v182 offset:21504
	ds_read_b128 v[214:217], v182 offset:22528
	ds_read_b128 v[218:221], v182 offset:23552
	global_load_lds_dwordx4 v[178:179], off
	s_add_i32 m0, s16, 0x2000
	s_add_u32 s56, s30, 0x40000
	v_lshl_add_u64 v[210:211], s[30:31], 0, v[136:137]
	s_addc_u32 s57, s31, 0
	s_add_i32 s16, s41, s2
	global_load_lds_dwordx4 v[210:211], off
	s_mov_b32 m0, s16
	v_lshl_add_u64 v[224:225], s[34:35], 0, v[134:135]
	global_load_lds_dwordx4 v132, s[56:57]
	s_add_i32 m0, s16, 0x2000
	s_nop 0
	global_load_lds_dwordx4 v136, s[56:57]
	v_lshl_add_u64 v[222:223], s[34:35], 0, v[130:131]
	s_mov_b32 m0, s3
	s_nop 0
	global_load_lds_dwordx4 v[222:223], off
	s_mov_b32 m0, s17
	s_nop 0
	global_load_lds_dwordx4 v[224:225], off
	s_waitcnt vmcnt(8)
	s_waitcnt lgkmcnt(0)
	s_barrier
; #define PG8_STAGE(bufoff, gbase, voff) do { _Pragma("unroll") for (int _i = 0; _i < 2; ++_i) \
;     __builtin_amdgcn_global_load_lds((const unsigned*)((const char*)(gbase) + (voff)[_i]), (PG8_LAS unsigned*)(lds + (bufoff) + ldsw + _i * 8192), 16, 0, 0); } while (0)
; #define PG8_LDA(dst, b, h) do { _Pragma("unroll") for (int m = 0; m < 4; ++m) _Pragma("unroll") for (int k = 0; k < 2; ++k) dst[m][k] = *(const PG8_LAS bf16x8*)(lds + PG8_SA(b, h) + aoff + m * 2048 + k * 1024); } while (0)
; #define PG8_LDB(dst, b, h) do { _Pragma("unroll") for (int n = 0; n < 2; ++n) _Pragma("unroll") for (int k = 0; k < 2; ++k) dst[n][k] = *(const PG8_LAS bf16x8*)(lds + PG8_SB(b, h) + boff + n * 2048 + k * 1024); } while (0)
; #define PG8_MMA(ai, bj, At, Bt) do { __builtin_amdgcn_s_setprio(1); _Pragma("unroll") for (int m = 0; m < 4; ++m) _Pragma("unroll") for (int n = 0; n < 2; ++n) _Pragma("unroll") for (int k = 0; k < 2; ++k) \
;     acc[ai][bj][m][n] = __builtin_amdgcn_mfma_f32_16x16x32_bf16(Bt[n][k], At[m][k], acc[ai][bj][m][n], 0, 0, 0); __builtin_amdgcn_s_setprio(0); } while (0)
; #define PG8_WAIT_V(n) asm volatile("s_waitcnt vmcnt(" #n ")" ::: "memory")
; #define PG8_WAIT_L(n) asm volatile("s_waitcnt lgkmcnt(" #n ")" ::: "memory")
; #define PG8_BAR __builtin_amdgcn_s_barrier()
; #define PG8_SCHED __builtin_amdgcn_sched_barrier(0)
; template <class Epi, class Sched>
; DI void gemm_phase(PG8_LAS unsigned char* lds, const Gemm g, const Sched& S, const Epi& E) {
;     ...
;       PG8_WAIT_V(8); PG8_WAIT_L(0); PG8_BAR; PG8_MMA(1, 0, At, B0); PG8_MMA(1, 1, At, B1); PG8_BAR; PG8_SCHED;
;       PG8_LDB(B0, 1, 0); PG8_LDB(B1, 1, 1); PG8_SCHED; PG8_LDA(At, 1, 0); PG8_STAGE(PG8_SA(0, 1), a2 + hstepA, voffA);
;       PG8_WAIT_V(8); PG8_WAIT_L(0); PG8_BAR; PG8_MMA(0, 0, At, B0); PG8_MMA(0, 1, At, B1); PG8_BAR; PG8_SCHED;
	s_setprio 1
	s_waitcnt lgkmcnt(0)
	v_mfma_f32_16x16x32_bf16 v[58:61], v[146:149], v[186:189], v[58:61]
	v_mfma_f32_16x16x32_bf16 v[62:65], v[154:157], v[186:189], v[62:65]
	v_mfma_f32_16x16x32_bf16 v[42:45], v[146:149], v[194:197], v[42:45]
	v_mfma_f32_16x16x32_bf16 v[46:49], v[154:157], v[194:197], v[46:49]
	v_mfma_f32_16x16x32_bf16 v[26:29], v[146:149], v[202:205], v[26:29]
	v_mfma_f32_16x16x32_bf16 v[30:33], v[154:157], v[202:205], v[30:33]
	v_mfma_f32_16x16x32_bf16 v[10:13], v[146:149], v[214:217], v[10:13]
	v_mfma_f32_16x16x32_bf16 v[14:17], v[154:157], v[214:217], v[14:17]
	v_mfma_f32_16x16x32_bf16 v[58:61], v[150:153], v[190:193], v[58:61]
	v_mfma_f32_16x16x32_bf16 v[62:65], v[158:161], v[190:193], v[62:65]
	v_mfma_f32_16x16x32_bf16 v[42:45], v[150:153], v[198:201], v[42:45]
	v_mfma_f32_16x16x32_bf16 v[46:49], v[158:161], v[198:201], v[46:49]
	v_mfma_f32_16x16x32_bf16 v[26:29], v[150:153], v[206:209], v[26:29]
	v_mfma_f32_16x16x32_bf16 v[30:33], v[158:161], v[206:209], v[30:33]
	v_mfma_f32_16x16x32_bf16 v[10:13], v[150:153], v[218:221], v[10:13]
	v_mfma_f32_16x16x32_bf16 v[14:17], v[158:161], v[218:221], v[14:17]
	s_setprio 0
	s_setprio 1
	v_mfma_f32_16x16x32_bf16 v[50:53], v[162:165], v[186:189], v[50:53]
	v_mfma_f32_16x16x32_bf16 v[54:57], v[170:173], v[186:189], v[54:57]
	v_mfma_f32_16x16x32_bf16 v[34:37], v[162:165], v[194:197], v[34:37]
	v_mfma_f32_16x16x32_bf16 v[38:41], v[170:173], v[194:197], v[38:41]
	v_mfma_f32_16x16x32_bf16 v[18:21], v[162:165], v[202:205], v[18:21]
	v_mfma_f32_16x16x32_bf16 v[22:25], v[170:173], v[202:205], v[22:25]
	v_mfma_f32_16x16x32_bf16 v[6:9], v[162:165], v[214:217], v[6:9]
	v_mfma_f32_16x16x32_bf16 v[2:5], v[170:173], v[214:217], v[2:5]
	v_mfma_f32_16x16x32_bf16 v[50:53], v[166:169], v[190:193], v[50:53]
	v_mfma_f32_16x16x32_bf16 v[54:57], v[174:177], v[190:193], v[54:57]
	v_mfma_f32_16x16x32_bf16 v[34:37], v[166:169], v[198:201], v[34:37]
	v_mfma_f32_16x16x32_bf16 v[38:41], v[174:177], v[198:201], v[38:41]
	v_mfma_f32_16x16x32_bf16 v[18:21], v[166:169], v[206:209], v[18:21]
	v_mfma_f32_16x16x32_bf16 v[22:25], v[174:177], v[206:209], v[22:25]
	v_mfma_f32_16x16x32_bf16 v[6:9], v[166:169], v[218:221], v[6:9]
	v_mfma_f32_16x16x32_bf16 v[2:5], v[174:177], v[218:221], v[2:5]
	s_setprio 0
	s_barrier
	ds_read_b128 v[146:149], v184
	ds_read_b128 v[150:153], v184 offset:1024
	ds_read_b128 v[154:157], v184 offset:2048
	ds_read_b128 v[158:161], v184 offset:3072
	ds_read_b128 v[162:165], v185
	ds_read_b128 v[166:169], v185 offset:1024
	ds_read_b128 v[170:173], v185 offset:2048
	ds_read_b128 v[174:177], v185 offset:3072
	s_add_u32 s34, s34, 0x40000
	s_addc_u32 s35, s35, 0
	s_mov_b32 m0, s19
	ds_read_b128 v[186:189], v182 offset:32768
	ds_read_b128 v[190:193], v182 offset:33792
	ds_read_b128 v[194:197], v182 offset:34816
	ds_read_b128 v[198:201], v182 offset:35840
	ds_read_b128 v[202:205], v182 offset:36864
	ds_read_b128 v[206:209], v182 offset:37888
	ds_read_b128 v[214:217], v182 offset:38912
	ds_read_b128 v[218:221], v182 offset:39936
	global_load_lds_dwordx4 v130, s[34:35]
	s_mov_b32 m0, s33
	s_nop 0
	global_load_lds_dwordx4 v134, s[34:35]
	s_waitcnt vmcnt(8)
	s_waitcnt lgkmcnt(0)
	s_barrier
	s_setprio 1
	s_waitcnt lgkmcnt(0)
	v_mfma_f32_16x16x32_bf16 v[122:125], v[146:149], v[186:189], v[122:125]
	v_mfma_f32_16x16x32_bf16 v[126:129], v[154:157], v[186:189], v[126:129]
	v_mfma_f32_16x16x32_bf16 v[106:109], v[146:149], v[194:197], v[106:109]
	v_mfma_f32_16x16x32_bf16 v[110:113], v[154:157], v[194:197], v[110:113]
	v_mfma_f32_16x16x32_bf16 v[90:93], v[146:149], v[202:205], v[90:93]
	v_mfma_f32_16x16x32_bf16 v[94:97], v[154:157], v[202:205], v[94:97]
	v_mfma_f32_16x16x32_bf16 v[74:77], v[146:149], v[214:217], v[74:77]
	v_mfma_f32_16x16x32_bf16 v[78:81], v[154:157], v[214:217], v[78:81]
	v_mfma_f32_16x16x32_bf16 v[122:125], v[150:153], v[190:193], v[122:125]
	v_mfma_f32_16x16x32_bf16 v[126:129], v[158:161], v[190:193], v[126:129]
	v_mfma_f32_16x16x32_bf16 v[106:109], v[150:153], v[198:201], v[106:109]
	v_mfma_f32_16x16x32_bf16 v[110:113], v[158:161], v[198:201], v[110:113]
	v_mfma_f32_16x16x32_bf16 v[90:93], v[150:153], v[206:209], v[90:93]
	v_mfma_f32_16x16x32_bf16 v[94:97], v[158:161], v[206:209], v[94:97]
	v_mfma_f32_16x16x32_bf16 v[74:77], v[150:153], v[218:221], v[74:77]
	v_mfma_f32_16x16x32_bf16 v[78:81], v[158:161], v[218:221], v[78:81]
	s_setprio 0
	s_setprio 1
	v_mfma_f32_16x16x32_bf16 v[114:117], v[162:165], v[186:189], v[114:117]
	v_mfma_f32_16x16x32_bf16 v[118:121], v[170:173], v[186:189], v[118:121]
	v_mfma_f32_16x16x32_bf16 v[98:101], v[162:165], v[194:197], v[98:101]
	v_mfma_f32_16x16x32_bf16 v[102:105], v[170:173], v[194:197], v[102:105]
	v_mfma_f32_16x16x32_bf16 v[82:85], v[162:165], v[202:205], v[82:85]
	v_mfma_f32_16x16x32_bf16 v[86:89], v[170:173], v[202:205], v[86:89]
	v_mfma_f32_16x16x32_bf16 v[66:69], v[162:165], v[214:217], v[66:69]
	v_mfma_f32_16x16x32_bf16 v[70:73], v[170:173], v[214:217], v[70:73]
	v_mfma_f32_16x16x32_bf16 v[114:117], v[166:169], v[190:193], v[114:117]
	v_mfma_f32_16x16x32_bf16 v[118:121], v[174:177], v[190:193], v[118:121]
	v_mfma_f32_16x16x32_bf16 v[98:101], v[166:169], v[198:201], v[98:101]
	v_mfma_f32_16x16x32_bf16 v[102:105], v[174:177], v[198:201], v[102:105]
	v_mfma_f32_16x16x32_bf16 v[82:85], v[166:169], v[206:209], v[82:85]
	v_mfma_f32_16x16x32_bf16 v[86:89], v[174:177], v[206:209], v[86:89]
	v_mfma_f32_16x16x32_bf16 v[66:69], v[166:169], v[218:221], v[66:69]
	v_mfma_f32_16x16x32_bf16 v[70:73], v[174:177], v[218:221], v[70:73]
	s_setprio 0
	s_barrier
; #define PG8_STAGE(bufoff, gbase, voff) do { _Pragma("unroll") for (int _i = 0; _i < 2; ++_i) \
;     __builtin_amdgcn_global_load_lds((const unsigned*)((const char*)(gbase) + (voff)[_i]), (PG8_LAS unsigned*)(lds + (bufoff) + ldsw + _i * 8192), 16, 0, 0); } while (0)
; #define PG8_LDA(dst, b, h) do { _Pragma("unroll") for (int m = 0; m < 4; ++m) _Pragma("unroll") for (int k = 0; k < 2; ++k) dst[m][k] = *(const PG8_LAS bf16x8*)(lds + PG8_SA(b, h) + aoff + m * 2048 + k * 1024); } while (0)
; #define PG8_MMA(ai, bj, At, Bt) do { __builtin_amdgcn_s_setprio(1); _Pragma("unroll") for (int m = 0; m < 4; ++m) _Pragma("unroll") for (int n = 0; n < 2; ++n) _Pragma("unroll") for (int k = 0; k < 2; ++k) \
;     acc[ai][bj][m][n] = __builtin_amdgcn_mfma_f32_16x16x32_bf16(Bt[n][k], At[m][k], acc[ai][bj][m][n], 0, 0, 0); __builtin_amdgcn_s_setprio(0); } while (0)
; #define PG8_WAIT_V(n) asm volatile("s_waitcnt vmcnt(" #n ")" ::: "memory")
; #define PG8_WAIT_L(n) asm volatile("s_waitcnt lgkmcnt(" #n ")" ::: "memory")
; #define PG8_BAR __builtin_amdgcn_s_barrier()
; #define PG8_SCHED __builtin_amdgcn_sched_barrier(0)
; DI void rows_rstd(float (&rs)[2][4], const float* ps, const Unit& u, int wr, int fr, int fq, int p_lo, int p_hi, float inv_dim) {
;   f32x4 pv[2][4];
; #pragma unroll
;   for (int ai = 0; ai < 2; ++ai)
; #pragma unroll
;     for (int m = 0; m < 4; ++m) pv[ai][m] = *(const f32x4*)(ps + (size_t)(u.pm * BM + ai * HALF + wr * 64 + m * 16 + fr) * 16 + 4 * fq);
; template <class Epi, class Sched>
; DI void gemm_phase(PG8_LAS unsigned char* lds, const Gemm g, const Sched& S, const Epi& E) {
;     ...
;       PG8_LDA(At, 1, 1); PG8_STAGE(PG8_SB(1, 0), b3, voffB); PG8_STAGE(PG8_SB(1, 1), b3 + hstepB, voffB); PG8_STAGE(PG8_SA(1, 0), a3, voffA);
;       PG8_WAIT_V(8); PG8_WAIT_L(0); PG8_BAR; PG8_MMA(1, 0, At, B0); PG8_MMA(1, 1, At, B1); PG8_BAR; PG8_SCHED;
;     }
	s_add_i32 s16, s65, s2
	v_lshl_add_u64 v[178:179], v[178:179], 0, s[12:13]
	s_mov_b32 m0, s16
	ds_read_b128 v[186:189], v182 offset:49152
	ds_read_b128 v[190:193], v182 offset:50176
	ds_read_b128 v[194:197], v182 offset:51200
	ds_read_b128 v[198:201], v182 offset:52224
	ds_read_b128 v[202:205], v182 offset:53248
	ds_read_b128 v[206:209], v182 offset:54272
	ds_read_b128 v[214:217], v182 offset:55296
	ds_read_b128 v[218:221], v182 offset:56320
	global_load_lds_dwordx4 v[178:179], off
	s_add_i32 m0, s16, 0x2000
	s_add_u32 s30, s30, 0x40080
	v_lshl_add_u64 v[178:179], v[210:211], 0, s[12:13]
	s_addc_u32 s31, s31, 0
	s_add_i32 s16, s66, s2
	global_load_lds_dwordx4 v[178:179], off
	s_mov_b32 m0, s16
	s_nop 0
	global_load_lds_dwordx4 v132, s[30:31]
	s_add_i32 m0, s16, 0x2000
	s_nop 0
	global_load_lds_dwordx4 v136, s[30:31]
	v_lshl_add_u64 v[178:179], v[222:223], 0, s[12:13]
	s_mov_b32 m0, s36
	s_nop 0
	global_load_lds_dwordx4 v[178:179], off
	v_lshl_add_u64 v[178:179], v[224:225], 0, s[12:13]
	s_mov_b32 m0, s37
	s_nop 0
	global_load_lds_dwordx4 v[178:179], off
	s_waitcnt vmcnt(8)
	s_waitcnt lgkmcnt(0)
	s_barrier
	s_setprio 1
	s_waitcnt lgkmcnt(0)
	v_mfma_f32_16x16x32_bf16 v[58:61], v[146:149], v[186:189], v[58:61]
	v_mfma_f32_16x16x32_bf16 v[62:65], v[154:157], v[186:189], v[62:65]
	v_mfma_f32_16x16x32_bf16 v[42:45], v[146:149], v[194:197], v[42:45]
	v_mfma_f32_16x16x32_bf16 v[46:49], v[154:157], v[194:197], v[46:49]
	v_mfma_f32_16x16x32_bf16 v[26:29], v[146:149], v[202:205], v[26:29]
	v_mfma_f32_16x16x32_bf16 v[30:33], v[154:157], v[202:205], v[30:33]
	v_mfma_f32_16x16x32_bf16 v[10:13], v[146:149], v[214:217], v[10:13]
	v_mfma_f32_16x16x32_bf16 v[14:17], v[154:157], v[214:217], v[14:17]
	v_mfma_f32_16x16x32_bf16 v[58:61], v[150:153], v[190:193], v[58:61]
	v_mfma_f32_16x16x32_bf16 v[62:65], v[158:161], v[190:193], v[62:65]
	v_mfma_f32_16x16x32_bf16 v[42:45], v[150:153], v[198:201], v[42:45]
	v_mfma_f32_16x16x32_bf16 v[46:49], v[158:161], v[198:201], v[46:49]
	v_mfma_f32_16x16x32_bf16 v[26:29], v[150:153], v[206:209], v[26:29]
	v_mfma_f32_16x16x32_bf16 v[30:33], v[158:161], v[206:209], v[30:33]
	v_mfma_f32_16x16x32_bf16 v[10:13], v[150:153], v[218:221], v[10:13]
	v_mfma_f32_16x16x32_bf16 v[14:17], v[158:161], v[218:221], v[14:17]
	s_setprio 0
	s_setprio 1
	v_mfma_f32_16x16x32_bf16 v[50:53], v[162:165], v[186:189], v[50:53]
	v_mfma_f32_16x16x32_bf16 v[54:57], v[170:173], v[186:189], v[54:57]
	v_mfma_f32_16x16x32_bf16 v[34:37], v[162:165], v[194:197], v[34:37]
	v_mfma_f32_16x16x32_bf16 v[38:41], v[170:173], v[194:197], v[38:41]
	v_mfma_f32_16x16x32_bf16 v[18:21], v[162:165], v[202:205], v[18:21]
	v_mfma_f32_16x16x32_bf16 v[22:25], v[170:173], v[202:205], v[22:25]
	v_mfma_f32_16x16x32_bf16 v[6:9], v[162:165], v[214:217], v[6:9]
	v_mfma_f32_16x16x32_bf16 v[2:5], v[170:173], v[214:217], v[2:5]
	v_mfma_f32_16x16x32_bf16 v[50:53], v[166:169], v[190:193], v[50:53]
	v_mfma_f32_16x16x32_bf16 v[54:57], v[174:177], v[190:193], v[54:57]
	v_mfma_f32_16x16x32_bf16 v[34:37], v[166:169], v[198:201], v[34:37]
	v_mfma_f32_16x16x32_bf16 v[38:41], v[174:177], v[198:201], v[38:41]
	v_mfma_f32_16x16x32_bf16 v[18:21], v[166:169], v[206:209], v[18:21]
	v_mfma_f32_16x16x32_bf16 v[22:25], v[174:177], v[206:209], v[22:25]
	v_mfma_f32_16x16x32_bf16 v[6:9], v[166:169], v[218:221], v[6:9]
	v_mfma_f32_16x16x32_bf16 v[2:5], v[174:177], v[218:221], v[2:5]
	s_setprio 0
	s_barrier
	s_add_i32 s69, s69, 2
	s_add_u32 s6, s6, 0x100
	s_addc_u32 s7, s7, 0
	s_add_u32 s67, s67, 0x100
	s_addc_u32 s68, s68, 0
	s_cmp_gt_u32 s69, 13
	s_cbranch_scc0 .LBB0_286
	v_lshl_add_u32 v166, s4, 8, v1
	v_or_b32_e32 v164, 16, v166
	v_ashrrev_i32_e32 v165, 31, v164
	v_or_b32_e32 v158, 32, v166
	v_lshlrev_b64 v[146:147], 6, v[164:165]
	v_ashrrev_i32_e32 v159, 31, v158
	v_lshl_add_u64 v[146:147], v[138:139], 0, v[146:147]
	v_lshlrev_b64 v[148:149], 6, v[158:159]
	v_ashrrev_i32_e32 v167, 31, v166
	v_lshl_add_u64 v[148:149], v[138:139], 0, v[148:149]
	global_load_dwordx4 v[160:163], v[146:147], off
	global_load_dwordx4 v[168:171], v[148:149], off
	v_lshlrev_b64 v[146:147], 6, v[166:167]
	v_lshl_add_u64 v[146:147], v[138:139], 0, v[146:147]
	global_load_dwordx4 v[172:175], v[146:147], off
	v_or_b32_e32 v156, 48, v166
	v_ashrrev_i32_e32 v157, 31, v156
	v_add_u32_e32 v154, 0x80, v166
	v_lshlrev_b64 v[146:147], 6, v[156:157]
	v_ashrrev_i32_e32 v155, 31, v154
	v_add_u32_e32 v150, 0x90, v166
	v_lshl_add_u64 v[146:147], v[138:139], 0, v[146:147]
	v_lshlrev_b64 v[148:149], 6, v[154:155]
	v_ashrrev_i32_e32 v151, 31, v150
	v_lshl_add_u64 v[148:149], v[138:139], 0, v[148:149]
	global_load_dwordx4 v[176:179], v[146:147], off
	global_load_dwordx4 v[186:189], v[148:149], off
	v_lshlrev_b64 v[146:147], 6, v[150:151]
	v_lshl_add_u64 v[146:147], v[138:139], 0, v[146:147]
	global_load_dwordx4 v[190:193], v[146:147], off
	v_add_u32_e32 v148, 0xa0, v166
	v_ashrrev_i32_e32 v149, 31, v148
	v_lshlrev_b64 v[146:147], 6, v[148:149]
	v_lshl_add_u64 v[146:147], v[138:139], 0, v[146:147]
	global_load_dwordx4 v[194:197], v[146:147], off
	v_add_u32_e32 v146, 0xb0, v166
	v_ashrrev_i32_e32 v147, 31, v146
	v_lshlrev_b64 v[152:153], 6, v[146:147]
	v_lshl_add_u64 v[152:153], v[138:139], 0, v[152:153]
	global_load_dwordx4 v[198:201], v[152:153], off
	s_and_b64 vcc, exec, s[14:15]
	s_cbranch_vccz .LBB0_289
	s_barrier

; DI unsigned xb_ld(unsigned* p) { return __hip_atomic_load(p, __ATOMIC_RELAXED, __HIP_MEMORY_SCOPE_AGENT); }
; DI unsigned xb_add(unsigned* p, unsigned v) { return __hip_atomic_fetch_add(p, v, __ATOMIC_RELAXED, __HIP_MEMORY_SCOPE_AGENT); }
; #define XB_SPIN(cond, bar) do { unsigned _sp = 0; while (cond) { __builtin_amdgcn_s_sleep(1); \
;     if ((++_sp & 255u) == 0u) { if (xb_ld(&(bar)[XB_TMO])) break; if (_sp > XB_SPIN_CAP) { atomicAdd(&(bar)[XB_TMO], 1u); break; } } } } while (0)
; DI void xcd_barrier(const XcdBarrier& b) {
;   asm volatile("s_waitcnt vmcnt(0)" ::: "memory");
;   __syncthreads();
;   if (threadIdx.x == 0) {
;     unsigned* bar = b.bar;
;     __builtin_amdgcn_s_waitcnt(0);
;     unsigned nloc = b.st[0], nx = b.st[1];
;     if (nloc == 0u) { xcd_barrier_complete(bar, b.x, nloc, nx); b.st[0] = nloc; b.st[1] = nx; }
;     const unsigned old = xb_add(&bar[XB_XSUB(b.x)], 1u);
;     const unsigned gen = old / nloc;
;     if (old + 1u == (gen + 1u) * nloc) {
;       __builtin_amdgcn_fence(__ATOMIC_RELEASE, "agent");
;       asm volatile("s_waitcnt vmcnt(0)" ::: "memory");
;       const unsigned og = xb_add(&bar[XB_TOP], 1u);
;       const unsigned tg = og / nx;
;       if (og + 1u == (tg + 1u) * nx) xb_add(&bar[XB_TOPGEN], 1u);
;       else XB_SPIN(xb_ld(&bar[XB_TOPGEN]) == tg, bar);
;       __builtin_amdgcn_fence(__ATOMIC_ACQUIRE, "agent");
;       xb_add(&bar[XB_XGEN(b.x)], 1u);
;       asm volatile("s_waitcnt vmcnt(0)" ::: "memory");
;     } else {
;       XB_SPIN(xb_ld(&bar[XB_XGEN(b.x)]) == gen, bar);
;       __builtin_amdgcn_fence(__ATOMIC_ACQUIRE, "agent");
;       asm volatile("s_waitcnt vmcnt(0)" ::: "memory");
;     }
;   }
;   __syncthreads();
; }
.LBB0_393:
	s_mov_b64 s[6:7], exec
	v_readlane_b32 s4, v254, 5
	s_lshl_b32 s4, s4, 8
	v_mbcnt_lo_u32_b32 v1, s6, 0
	s_add_u32 s4, s92, s4
	v_mbcnt_hi_u32_b32 v1, s7, v1
	s_addc_u32 s5, s93, 0
	v_cmp_eq_u32_e32 vcc, 0, v1
	s_and_saveexec_b64 s[8:9], vcc
	s_cbranch_execz .LBB0_395
	v_mov_b32_e32 v255, 0
	ds_read_b32 v255, v255 offset:264
	s_waitcnt lgkmcnt(0)
	v_readfirstlane_b32 s100, v255
	s_nop 3
	s_cmp_lg_u32 s100, 0
	s_cbranch_scc0 .Lei_a_2
	buffer_inv sc1

; DI unsigned xb_ld(unsigned* p) { return __hip_atomic_load(p, __ATOMIC_RELAXED, __HIP_MEMORY_SCOPE_AGENT); }
; DI unsigned xb_add(unsigned* p, unsigned v) { return __hip_atomic_fetch_add(p, v, __ATOMIC_RELAXED, __HIP_MEMORY_SCOPE_AGENT); }
; #define XB_SPIN(cond, bar) do { unsigned _sp = 0; while (cond) { __builtin_amdgcn_s_sleep(1); \
;     if ((++_sp & 255u) == 0u) { if (xb_ld(&(bar)[XB_TMO])) break; if (_sp > XB_SPIN_CAP) { atomicAdd(&(bar)[XB_TMO], 1u); break; } } } } while (0)
; DI void xcd_barrier(const XcdBarrier& b) {
;   asm volatile("s_waitcnt vmcnt(0)" ::: "memory");
;   __syncthreads();
;   if (threadIdx.x == 0) {
;     unsigned* bar = b.bar;
;     __builtin_amdgcn_s_waitcnt(0);
;     unsigned nloc = b.st[0], nx = b.st[1];
;     if (nloc == 0u) { xcd_barrier_complete(bar, b.x, nloc, nx); b.st[0] = nloc; b.st[1] = nx; }
;     const unsigned old = xb_add(&bar[XB_XSUB(b.x)], 1u);
;     const unsigned gen = old / nloc;
;     if (old + 1u == (gen + 1u) * nloc) {
;       __builtin_amdgcn_fence(__ATOMIC_RELEASE, "agent");
;       asm volatile("s_waitcnt vmcnt(0)" ::: "memory");
;       const unsigned og = xb_add(&bar[XB_TOP], 1u);
;       const unsigned tg = og / nx;
;       if (og + 1u == (tg + 1u) * nx) xb_add(&bar[XB_TOPGEN], 1u);
;       else XB_SPIN(xb_ld(&bar[XB_TOPGEN]) == tg, bar);
;       __builtin_amdgcn_fence(__ATOMIC_ACQUIRE, "agent");
;       xb_add(&bar[XB_XGEN(b.x)], 1u);
;       asm volatile("s_waitcnt vmcnt(0)" ::: "memory");
;     } else {
;       XB_SPIN(xb_ld(&bar[XB_XGEN(b.x)]) == gen, bar);
;       __builtin_amdgcn_fence(__ATOMIC_ACQUIRE, "agent");
;       asm volatile("s_waitcnt vmcnt(0)" ::: "memory");
;     }
;   }
;   __syncthreads();
; }
.LBB0_516:
	s_mov_b64 s[6:7], exec
	v_readlane_b32 s2, v254, 5
	s_lshl_b32 s2, s2, 8
	v_mbcnt_lo_u32_b32 v0, s6, 0
	s_add_u32 s4, s92, s2
	v_mbcnt_hi_u32_b32 v0, s7, v0
	s_addc_u32 s5, s93, 0
	v_cmp_eq_u32_e32 vcc, 0, v0
	s_and_saveexec_b64 s[8:9], vcc
	s_cbranch_execz .LBB0_518
	v_mov_b32_e32 v255, 0
	ds_read_b32 v255, v255 offset:264
	s_waitcnt lgkmcnt(0)
	v_readfirstlane_b32 s100, v255
	s_nop 3
	s_cmp_lg_u32 s100, 0
	s_cbranch_scc0 .Lei_a_3
	buffer_inv sc1

; #define PG8_STAGE(bufoff, gbase, voff) do { _Pragma("unroll") for (int _i = 0; _i < 2; ++_i) \
;     __builtin_amdgcn_global_load_lds((const unsigned*)((const char*)(gbase) + (voff)[_i]), (PG8_LAS unsigned*)(lds + (bufoff) + ldsw + _i * 8192), 16, 0, 0); } while (0)
; #define PG8_LDA(dst, b, h) do { _Pragma("unroll") for (int m = 0; m < 4; ++m) _Pragma("unroll") for (int k = 0; k < 2; ++k) dst[m][k] = *(const PG8_LAS bf16x8*)(lds + PG8_SA(b, h) + aoff + m * 2048 + k * 1024); } while (0)
; #define PG8_LDB(dst, b, h) do { _Pragma("unroll") for (int n = 0; n < 2; ++n) _Pragma("unroll") for (int k = 0; k < 2; ++k) dst[n][k] = *(const PG8_LAS bf16x8*)(lds + PG8_SB(b, h) + boff + n * 2048 + k * 1024); } while (0)
; #define PG8_MMA(ai, bj, At, Bt) do { __builtin_amdgcn_s_setprio(1); _Pragma("unroll") for (int m = 0; m < 4; ++m) _Pragma("unroll") for (int n = 0; n < 2; ++n) _Pragma("unroll") for (int k = 0; k < 2; ++k) \
;     acc[ai][bj][m][n] = __builtin_amdgcn_mfma_f32_16x16x32_bf16(Bt[n][k], At[m][k], acc[ai][bj][m][n], 0, 0, 0); __builtin_amdgcn_s_setprio(0); } while (0)
; #define PG8_WAIT_V(n) asm volatile("s_waitcnt vmcnt(" #n ")" ::: "memory")
; #define PG8_WAIT_L(n) asm volatile("s_waitcnt lgkmcnt(" #n ")" ::: "memory")
; #define PG8_BAR __builtin_amdgcn_s_barrier()
; #define PG8_SCHED __builtin_amdgcn_sched_barrier(0)
; template <class Epi, class Sched>
; DI void gemm_phase(PG8_LAS unsigned char* lds, const Gemm g, const Sched& S, const Epi& E) {
;     ...
;     for (int t = 0; t < nt; t += 2) {
;       const bool last = (t == nt - 2);
;       const char* a1 = cA + (size_t)(t + 1) * kstep;
;       const char* a2 = last ? nA : cA + (size_t)(t + 2) * kstep; const char* b2 = last ? nB : cB + (size_t)(t + 2) * kstep;
;       const char* a3 = a2 + kstep; const char* b3 = b2 + kstep;
;       PG8_LDB(B0, 0, 0); PG8_LDB(B1, 0, 1); PG8_SCHED; PG8_LDA(At, 0, 0); PG8_STAGE(PG8_SA(1, 1), a1 + hstepA, voffA);
;       PG8_WAIT_V(8); PG8_WAIT_L(0); PG8_BAR; PG8_MMA(0, 0, At, B0); PG8_MMA(0, 1, At, B1); PG8_BAR; PG8_SCHED;
;       PG8_LDA(At, 0, 1); PG8_STAGE(PG8_SB(0, 0), b2, voffB); PG8_STAGE(PG8_SB(0, 1), b2 + hstepB, voffB); PG8_STAGE(PG8_SA(0, 0), a2, voffA);
;       PG8_WAIT_V(8); PG8_WAIT_L(0); PG8_BAR; PG8_MMA(1, 0, At, B0); PG8_MMA(1, 1, At, B1); PG8_BAR; PG8_SCHED;
.LBB0_563:
	ds_read_b128 v[128:131], v167
	ds_read_b128 v[132:135], v167 offset:1024
	ds_read_b128 v[136:139], v167 offset:2048
	ds_read_b128 v[140:143], v167 offset:3072
	ds_read_b128 v[158:161], v168
	ds_read_b128 v[162:165], v168 offset:1024
	ds_read_b128 v[172:175], v168 offset:2048
	ds_read_b128 v[176:179], v168 offset:3072
	s_add_u32 s16, s28, 0xfffc0080
	s_addc_u32 s17, s29, -1
	s_cmp_eq_u32 s70, 12
	s_cselect_b32 s35, s19, s17
	s_cselect_b32 s34, s27, s16
	s_cselect_b32 s31, s15, s69
	s_cselect_b32 s30, s67, s68
	s_add_i32 m0, s3, 0xc000
	ds_read_b128 v[180:183], v169
	ds_read_b128 v[184:187], v169 offset:1024
	ds_read_b128 v[188:191], v169 offset:2048
	ds_read_b128 v[192:195], v169 offset:3072
	ds_read_b128 v[196:199], v169 offset:4096
	ds_read_b128 v[200:203], v169 offset:5120
	ds_read_b128 v[204:207], v169 offset:6144
	ds_read_b128 v[208:211], v169 offset:7168
	global_load_lds_dwordx4 v154, s[28:29]
	s_add_i32 m0, s3, 0xe000
	s_nop 0
	global_load_lds_dwordx4 v156, s[28:29]
	s_waitcnt vmcnt(8)
	s_waitcnt lgkmcnt(0)
	s_barrier
	s_setprio 1
	s_waitcnt lgkmcnt(0)
	v_mfma_f32_16x16x32_bf16 v[124:127], v[128:131], v[180:183], v[124:127]
	v_mfma_f32_16x16x32_bf16 v[120:123], v[136:139], v[180:183], v[120:123]
	v_mfma_f32_16x16x32_bf16 v[108:111], v[128:131], v[188:191], v[108:111]
	v_mfma_f32_16x16x32_bf16 v[104:107], v[136:139], v[188:191], v[104:107]
	v_mfma_f32_16x16x32_bf16 v[92:95], v[128:131], v[196:199], v[92:95]
	v_mfma_f32_16x16x32_bf16 v[88:91], v[136:139], v[196:199], v[88:91]
	v_mfma_f32_16x16x32_bf16 v[76:79], v[128:131], v[204:207], v[76:79]
	v_mfma_f32_16x16x32_bf16 v[72:75], v[136:139], v[204:207], v[72:75]
	v_mfma_f32_16x16x32_bf16 v[124:127], v[132:135], v[184:187], v[124:127]
	v_mfma_f32_16x16x32_bf16 v[120:123], v[140:143], v[184:187], v[120:123]
	v_mfma_f32_16x16x32_bf16 v[108:111], v[132:135], v[192:195], v[108:111]
	v_mfma_f32_16x16x32_bf16 v[104:107], v[140:143], v[192:195], v[104:107]
	v_mfma_f32_16x16x32_bf16 v[92:95], v[132:135], v[200:203], v[92:95]
	v_mfma_f32_16x16x32_bf16 v[88:91], v[140:143], v[200:203], v[88:91]
	v_mfma_f32_16x16x32_bf16 v[76:79], v[132:135], v[208:211], v[76:79]
	v_mfma_f32_16x16x32_bf16 v[72:75], v[140:143], v[208:211], v[72:75]
	s_setprio 0
	s_setprio 1
	v_mfma_f32_16x16x32_bf16 v[116:119], v[158:161], v[180:183], v[116:119]
	v_mfma_f32_16x16x32_bf16 v[112:115], v[172:175], v[180:183], v[112:115]
	v_mfma_f32_16x16x32_bf16 v[100:103], v[158:161], v[188:191], v[100:103]
	v_mfma_f32_16x16x32_bf16 v[96:99], v[172:175], v[188:191], v[96:99]
	v_mfma_f32_16x16x32_bf16 v[84:87], v[158:161], v[196:199], v[84:87]
	v_mfma_f32_16x16x32_bf16 v[80:83], v[172:175], v[196:199], v[80:83]
	v_mfma_f32_16x16x32_bf16 v[68:71], v[158:161], v[204:207], v[68:71]
	v_mfma_f32_16x16x32_bf16 v[64:67], v[172:175], v[204:207], v[64:67]
	v_mfma_f32_16x16x32_bf16 v[116:119], v[162:165], v[184:187], v[116:119]
	v_mfma_f32_16x16x32_bf16 v[112:115], v[176:179], v[184:187], v[112:115]
	v_mfma_f32_16x16x32_bf16 v[100:103], v[162:165], v[192:195], v[100:103]
	v_mfma_f32_16x16x32_bf16 v[96:99], v[176:179], v[192:195], v[96:99]
	v_mfma_f32_16x16x32_bf16 v[84:87], v[162:165], v[200:203], v[84:87]
	v_mfma_f32_16x16x32_bf16 v[80:83], v[176:179], v[200:203], v[80:83]
	v_mfma_f32_16x16x32_bf16 v[68:71], v[162:165], v[208:211], v[68:71]
	v_mfma_f32_16x16x32_bf16 v[64:67], v[176:179], v[208:211], v[64:67]
	s_setprio 0
	s_barrier
	s_add_i32 s16, s55, s2
	v_lshl_add_u64 v[214:215], s[30:31], 0, v[146:147]
	s_mov_b32 m0, s16
	ds_read_b128 v[180:183], v169 offset:16384
	ds_read_b128 v[184:187], v169 offset:17408
	ds_read_b128 v[188:191], v169 offset:18432
	ds_read_b128 v[192:195], v169 offset:19456
	ds_read_b128 v[196:199], v169 offset:20480
	ds_read_b128 v[200:203], v169 offset:21504
	ds_read_b128 v[204:207], v169 offset:22528
	ds_read_b128 v[208:211], v169 offset:23552
	global_load_lds_dwordx4 v[214:215], off
	s_add_i32 m0, s16, 0x2000
	s_add_u32 s16, s30, 0x40000
	v_lshl_add_u64 v[216:217], s[30:31], 0, v[150:151]
	s_addc_u32 s17, s31, 0
	s_add_i32 s33, s64, s2
	global_load_lds_dwordx4 v[216:217], off
	s_mov_b32 m0, s33
	v_lshl_add_u64 v[220:221], s[34:35], 0, v[148:149]
	global_load_lds_dwordx4 v146, s[16:17]
	s_add_i32 m0, s33, 0x2000
	s_nop 0
	global_load_lds_dwordx4 v150, s[16:17]
	v_lshl_add_u64 v[218:219], s[34:35], 0, v[144:145]
	s_mov_b32 m0, s3
	s_nop 0
	global_load_lds_dwordx4 v[218:219], off
	s_mov_b32 m0, s36
	s_nop 0
	global_load_lds_dwordx4 v[220:221], off
	s_waitcnt vmcnt(8)
	s_waitcnt lgkmcnt(0)
	s_barrier
; #define PG8_STAGE(bufoff, gbase, voff) do { _Pragma("unroll") for (int _i = 0; _i < 2; ++_i) \
;     __builtin_amdgcn_global_load_lds((const unsigned*)((const char*)(gbase) + (voff)[_i]), (PG8_LAS unsigned*)(lds + (bufoff) + ldsw + _i * 8192), 16, 0, 0); } while (0)
; #define PG8_LDA(dst, b, h) do { _Pragma("unroll") for (int m = 0; m < 4; ++m) _Pragma("unroll") for (int k = 0; k < 2; ++k) dst[m][k] = *(const PG8_LAS bf16x8*)(lds + PG8_SA(b, h) + aoff + m * 2048 + k * 1024); } while (0)
; #define PG8_LDB(dst, b, h) do { _Pragma("unroll") for (int n = 0; n < 2; ++n) _Pragma("unroll") for (int k = 0; k < 2; ++k) dst[n][k] = *(const PG8_LAS bf16x8*)(lds + PG8_SB(b, h) + boff + n * 2048 + k * 1024); } while (0)
; #define PG8_MMA(ai, bj, At, Bt) do { __builtin_amdgcn_s_setprio(1); _Pragma("unroll") for (int m = 0; m < 4; ++m) _Pragma("unroll") for (int n = 0; n < 2; ++n) _Pragma("unroll") for (int k = 0; k < 2; ++k) \
;     acc[ai][bj][m][n] = __builtin_amdgcn_mfma_f32_16x16x32_bf16(Bt[n][k], At[m][k], acc[ai][bj][m][n], 0, 0, 0); __builtin_amdgcn_s_setprio(0); } while (0)
; #define PG8_WAIT_V(n) asm volatile("s_waitcnt vmcnt(" #n ")" ::: "memory")
; #define PG8_WAIT_L(n) asm volatile("s_waitcnt lgkmcnt(" #n ")" ::: "memory")
; #define PG8_BAR __builtin_amdgcn_s_barrier()
; #define PG8_SCHED __builtin_amdgcn_sched_barrier(0)
; template <class Epi, class Sched>
; DI void gemm_phase(PG8_LAS unsigned char* lds, const Gemm g, const Sched& S, const Epi& E) {
;     ...
;       PG8_WAIT_V(8); PG8_WAIT_L(0); PG8_BAR; PG8_MMA(1, 0, At, B0); PG8_MMA(1, 1, At, B1); PG8_BAR; PG8_SCHED;
;       PG8_LDB(B0, 1, 0); PG8_LDB(B1, 1, 1); PG8_SCHED; PG8_LDA(At, 1, 0); PG8_STAGE(PG8_SA(0, 1), a2 + hstepA, voffA);
;       PG8_WAIT_V(8); PG8_WAIT_L(0); PG8_BAR; PG8_MMA(0, 0, At, B0); PG8_MMA(0, 1, At, B1); PG8_BAR; PG8_SCHED;
	s_setprio 1
	s_waitcnt lgkmcnt(0)
	v_mfma_f32_16x16x32_bf16 v[60:63], v[128:131], v[180:183], v[60:63]
	v_mfma_f32_16x16x32_bf16 v[56:59], v[136:139], v[180:183], v[56:59]
	v_mfma_f32_16x16x32_bf16 v[44:47], v[128:131], v[188:191], v[44:47]
	v_mfma_f32_16x16x32_bf16 v[40:43], v[136:139], v[188:191], v[40:43]
	v_mfma_f32_16x16x32_bf16 v[28:31], v[128:131], v[196:199], v[28:31]
	v_mfma_f32_16x16x32_bf16 v[24:27], v[136:139], v[196:199], v[24:27]
	v_mfma_f32_16x16x32_bf16 v[12:15], v[128:131], v[204:207], v[12:15]
	v_mfma_f32_16x16x32_bf16 v[8:11], v[136:139], v[204:207], v[8:11]
	v_mfma_f32_16x16x32_bf16 v[60:63], v[132:135], v[184:187], v[60:63]
	v_mfma_f32_16x16x32_bf16 v[56:59], v[140:143], v[184:187], v[56:59]
	v_mfma_f32_16x16x32_bf16 v[44:47], v[132:135], v[192:195], v[44:47]
	v_mfma_f32_16x16x32_bf16 v[40:43], v[140:143], v[192:195], v[40:43]
	v_mfma_f32_16x16x32_bf16 v[28:31], v[132:135], v[200:203], v[28:31]
	v_mfma_f32_16x16x32_bf16 v[24:27], v[140:143], v[200:203], v[24:27]
	v_mfma_f32_16x16x32_bf16 v[12:15], v[132:135], v[208:211], v[12:15]
	v_mfma_f32_16x16x32_bf16 v[8:11], v[140:143], v[208:211], v[8:11]
	s_setprio 0
	s_setprio 1
	v_mfma_f32_16x16x32_bf16 v[52:55], v[158:161], v[180:183], v[52:55]
	v_mfma_f32_16x16x32_bf16 v[48:51], v[172:175], v[180:183], v[48:51]
	v_mfma_f32_16x16x32_bf16 v[36:39], v[158:161], v[188:191], v[36:39]
	v_mfma_f32_16x16x32_bf16 v[32:35], v[172:175], v[188:191], v[32:35]
	v_mfma_f32_16x16x32_bf16 v[20:23], v[158:161], v[196:199], v[20:23]
	v_mfma_f32_16x16x32_bf16 v[16:19], v[172:175], v[196:199], v[16:19]
	v_mfma_f32_16x16x32_bf16 v[4:7], v[158:161], v[204:207], v[4:7]
	v_mfma_f32_16x16x32_bf16 v[0:3], v[172:175], v[204:207], v[0:3]
	v_mfma_f32_16x16x32_bf16 v[52:55], v[162:165], v[184:187], v[52:55]
	v_mfma_f32_16x16x32_bf16 v[48:51], v[176:179], v[184:187], v[48:51]
	v_mfma_f32_16x16x32_bf16 v[36:39], v[162:165], v[192:195], v[36:39]
	v_mfma_f32_16x16x32_bf16 v[32:35], v[176:179], v[192:195], v[32:35]
	v_mfma_f32_16x16x32_bf16 v[20:23], v[162:165], v[200:203], v[20:23]
	v_mfma_f32_16x16x32_bf16 v[16:19], v[176:179], v[200:203], v[16:19]
	v_mfma_f32_16x16x32_bf16 v[4:7], v[162:165], v[208:211], v[4:7]
	v_mfma_f32_16x16x32_bf16 v[0:3], v[176:179], v[208:211], v[0:3]
	s_setprio 0
	s_barrier
	s_add_i32 s33, s41, 0x110
	v_add_u32_e32 v140, s33, v166
	ds_read_b128 v[128:131], v140
	ds_read_b128 v[132:135], v140 offset:1024
	ds_read_b128 v[136:139], v140 offset:2048
	ds_read_b128 v[140:143], v140 offset:3072
	ds_read_b128 v[158:161], v171
	ds_read_b128 v[162:165], v171 offset:1024
	ds_read_b128 v[172:175], v171 offset:2048
	ds_read_b128 v[176:179], v171 offset:3072
	s_add_u32 s16, s34, 0x40000
	s_addc_u32 s17, s35, 0
	s_mov_b32 m0, s37
	ds_read_b128 v[180:183], v169 offset:32768
	ds_read_b128 v[184:187], v169 offset:33792
	ds_read_b128 v[188:191], v169 offset:34816
	ds_read_b128 v[192:195], v169 offset:35840
	ds_read_b128 v[196:199], v169 offset:36864
	ds_read_b128 v[200:203], v169 offset:37888
	ds_read_b128 v[204:207], v169 offset:38912
	ds_read_b128 v[208:211], v169 offset:39936
	global_load_lds_dwordx4 v144, s[16:17]
	s_mov_b32 m0, s38
	s_nop 0
	global_load_lds_dwordx4 v148, s[16:17]
	s_waitcnt vmcnt(8)
	s_waitcnt lgkmcnt(0)
	s_barrier
	s_setprio 1
	s_waitcnt lgkmcnt(0)
	v_mfma_f32_16x16x32_bf16 v[124:127], v[128:131], v[180:183], v[124:127]
	v_mfma_f32_16x16x32_bf16 v[120:123], v[136:139], v[180:183], v[120:123]
	v_mfma_f32_16x16x32_bf16 v[108:111], v[128:131], v[188:191], v[108:111]
	v_mfma_f32_16x16x32_bf16 v[104:107], v[136:139], v[188:191], v[104:107]
	v_mfma_f32_16x16x32_bf16 v[92:95], v[128:131], v[196:199], v[92:95]
	v_mfma_f32_16x16x32_bf16 v[88:91], v[136:139], v[196:199], v[88:91]
	v_mfma_f32_16x16x32_bf16 v[76:79], v[128:131], v[204:207], v[76:79]
	v_mfma_f32_16x16x32_bf16 v[72:75], v[136:139], v[204:207], v[72:75]
	v_mfma_f32_16x16x32_bf16 v[124:127], v[132:135], v[184:187], v[124:127]
	v_mfma_f32_16x16x32_bf16 v[120:123], v[140:143], v[184:187], v[120:123]
	v_mfma_f32_16x16x32_bf16 v[108:111], v[132:135], v[192:195], v[108:111]
	v_mfma_f32_16x16x32_bf16 v[104:107], v[140:143], v[192:195], v[104:107]
	v_mfma_f32_16x16x32_bf16 v[92:95], v[132:135], v[200:203], v[92:95]
	v_mfma_f32_16x16x32_bf16 v[88:91], v[140:143], v[200:203], v[88:91]
	v_mfma_f32_16x16x32_bf16 v[76:79], v[132:135], v[208:211], v[76:79]
	v_mfma_f32_16x16x32_bf16 v[72:75], v[140:143], v[208:211], v[72:75]
	s_setprio 0
	s_setprio 1
	v_mfma_f32_16x16x32_bf16 v[116:119], v[158:161], v[180:183], v[116:119]
	v_mfma_f32_16x16x32_bf16 v[112:115], v[172:175], v[180:183], v[112:115]
	v_mfma_f32_16x16x32_bf16 v[100:103], v[158:161], v[188:191], v[100:103]
	v_mfma_f32_16x16x32_bf16 v[96:99], v[172:175], v[188:191], v[96:99]
	v_mfma_f32_16x16x32_bf16 v[84:87], v[158:161], v[196:199], v[84:87]
	v_mfma_f32_16x16x32_bf16 v[80:83], v[172:175], v[196:199], v[80:83]
	v_mfma_f32_16x16x32_bf16 v[68:71], v[158:161], v[204:207], v[68:71]
	v_mfma_f32_16x16x32_bf16 v[64:67], v[172:175], v[204:207], v[64:67]
	v_mfma_f32_16x16x32_bf16 v[116:119], v[162:165], v[184:187], v[116:119]
	v_mfma_f32_16x16x32_bf16 v[112:115], v[176:179], v[184:187], v[112:115]
	v_mfma_f32_16x16x32_bf16 v[100:103], v[162:165], v[192:195], v[100:103]
	v_mfma_f32_16x16x32_bf16 v[96:99], v[176:179], v[192:195], v[96:99]
	v_mfma_f32_16x16x32_bf16 v[84:87], v[162:165], v[200:203], v[84:87]
	v_mfma_f32_16x16x32_bf16 v[80:83], v[176:179], v[200:203], v[80:83]
	v_mfma_f32_16x16x32_bf16 v[68:71], v[162:165], v[208:211], v[68:71]
	v_mfma_f32_16x16x32_bf16 v[64:67], v[176:179], v[208:211], v[64:67]
	s_setprio 0
	s_barrier
; #define PG8_STAGE(bufoff, gbase, voff) do { _Pragma("unroll") for (int _i = 0; _i < 2; ++_i) \
;     __builtin_amdgcn_global_load_lds((const unsigned*)((const char*)(gbase) + (voff)[_i]), (PG8_LAS unsigned*)(lds + (bufoff) + ldsw + _i * 8192), 16, 0, 0); } while (0)
; #define PG8_LDA(dst, b, h) do { _Pragma("unroll") for (int m = 0; m < 4; ++m) _Pragma("unroll") for (int k = 0; k < 2; ++k) dst[m][k] = *(const PG8_LAS bf16x8*)(lds + PG8_SA(b, h) + aoff + m * 2048 + k * 1024); } while (0)
; #define PG8_MMA(ai, bj, At, Bt) do { __builtin_amdgcn_s_setprio(1); _Pragma("unroll") for (int m = 0; m < 4; ++m) _Pragma("unroll") for (int n = 0; n < 2; ++n) _Pragma("unroll") for (int k = 0; k < 2; ++k) \
;     acc[ai][bj][m][n] = __builtin_amdgcn_mfma_f32_16x16x32_bf16(Bt[n][k], At[m][k], acc[ai][bj][m][n], 0, 0, 0); __builtin_amdgcn_s_setprio(0); } while (0)
; #define PG8_WAIT_V(n) asm volatile("s_waitcnt vmcnt(" #n ")" ::: "memory")
; #define PG8_WAIT_L(n) asm volatile("s_waitcnt lgkmcnt(" #n ")" ::: "memory")
; #define PG8_BAR __builtin_amdgcn_s_barrier()
; #define PG8_SCHED __builtin_amdgcn_sched_barrier(0)
;   DI void operator()(const f32x4 (&acc)[2][2][4][2], const Unit& u, int wr, int wc, int fr, int fq) const {
;     const int row0 = u.pm * BM + wr * 64 + fr;
;     const size_t base = (size_t)row0 * DM + u.pn * BM + wc * 32 + 8 * fq;
;     f32x4 xv[2][4];
;     u32x4 xh[2][2];
; template <class Epi, class Sched>
; DI void gemm_phase(PG8_LAS unsigned char* lds, const Gemm g, const Sched& S, const Epi& E) {
;     ...
;       PG8_LDA(At, 1, 1); PG8_STAGE(PG8_SB(1, 0), b3, voffB); PG8_STAGE(PG8_SB(1, 1), b3 + hstepB, voffB); PG8_STAGE(PG8_SA(1, 0), a3, voffA);
;       PG8_WAIT_V(8); PG8_WAIT_L(0); PG8_BAR; PG8_MMA(1, 0, At, B0); PG8_MMA(1, 1, At, B1); PG8_BAR; PG8_SCHED;
;     }
	s_add_i32 s16, s33, s2
	v_lshl_add_u64 v[214:215], v[214:215], 0, s[8:9]
	s_mov_b32 m0, s16
	ds_read_b128 v[180:183], v169 offset:49152
	ds_read_b128 v[184:187], v169 offset:50176
	ds_read_b128 v[188:191], v169 offset:51200
	ds_read_b128 v[192:195], v169 offset:52224
	ds_read_b128 v[196:199], v169 offset:53248
	ds_read_b128 v[200:203], v169 offset:54272
	ds_read_b128 v[204:207], v169 offset:55296
	ds_read_b128 v[208:211], v169 offset:56320
	global_load_lds_dwordx4 v[214:215], off
	s_add_i32 m0, s16, 0x2000
	s_add_u32 s16, s30, 0x40080
	v_lshl_add_u64 v[214:215], v[216:217], 0, s[8:9]
	s_addc_u32 s17, s31, 0
	s_add_i32 s30, s65, s2
	global_load_lds_dwordx4 v[214:215], off
	s_mov_b32 m0, s30
	s_nop 0
	global_load_lds_dwordx4 v146, s[16:17]
	s_add_i32 m0, s30, 0x2000
	s_nop 0
	global_load_lds_dwordx4 v150, s[16:17]
	v_lshl_add_u64 v[214:215], v[218:219], 0, s[8:9]
	s_mov_b32 m0, s4
	s_nop 0
	global_load_lds_dwordx4 v[214:215], off
	v_lshl_add_u64 v[214:215], v[220:221], 0, s[8:9]
	s_mov_b32 m0, s5
	s_nop 0
	global_load_lds_dwordx4 v[214:215], off
	s_waitcnt vmcnt(8)
	s_waitcnt lgkmcnt(0)
	s_barrier
	s_setprio 1
	s_waitcnt lgkmcnt(0)
	v_mfma_f32_16x16x32_bf16 v[60:63], v[128:131], v[180:183], v[60:63]
	v_mfma_f32_16x16x32_bf16 v[56:59], v[136:139], v[180:183], v[56:59]
	v_mfma_f32_16x16x32_bf16 v[44:47], v[128:131], v[188:191], v[44:47]
	v_mfma_f32_16x16x32_bf16 v[40:43], v[136:139], v[188:191], v[40:43]
	v_mfma_f32_16x16x32_bf16 v[28:31], v[128:131], v[196:199], v[28:31]
	v_mfma_f32_16x16x32_bf16 v[24:27], v[136:139], v[196:199], v[24:27]
	v_mfma_f32_16x16x32_bf16 v[12:15], v[128:131], v[204:207], v[12:15]
	v_mfma_f32_16x16x32_bf16 v[8:11], v[136:139], v[204:207], v[8:11]
	v_mfma_f32_16x16x32_bf16 v[60:63], v[132:135], v[184:187], v[60:63]
	v_mfma_f32_16x16x32_bf16 v[56:59], v[140:143], v[184:187], v[56:59]
	v_mfma_f32_16x16x32_bf16 v[44:47], v[132:135], v[192:195], v[44:47]
	v_mfma_f32_16x16x32_bf16 v[40:43], v[140:143], v[192:195], v[40:43]
	v_mfma_f32_16x16x32_bf16 v[28:31], v[132:135], v[200:203], v[28:31]
	v_mfma_f32_16x16x32_bf16 v[24:27], v[140:143], v[200:203], v[24:27]
	v_mfma_f32_16x16x32_bf16 v[12:15], v[132:135], v[208:211], v[12:15]
	v_mfma_f32_16x16x32_bf16 v[8:11], v[140:143], v[208:211], v[8:11]
	s_setprio 0
	s_setprio 1
	v_mfma_f32_16x16x32_bf16 v[52:55], v[158:161], v[180:183], v[52:55]
	v_mfma_f32_16x16x32_bf16 v[48:51], v[172:175], v[180:183], v[48:51]
	v_mfma_f32_16x16x32_bf16 v[36:39], v[158:161], v[188:191], v[36:39]
	v_mfma_f32_16x16x32_bf16 v[32:35], v[172:175], v[188:191], v[32:35]
	v_mfma_f32_16x16x32_bf16 v[20:23], v[158:161], v[196:199], v[20:23]
	v_mfma_f32_16x16x32_bf16 v[16:19], v[172:175], v[196:199], v[16:19]
	v_mfma_f32_16x16x32_bf16 v[4:7], v[158:161], v[204:207], v[4:7]
	v_mfma_f32_16x16x32_bf16 v[0:3], v[172:175], v[204:207], v[0:3]
	v_mfma_f32_16x16x32_bf16 v[52:55], v[162:165], v[184:187], v[52:55]
	v_mfma_f32_16x16x32_bf16 v[48:51], v[176:179], v[184:187], v[48:51]
	v_mfma_f32_16x16x32_bf16 v[36:39], v[162:165], v[192:195], v[36:39]
	v_mfma_f32_16x16x32_bf16 v[32:35], v[176:179], v[192:195], v[32:35]
	v_mfma_f32_16x16x32_bf16 v[20:23], v[162:165], v[200:203], v[20:23]
	v_mfma_f32_16x16x32_bf16 v[16:19], v[176:179], v[200:203], v[16:19]
	v_mfma_f32_16x16x32_bf16 v[4:7], v[162:165], v[208:211], v[4:7]
	v_mfma_f32_16x16x32_bf16 v[0:3], v[176:179], v[208:211], v[0:3]
	s_setprio 0
	s_barrier
	s_add_i32 s70, s70, 2
	s_add_u32 s28, s28, 0x100
	s_addc_u32 s29, s29, 0
	s_add_u32 s68, s68, 0x100
	s_addc_u32 s69, s69, 0
	s_cmp_gt_u32 s70, 13
	s_cbranch_scc0 .LBB0_563
	v_lshl_add_u32 v164, s26, 8, v153
	v_ashrrev_i32_e32 v165, 31, v164
	s_lshl_b32 s16, s12, 8
	v_lshlrev_b64 v[128:129], 10, v[164:165]
	s_ashr_i32 s17, s16, 31
	v_lshl_add_u64 v[186:187], v[128:129], 0, s[16:17]
	v_or_b32_e32 v186, v186, v152
	v_lshl_add_u64 v[162:163], v[186:187], 2, s[44:45]
	s_mov_b64 s[16:17], 0x10000
	v_add_co_u32_e32 v130, vcc, s39, v162
	global_load_dwordx4 v[158:161], v[162:163], off offset:16
	global_load_dwordx4 v[174:177], v[162:163], off
	global_load_dwordx4 v[178:181], v[162:163], off offset:528
	global_load_dwordx4 v[182:185], v[162:163], off offset:512
	v_lshl_add_u64 v[128:129], v[162:163], 0, s[16:17]
	v_addc_co_u32_e32 v131, vcc, 0, v163, vcc
	s_mov_b64 s[16:17], 0x10200
	global_load_dwordx4 v[140:143], v[130:131], off
	global_load_dwordx4 v[136:139], v[128:129], off offset:16
	v_lshl_add_u64 v[128:129], v[162:163], 0, s[16:17]
	global_load_dwordx4 v[132:135], v[130:131], off offset:512
	s_nop 0
	global_load_dwordx4 v[128:131], v[128:129], off offset:16
	s_and_b64 vcc, exec, s[10:11]
	s_cbranch_vccz .LBB0_566
	s_barrier

; DI unsigned xb_ld(unsigned* p) { return __hip_atomic_load(p, __ATOMIC_RELAXED, __HIP_MEMORY_SCOPE_AGENT); }
; DI unsigned xb_add(unsigned* p, unsigned v) { return __hip_atomic_fetch_add(p, v, __ATOMIC_RELAXED, __HIP_MEMORY_SCOPE_AGENT); }
; #define XB_SPIN(cond, bar) do { unsigned _sp = 0; while (cond) { __builtin_amdgcn_s_sleep(1); \
;     if ((++_sp & 255u) == 0u) { if (xb_ld(&(bar)[XB_TMO])) break; if (_sp > XB_SPIN_CAP) { atomicAdd(&(bar)[XB_TMO], 1u); break; } } } } while (0)
; DI void xcd_barrier(const XcdBarrier& b) {
;   asm volatile("s_waitcnt vmcnt(0)" ::: "memory");
;   __syncthreads();
;   if (threadIdx.x == 0) {
;     unsigned* bar = b.bar;
;     __builtin_amdgcn_s_waitcnt(0);
;     unsigned nloc = b.st[0], nx = b.st[1];
;     if (nloc == 0u) { xcd_barrier_complete(bar, b.x, nloc, nx); b.st[0] = nloc; b.st[1] = nx; }
;     const unsigned old = xb_add(&bar[XB_XSUB(b.x)], 1u);
;     const unsigned gen = old / nloc;
;     if (old + 1u == (gen + 1u) * nloc) {
;       __builtin_amdgcn_fence(__ATOMIC_RELEASE, "agent");
;       asm volatile("s_waitcnt vmcnt(0)" ::: "memory");
;       const unsigned og = xb_add(&bar[XB_TOP], 1u);
;       const unsigned tg = og / nx;
;       if (og + 1u == (tg + 1u) * nx) xb_add(&bar[XB_TOPGEN], 1u);
;       else XB_SPIN(xb_ld(&bar[XB_TOPGEN]) == tg, bar);
;       __builtin_amdgcn_fence(__ATOMIC_ACQUIRE, "agent");
;       xb_add(&bar[XB_XGEN(b.x)], 1u);
;       asm volatile("s_waitcnt vmcnt(0)" ::: "memory");
;     } else {
;       XB_SPIN(xb_ld(&bar[XB_XGEN(b.x)]) == gen, bar);
;       __builtin_amdgcn_fence(__ATOMIC_ACQUIRE, "agent");
;       asm volatile("s_waitcnt vmcnt(0)" ::: "memory");
;     }
;   }
;   __syncthreads();
; }
.LBB0_602:
	s_mov_b64 s[8:9], exec
	s_lshl_b32 s2, s78, 8
	v_mbcnt_lo_u32_b32 v0, s8, 0
	s_add_u32 s6, s92, s2
	v_mbcnt_hi_u32_b32 v0, s9, v0
	s_addc_u32 s7, s93, 0
	v_cmp_eq_u32_e32 vcc, 0, v0
	s_and_saveexec_b64 s[10:11], vcc
	s_cbranch_execz .LBB0_604
	v_mov_b32_e32 v255, 0
	ds_read_b32 v255, v255 offset:264
	s_waitcnt lgkmcnt(0)
	v_readfirstlane_b32 s100, v255
	s_nop 3
	s_cmp_lg_u32 s100, 0
	s_cbranch_scc0 .Lei_a_4
	buffer_inv sc1

; #define PG8_STAGE(bufoff, gbase, voff) do { _Pragma("unroll") for (int _i = 0; _i < 2; ++_i) \
;     __builtin_amdgcn_global_load_lds((const unsigned*)((const char*)(gbase) + (voff)[_i]), (PG8_LAS unsigned*)(lds + (bufoff) + ldsw + _i * 8192), 16, 0, 0); } while (0)
; #define PG8_LDA(dst, b, h) do { _Pragma("unroll") for (int m = 0; m < 4; ++m) _Pragma("unroll") for (int k = 0; k < 2; ++k) dst[m][k] = *(const PG8_LAS bf16x8*)(lds + PG8_SA(b, h) + aoff + m * 2048 + k * 1024); } while (0)
; #define PG8_LDB(dst, b, h) do { _Pragma("unroll") for (int n = 0; n < 2; ++n) _Pragma("unroll") for (int k = 0; k < 2; ++k) dst[n][k] = *(const PG8_LAS bf16x8*)(lds + PG8_SB(b, h) + boff + n * 2048 + k * 1024); } while (0)
; #define PG8_MMA(ai, bj, At, Bt) do { __builtin_amdgcn_s_setprio(1); _Pragma("unroll") for (int m = 0; m < 4; ++m) _Pragma("unroll") for (int n = 0; n < 2; ++n) _Pragma("unroll") for (int k = 0; k < 2; ++k) \
;     acc[ai][bj][m][n] = __builtin_amdgcn_mfma_f32_16x16x32_bf16(Bt[n][k], At[m][k], acc[ai][bj][m][n], 0, 0, 0); __builtin_amdgcn_s_setprio(0); } while (0)
; #define PG8_WAIT_V(n) asm volatile("s_waitcnt vmcnt(" #n ")" ::: "memory")
; #define PG8_WAIT_L(n) asm volatile("s_waitcnt lgkmcnt(" #n ")" ::: "memory")
; #define PG8_BAR __builtin_amdgcn_s_barrier()
; #define PG8_SCHED __builtin_amdgcn_sched_barrier(0)
; template <class Epi, class Sched>
; DI void gemm_phase(PG8_LAS unsigned char* lds, const Gemm g, const Sched& S, const Epi& E) {
;     ...
;     for (int t = 0; t < nt; t += 2) {
;       const bool last = (t == nt - 2);
;       const char* a1 = cA + (size_t)(t + 1) * kstep;
;       const char* a2 = last ? nA : cA + (size_t)(t + 2) * kstep; const char* b2 = last ? nB : cB + (size_t)(t + 2) * kstep;
;       const char* a3 = a2 + kstep; const char* b3 = b2 + kstep;
;       PG8_LDB(B0, 0, 0); PG8_LDB(B1, 0, 1); PG8_SCHED; PG8_LDA(At, 0, 0); PG8_STAGE(PG8_SA(1, 1), a1 + hstepA, voffA);
;       PG8_WAIT_V(8); PG8_WAIT_L(0); PG8_BAR; PG8_MMA(0, 0, At, B0); PG8_MMA(0, 1, At, B1); PG8_BAR; PG8_SCHED;
;       PG8_LDA(At, 0, 1); PG8_STAGE(PG8_SB(0, 0), b2, voffB); PG8_STAGE(PG8_SB(0, 1), b2 + hstepB, voffB); PG8_STAGE(PG8_SA(0, 0), a2, voffA);
;       PG8_WAIT_V(8); PG8_WAIT_L(0); PG8_BAR; PG8_MMA(1, 0, At, B0); PG8_MMA(1, 1, At, B1); PG8_BAR; PG8_SCHED;
.LBB0_647:
	ds_read_b128 v[144:147], v157
	ds_read_b128 v[148:151], v157 offset:1024
	ds_read_b128 v[174:177], v157 offset:2048
	ds_read_b128 v[178:181], v157 offset:3072
	ds_read_b128 v[182:185], v161
	ds_read_b128 v[186:189], v161 offset:1024
	ds_read_b128 v[190:193], v161 offset:2048
	ds_read_b128 v[194:197], v161 offset:3072
	s_add_u32 s16, s6, 0xfffc0080
	s_addc_u32 s17, s7, -1
	s_cmp_eq_u32 s68, 12
	s_cselect_b32 s37, s1, s17
	s_cselect_b32 s36, s25, s16
	s_cselect_b32 s35, s23, s67
	s_cselect_b32 s34, s65, s66
	s_add_i32 m0, s21, 0xc000
	ds_read_b128 v[198:201], v165
	ds_read_b128 v[202:205], v165 offset:1024
	ds_read_b128 v[206:209], v165 offset:2048
	ds_read_b128 v[214:217], v165 offset:3072
	ds_read_b128 v[218:221], v165 offset:4096
	ds_read_b128 v[222:225], v165 offset:5120
	ds_read_b128 v[226:229], v165 offset:6144
	ds_read_b128 v[230:233], v165 offset:7168
	global_load_lds_dwordx4 v140, s[6:7]
	s_add_i32 m0, s21, 0xe000
	s_nop 0
	global_load_lds_dwordx4 v142, s[6:7]
	s_waitcnt vmcnt(8)
	s_waitcnt lgkmcnt(0)
	s_barrier
	s_setprio 1
	s_waitcnt lgkmcnt(0)
	v_mfma_f32_16x16x32_bf16 v[124:127], v[144:147], v[198:201], v[124:127]
	v_mfma_f32_16x16x32_bf16 v[120:123], v[174:177], v[198:201], v[120:123]
	v_mfma_f32_16x16x32_bf16 v[108:111], v[144:147], v[206:209], v[108:111]
	v_mfma_f32_16x16x32_bf16 v[104:107], v[174:177], v[206:209], v[104:107]
	v_mfma_f32_16x16x32_bf16 v[92:95], v[144:147], v[218:221], v[92:95]
	v_mfma_f32_16x16x32_bf16 v[88:91], v[174:177], v[218:221], v[88:91]
	v_mfma_f32_16x16x32_bf16 v[76:79], v[144:147], v[226:229], v[76:79]
	v_mfma_f32_16x16x32_bf16 v[72:75], v[174:177], v[226:229], v[72:75]
	v_mfma_f32_16x16x32_bf16 v[124:127], v[148:151], v[202:205], v[124:127]
	v_mfma_f32_16x16x32_bf16 v[120:123], v[178:181], v[202:205], v[120:123]
	v_mfma_f32_16x16x32_bf16 v[108:111], v[148:151], v[214:217], v[108:111]
	v_mfma_f32_16x16x32_bf16 v[104:107], v[178:181], v[214:217], v[104:107]
	v_mfma_f32_16x16x32_bf16 v[92:95], v[148:151], v[222:225], v[92:95]
	v_mfma_f32_16x16x32_bf16 v[88:91], v[178:181], v[222:225], v[88:91]
	v_mfma_f32_16x16x32_bf16 v[76:79], v[148:151], v[230:233], v[76:79]
	v_mfma_f32_16x16x32_bf16 v[72:75], v[178:181], v[230:233], v[72:75]
	s_setprio 0
	s_setprio 1
	v_mfma_f32_16x16x32_bf16 v[116:119], v[182:185], v[198:201], v[116:119]
	v_mfma_f32_16x16x32_bf16 v[112:115], v[190:193], v[198:201], v[112:115]
	v_mfma_f32_16x16x32_bf16 v[100:103], v[182:185], v[206:209], v[100:103]
	v_mfma_f32_16x16x32_bf16 v[96:99], v[190:193], v[206:209], v[96:99]
	v_mfma_f32_16x16x32_bf16 v[84:87], v[182:185], v[218:221], v[84:87]
	v_mfma_f32_16x16x32_bf16 v[80:83], v[190:193], v[218:221], v[80:83]
	v_mfma_f32_16x16x32_bf16 v[68:71], v[182:185], v[226:229], v[68:71]
	v_mfma_f32_16x16x32_bf16 v[64:67], v[190:193], v[226:229], v[64:67]
	v_mfma_f32_16x16x32_bf16 v[116:119], v[186:189], v[202:205], v[116:119]
	v_mfma_f32_16x16x32_bf16 v[112:115], v[194:197], v[202:205], v[112:115]
	v_mfma_f32_16x16x32_bf16 v[100:103], v[186:189], v[214:217], v[100:103]
	v_mfma_f32_16x16x32_bf16 v[96:99], v[194:197], v[214:217], v[96:99]
	v_mfma_f32_16x16x32_bf16 v[84:87], v[186:189], v[222:225], v[84:87]
	v_mfma_f32_16x16x32_bf16 v[80:83], v[194:197], v[222:225], v[80:83]
	v_mfma_f32_16x16x32_bf16 v[68:71], v[186:189], v[230:233], v[68:71]
	v_mfma_f32_16x16x32_bf16 v[64:67], v[194:197], v[230:233], v[64:67]
	s_setprio 0
	s_barrier
	s_add_i32 s16, s39, s2
	v_lshl_add_u64 v[154:155], s[34:35], 0, v[132:133]
	s_mov_b32 m0, s16
	ds_read_b128 v[198:201], v165 offset:16384
	ds_read_b128 v[202:205], v165 offset:17408
	ds_read_b128 v[206:209], v165 offset:18432
	ds_read_b128 v[214:217], v165 offset:19456
	ds_read_b128 v[218:221], v165 offset:20480
	ds_read_b128 v[222:225], v165 offset:21504
	ds_read_b128 v[226:229], v165 offset:22528
	ds_read_b128 v[230:233], v165 offset:23552
	global_load_lds_dwordx4 v[154:155], off
	s_add_i32 m0, s16, 0x2000
	s_add_u32 s16, s34, 0x40000
	v_lshl_add_u64 v[158:159], s[34:35], 0, v[128:129]
	s_addc_u32 s17, s35, 0
	s_add_i32 s33, s40, s2
	global_load_lds_dwordx4 v[158:159], off
	s_mov_b32 m0, s33
	v_lshl_add_u64 v[166:167], s[36:37], 0, v[130:131]
	global_load_lds_dwordx4 v132, s[16:17]
	s_add_i32 m0, s33, 0x2000
	s_nop 0
	global_load_lds_dwordx4 v128, s[16:17]
	v_lshl_add_u64 v[162:163], s[36:37], 0, v[134:135]
	s_mov_b32 m0, s21
	s_nop 0
	global_load_lds_dwordx4 v[162:163], off
	s_mov_b32 m0, s4
	s_nop 0
	global_load_lds_dwordx4 v[166:167], off
	s_waitcnt vmcnt(8)
	s_waitcnt lgkmcnt(0)
	s_barrier
; #define PG8_STAGE(bufoff, gbase, voff) do { _Pragma("unroll") for (int _i = 0; _i < 2; ++_i) \
;     __builtin_amdgcn_global_load_lds((const unsigned*)((const char*)(gbase) + (voff)[_i]), (PG8_LAS unsigned*)(lds + (bufoff) + ldsw + _i * 8192), 16, 0, 0); } while (0)
; #define PG8_LDA(dst, b, h) do { _Pragma("unroll") for (int m = 0; m < 4; ++m) _Pragma("unroll") for (int k = 0; k < 2; ++k) dst[m][k] = *(const PG8_LAS bf16x8*)(lds + PG8_SA(b, h) + aoff + m * 2048 + k * 1024); } while (0)
; #define PG8_LDB(dst, b, h) do { _Pragma("unroll") for (int n = 0; n < 2; ++n) _Pragma("unroll") for (int k = 0; k < 2; ++k) dst[n][k] = *(const PG8_LAS bf16x8*)(lds + PG8_SB(b, h) + boff + n * 2048 + k * 1024); } while (0)
; #define PG8_MMA(ai, bj, At, Bt) do { __builtin_amdgcn_s_setprio(1); _Pragma("unroll") for (int m = 0; m < 4; ++m) _Pragma("unroll") for (int n = 0; n < 2; ++n) _Pragma("unroll") for (int k = 0; k < 2; ++k) \
;     acc[ai][bj][m][n] = __builtin_amdgcn_mfma_f32_16x16x32_bf16(Bt[n][k], At[m][k], acc[ai][bj][m][n], 0, 0, 0); __builtin_amdgcn_s_setprio(0); } while (0)
; #define PG8_WAIT_V(n) asm volatile("s_waitcnt vmcnt(" #n ")" ::: "memory")
; #define PG8_WAIT_L(n) asm volatile("s_waitcnt lgkmcnt(" #n ")" ::: "memory")
; #define PG8_BAR __builtin_amdgcn_s_barrier()
; #define PG8_SCHED __builtin_amdgcn_sched_barrier(0)
; template <class Epi, class Sched>
; DI void gemm_phase(PG8_LAS unsigned char* lds, const Gemm g, const Sched& S, const Epi& E) {
;     ...
;       PG8_WAIT_V(8); PG8_WAIT_L(0); PG8_BAR; PG8_MMA(1, 0, At, B0); PG8_MMA(1, 1, At, B1); PG8_BAR; PG8_SCHED;
;       PG8_LDB(B0, 1, 0); PG8_LDB(B1, 1, 1); PG8_SCHED; PG8_LDA(At, 1, 0); PG8_STAGE(PG8_SA(0, 1), a2 + hstepA, voffA);
;       PG8_WAIT_V(8); PG8_WAIT_L(0); PG8_BAR; PG8_MMA(0, 0, At, B0); PG8_MMA(0, 1, At, B1); PG8_BAR; PG8_SCHED;
	s_setprio 1
	s_waitcnt lgkmcnt(0)
	v_mfma_f32_16x16x32_bf16 v[60:63], v[144:147], v[198:201], v[60:63]
	v_mfma_f32_16x16x32_bf16 v[56:59], v[174:177], v[198:201], v[56:59]
	v_mfma_f32_16x16x32_bf16 v[44:47], v[144:147], v[206:209], v[44:47]
	v_mfma_f32_16x16x32_bf16 v[40:43], v[174:177], v[206:209], v[40:43]
	v_mfma_f32_16x16x32_bf16 v[28:31], v[144:147], v[218:221], v[28:31]
	v_mfma_f32_16x16x32_bf16 v[24:27], v[174:177], v[218:221], v[24:27]
	v_mfma_f32_16x16x32_bf16 v[12:15], v[144:147], v[226:229], v[12:15]
	v_mfma_f32_16x16x32_bf16 v[8:11], v[174:177], v[226:229], v[8:11]
	v_mfma_f32_16x16x32_bf16 v[60:63], v[148:151], v[202:205], v[60:63]
	v_mfma_f32_16x16x32_bf16 v[56:59], v[178:181], v[202:205], v[56:59]
	v_mfma_f32_16x16x32_bf16 v[44:47], v[148:151], v[214:217], v[44:47]
	v_mfma_f32_16x16x32_bf16 v[40:43], v[178:181], v[214:217], v[40:43]
	v_mfma_f32_16x16x32_bf16 v[28:31], v[148:151], v[222:225], v[28:31]
	v_mfma_f32_16x16x32_bf16 v[24:27], v[178:181], v[222:225], v[24:27]
	v_mfma_f32_16x16x32_bf16 v[12:15], v[148:151], v[230:233], v[12:15]
	v_mfma_f32_16x16x32_bf16 v[8:11], v[178:181], v[230:233], v[8:11]
	s_setprio 0
	s_setprio 1
	v_mfma_f32_16x16x32_bf16 v[52:55], v[182:185], v[198:201], v[52:55]
	v_mfma_f32_16x16x32_bf16 v[48:51], v[190:193], v[198:201], v[48:51]
	v_mfma_f32_16x16x32_bf16 v[36:39], v[182:185], v[206:209], v[36:39]
	v_mfma_f32_16x16x32_bf16 v[32:35], v[190:193], v[206:209], v[32:35]
	v_mfma_f32_16x16x32_bf16 v[20:23], v[182:185], v[218:221], v[20:23]
	v_mfma_f32_16x16x32_bf16 v[16:19], v[190:193], v[218:221], v[16:19]
	v_mfma_f32_16x16x32_bf16 v[4:7], v[182:185], v[226:229], v[4:7]
	v_mfma_f32_16x16x32_bf16 v[0:3], v[190:193], v[226:229], v[0:3]
	v_mfma_f32_16x16x32_bf16 v[52:55], v[186:189], v[202:205], v[52:55]
	v_mfma_f32_16x16x32_bf16 v[48:51], v[194:197], v[202:205], v[48:51]
	v_mfma_f32_16x16x32_bf16 v[36:39], v[186:189], v[214:217], v[36:39]
	v_mfma_f32_16x16x32_bf16 v[32:35], v[194:197], v[214:217], v[32:35]
	v_mfma_f32_16x16x32_bf16 v[20:23], v[186:189], v[222:225], v[20:23]
	v_mfma_f32_16x16x32_bf16 v[16:19], v[194:197], v[222:225], v[16:19]
	v_mfma_f32_16x16x32_bf16 v[4:7], v[186:189], v[230:233], v[4:7]
	v_mfma_f32_16x16x32_bf16 v[0:3], v[194:197], v[230:233], v[0:3]
	s_setprio 0
	s_barrier
	ds_read_b128 v[144:147], v171
	ds_read_b128 v[148:151], v171 offset:1024
	ds_read_b128 v[174:177], v171 offset:2048
	ds_read_b128 v[178:181], v171 offset:3072
	ds_read_b128 v[182:185], v173
	ds_read_b128 v[186:189], v173 offset:1024
	ds_read_b128 v[190:193], v173 offset:2048
	ds_read_b128 v[194:197], v173 offset:3072
	s_add_u32 s16, s36, 0x40000
	s_addc_u32 s17, s37, 0
	s_mov_b32 m0, s5
	ds_read_b128 v[198:201], v165 offset:32768
	ds_read_b128 v[202:205], v165 offset:33792
	ds_read_b128 v[206:209], v165 offset:34816
	ds_read_b128 v[214:217], v165 offset:35840
	ds_read_b128 v[218:221], v165 offset:36864
	ds_read_b128 v[222:225], v165 offset:37888
	ds_read_b128 v[226:229], v165 offset:38912
	ds_read_b128 v[230:233], v165 offset:39936
	global_load_lds_dwordx4 v134, s[16:17]
	s_mov_b32 m0, s18
	s_nop 0
	global_load_lds_dwordx4 v130, s[16:17]
	s_waitcnt vmcnt(8)
	s_waitcnt lgkmcnt(0)
	s_barrier
	s_setprio 1
	s_waitcnt lgkmcnt(0)
	v_mfma_f32_16x16x32_bf16 v[124:127], v[144:147], v[198:201], v[124:127]
	v_mfma_f32_16x16x32_bf16 v[120:123], v[174:177], v[198:201], v[120:123]
	v_mfma_f32_16x16x32_bf16 v[108:111], v[144:147], v[206:209], v[108:111]
	v_mfma_f32_16x16x32_bf16 v[104:107], v[174:177], v[206:209], v[104:107]
	v_mfma_f32_16x16x32_bf16 v[92:95], v[144:147], v[218:221], v[92:95]
	v_mfma_f32_16x16x32_bf16 v[88:91], v[174:177], v[218:221], v[88:91]
	v_mfma_f32_16x16x32_bf16 v[76:79], v[144:147], v[226:229], v[76:79]
	v_mfma_f32_16x16x32_bf16 v[72:75], v[174:177], v[226:229], v[72:75]
	v_mfma_f32_16x16x32_bf16 v[124:127], v[148:151], v[202:205], v[124:127]
	v_mfma_f32_16x16x32_bf16 v[120:123], v[178:181], v[202:205], v[120:123]
	v_mfma_f32_16x16x32_bf16 v[108:111], v[148:151], v[214:217], v[108:111]
	v_mfma_f32_16x16x32_bf16 v[104:107], v[178:181], v[214:217], v[104:107]
	v_mfma_f32_16x16x32_bf16 v[92:95], v[148:151], v[222:225], v[92:95]
	v_mfma_f32_16x16x32_bf16 v[88:91], v[178:181], v[222:225], v[88:91]
	v_mfma_f32_16x16x32_bf16 v[76:79], v[148:151], v[230:233], v[76:79]
	v_mfma_f32_16x16x32_bf16 v[72:75], v[178:181], v[230:233], v[72:75]
	s_setprio 0
	s_setprio 1
	v_mfma_f32_16x16x32_bf16 v[116:119], v[182:185], v[198:201], v[116:119]
	v_mfma_f32_16x16x32_bf16 v[112:115], v[190:193], v[198:201], v[112:115]
	v_mfma_f32_16x16x32_bf16 v[100:103], v[182:185], v[206:209], v[100:103]
	v_mfma_f32_16x16x32_bf16 v[96:99], v[190:193], v[206:209], v[96:99]
	v_mfma_f32_16x16x32_bf16 v[84:87], v[182:185], v[218:221], v[84:87]
	v_mfma_f32_16x16x32_bf16 v[80:83], v[190:193], v[218:221], v[80:83]
	v_mfma_f32_16x16x32_bf16 v[68:71], v[182:185], v[226:229], v[68:71]
	v_mfma_f32_16x16x32_bf16 v[64:67], v[190:193], v[226:229], v[64:67]
	v_mfma_f32_16x16x32_bf16 v[116:119], v[186:189], v[202:205], v[116:119]
	v_mfma_f32_16x16x32_bf16 v[112:115], v[194:197], v[202:205], v[112:115]
	v_mfma_f32_16x16x32_bf16 v[100:103], v[186:189], v[214:217], v[100:103]
	v_mfma_f32_16x16x32_bf16 v[96:99], v[194:197], v[214:217], v[96:99]
	v_mfma_f32_16x16x32_bf16 v[84:87], v[186:189], v[222:225], v[84:87]
	v_mfma_f32_16x16x32_bf16 v[80:83], v[194:197], v[222:225], v[80:83]
	v_mfma_f32_16x16x32_bf16 v[68:71], v[186:189], v[230:233], v[68:71]
	v_mfma_f32_16x16x32_bf16 v[64:67], v[194:197], v[230:233], v[64:67]
	s_setprio 0
	s_barrier
; #define PG8_STAGE(bufoff, gbase, voff) do { _Pragma("unroll") for (int _i = 0; _i < 2; ++_i) \
;     __builtin_amdgcn_global_load_lds((const unsigned*)((const char*)(gbase) + (voff)[_i]), (PG8_LAS unsigned*)(lds + (bufoff) + ldsw + _i * 8192), 16, 0, 0); } while (0)
; #define PG8_LDA(dst, b, h) do { _Pragma("unroll") for (int m = 0; m < 4; ++m) _Pragma("unroll") for (int k = 0; k < 2; ++k) dst[m][k] = *(const PG8_LAS bf16x8*)(lds + PG8_SA(b, h) + aoff + m * 2048 + k * 1024); } while (0)
; #define PG8_MMA(ai, bj, At, Bt) do { __builtin_amdgcn_s_setprio(1); _Pragma("unroll") for (int m = 0; m < 4; ++m) _Pragma("unroll") for (int n = 0; n < 2; ++n) _Pragma("unroll") for (int k = 0; k < 2; ++k) \
;     acc[ai][bj][m][n] = __builtin_amdgcn_mfma_f32_16x16x32_bf16(Bt[n][k], At[m][k], acc[ai][bj][m][n], 0, 0, 0); __builtin_amdgcn_s_setprio(0); } while (0)
; #define PG8_WAIT_V(n) asm volatile("s_waitcnt vmcnt(" #n ")" ::: "memory")
; #define PG8_WAIT_L(n) asm volatile("s_waitcnt lgkmcnt(" #n ")" ::: "memory")
; #define PG8_BAR __builtin_amdgcn_s_barrier()
; #define PG8_SCHED __builtin_amdgcn_sched_barrier(0)
; DI void rows_rstd(float (&rs)[2][4], const float* ps, const Unit& u, int wr, int fr, int fq, int p_lo, int p_hi, float inv_dim) {
;   f32x4 pv[2][4];
; #pragma unroll
;   for (int ai = 0; ai < 2; ++ai)
; #pragma unroll
;     for (int m = 0; m < 4; ++m) pv[ai][m] = *(const f32x4*)(ps + (size_t)(u.pm * BM + ai * HALF + wr * 64 + m * 16 + fr) * 16 + 4 * fq);
; template <class Epi, class Sched>
; DI void gemm_phase(PG8_LAS unsigned char* lds, const Gemm g, const Sched& S, const Epi& E) {
;     ...
;       PG8_LDA(At, 1, 1); PG8_STAGE(PG8_SB(1, 0), b3, voffB); PG8_STAGE(PG8_SB(1, 1), b3 + hstepB, voffB); PG8_STAGE(PG8_SA(1, 0), a3, voffA);
;       PG8_WAIT_V(8); PG8_WAIT_L(0); PG8_BAR; PG8_MMA(1, 0, At, B0); PG8_MMA(1, 1, At, B1); PG8_BAR; PG8_SCHED;
;     }
	s_add_i32 s16, s45, s2
	v_lshl_add_u64 v[154:155], v[154:155], 0, s[10:11]
	s_mov_b32 m0, s16
	ds_read_b128 v[198:201], v165 offset:49152
	ds_read_b128 v[202:205], v165 offset:50176
	ds_read_b128 v[206:209], v165 offset:51200
	ds_read_b128 v[214:217], v165 offset:52224
	ds_read_b128 v[218:221], v165 offset:53248
	ds_read_b128 v[222:225], v165 offset:54272
	ds_read_b128 v[226:229], v165 offset:55296
	ds_read_b128 v[230:233], v165 offset:56320
	global_load_lds_dwordx4 v[154:155], off
	s_add_i32 m0, s16, 0x2000
	s_add_u32 s16, s34, 0x40080
	v_lshl_add_u64 v[154:155], v[158:159], 0, s[10:11]
	s_addc_u32 s17, s35, 0
	s_add_i32 s33, s53, s2
	global_load_lds_dwordx4 v[154:155], off
	s_mov_b32 m0, s33
	s_nop 0
	global_load_lds_dwordx4 v132, s[16:17]
	s_add_i32 m0, s33, 0x2000
	s_nop 0
	global_load_lds_dwordx4 v128, s[16:17]
	v_lshl_add_u64 v[154:155], v[162:163], 0, s[10:11]
	s_mov_b32 m0, s19
	s_nop 0
	global_load_lds_dwordx4 v[154:155], off
	v_lshl_add_u64 v[154:155], v[166:167], 0, s[10:11]
	s_mov_b32 m0, s38
	s_nop 0
	global_load_lds_dwordx4 v[154:155], off
	s_waitcnt vmcnt(8)
	s_waitcnt lgkmcnt(0)
	s_barrier
	s_setprio 1
	s_waitcnt lgkmcnt(0)
	v_mfma_f32_16x16x32_bf16 v[60:63], v[144:147], v[198:201], v[60:63]
	v_mfma_f32_16x16x32_bf16 v[56:59], v[174:177], v[198:201], v[56:59]
	v_mfma_f32_16x16x32_bf16 v[44:47], v[144:147], v[206:209], v[44:47]
	v_mfma_f32_16x16x32_bf16 v[40:43], v[174:177], v[206:209], v[40:43]
	v_mfma_f32_16x16x32_bf16 v[28:31], v[144:147], v[218:221], v[28:31]
	v_mfma_f32_16x16x32_bf16 v[24:27], v[174:177], v[218:221], v[24:27]
	v_mfma_f32_16x16x32_bf16 v[12:15], v[144:147], v[226:229], v[12:15]
	v_mfma_f32_16x16x32_bf16 v[8:11], v[174:177], v[226:229], v[8:11]
	v_mfma_f32_16x16x32_bf16 v[60:63], v[148:151], v[202:205], v[60:63]
	v_mfma_f32_16x16x32_bf16 v[56:59], v[178:181], v[202:205], v[56:59]
	v_mfma_f32_16x16x32_bf16 v[44:47], v[148:151], v[214:217], v[44:47]
	v_mfma_f32_16x16x32_bf16 v[40:43], v[178:181], v[214:217], v[40:43]
	v_mfma_f32_16x16x32_bf16 v[28:31], v[148:151], v[222:225], v[28:31]
	v_mfma_f32_16x16x32_bf16 v[24:27], v[178:181], v[222:225], v[24:27]
	v_mfma_f32_16x16x32_bf16 v[12:15], v[148:151], v[230:233], v[12:15]
	v_mfma_f32_16x16x32_bf16 v[8:11], v[178:181], v[230:233], v[8:11]
	s_setprio 0
	s_setprio 1
	v_mfma_f32_16x16x32_bf16 v[52:55], v[182:185], v[198:201], v[52:55]
	v_mfma_f32_16x16x32_bf16 v[48:51], v[190:193], v[198:201], v[48:51]
	v_mfma_f32_16x16x32_bf16 v[36:39], v[182:185], v[206:209], v[36:39]
	v_mfma_f32_16x16x32_bf16 v[32:35], v[190:193], v[206:209], v[32:35]
	v_mfma_f32_16x16x32_bf16 v[20:23], v[182:185], v[218:221], v[20:23]
	v_mfma_f32_16x16x32_bf16 v[16:19], v[190:193], v[218:221], v[16:19]
	v_mfma_f32_16x16x32_bf16 v[4:7], v[182:185], v[226:229], v[4:7]
	v_mfma_f32_16x16x32_bf16 v[0:3], v[190:193], v[226:229], v[0:3]
	v_mfma_f32_16x16x32_bf16 v[52:55], v[186:189], v[202:205], v[52:55]
	v_mfma_f32_16x16x32_bf16 v[48:51], v[194:197], v[202:205], v[48:51]
	v_mfma_f32_16x16x32_bf16 v[36:39], v[186:189], v[214:217], v[36:39]
	v_mfma_f32_16x16x32_bf16 v[32:35], v[194:197], v[214:217], v[32:35]
	v_mfma_f32_16x16x32_bf16 v[20:23], v[186:189], v[222:225], v[20:23]
	v_mfma_f32_16x16x32_bf16 v[16:19], v[194:197], v[222:225], v[16:19]
	v_mfma_f32_16x16x32_bf16 v[4:7], v[186:189], v[230:233], v[4:7]
	v_mfma_f32_16x16x32_bf16 v[0:3], v[194:197], v[230:233], v[0:3]
	s_setprio 0
	s_barrier
	s_add_i32 s68, s68, 2
	s_add_u32 s6, s6, 0x100
	s_addc_u32 s7, s7, 0
	s_add_u32 s66, s66, 0x100
	s_addc_u32 s67, s67, 0
	s_cmp_gt_u32 s68, 13
	s_cbranch_scc0 .LBB0_647
	v_lshl_add_u32 v166, s0, 8, v153
	v_or_b32_e32 v162, 16, v166
	v_ashrrev_i32_e32 v167, 31, v166
	v_ashrrev_i32_e32 v163, 31, v162
	v_or_b32_e32 v158, 32, v166
	v_lshlrev_b64 v[146:147], 6, v[166:167]
	v_lshlrev_b64 v[144:145], 6, v[162:163]
	v_ashrrev_i32_e32 v159, 31, v158
	v_lshl_add_u64 v[146:147], v[138:139], 0, v[146:147]
	v_or_b32_e32 v154, 48, v166
	v_lshl_add_u64 v[144:145], v[138:139], 0, v[144:145]
	global_load_dwordx4 v[174:177], v[146:147], off
	v_lshlrev_b64 v[146:147], 6, v[158:159]
	v_ashrrev_i32_e32 v155, 31, v154
	v_lshl_add_u64 v[146:147], v[138:139], 0, v[146:147]
	global_load_dwordx4 v[178:181], v[144:145], off
	global_load_dwordx4 v[182:185], v[146:147], off
	v_lshlrev_b64 v[144:145], 6, v[154:155]
	v_lshl_add_u64 v[144:145], v[138:139], 0, v[144:145]
	global_load_dwordx4 v[186:189], v[144:145], off
	v_add_u32_e32 v150, 0x80, v166
	v_ashrrev_i32_e32 v151, 31, v150
	v_lshlrev_b64 v[144:145], 6, v[150:151]
	v_add_u32_e32 v148, 0x90, v166
	v_lshl_add_u64 v[144:145], v[138:139], 0, v[144:145]
	v_ashrrev_i32_e32 v149, 31, v148
	global_load_dwordx4 v[190:193], v[144:145], off
	v_lshlrev_b64 v[144:145], 6, v[148:149]
	v_lshl_add_u64 v[144:145], v[138:139], 0, v[144:145]
	global_load_dwordx4 v[194:197], v[144:145], off
	v_and_b32_e32 v145, 64, v169
	v_add_u32_e32 v144, 0xb0, v166
	v_add_u32_e32 v146, 0xa0, v166
	v_add_u32_e32 v152, 64, v145
	v_ashrrev_i32_e32 v145, 31, v144
	v_ashrrev_i32_e32 v147, 31, v146
	v_lshlrev_b64 v[198:199], 6, v[144:145]
	v_lshlrev_b64 v[200:201], 6, v[146:147]
	v_lshl_add_u64 v[198:199], v[138:139], 0, v[198:199]
	v_lshl_add_u64 v[202:203], v[138:139], 0, v[200:201]
	global_load_dwordx4 v[198:201], v[198:199], off
	s_nop 0
	global_load_dwordx4 v[202:205], v[202:203], off
	s_and_b64 vcc, exec, s[12:13]
	s_cbranch_vccz .LBB0_650
	s_barrier

; #define PG8_STAGE(bufoff, gbase, voff) do { _Pragma("unroll") for (int _i = 0; _i < 2; ++_i) \
;     __builtin_amdgcn_global_load_lds((const unsigned*)((const char*)(gbase) + (voff)[_i]), (PG8_LAS unsigned*)(lds + (bufoff) + ldsw + _i * 8192), 16, 0, 0); } while (0)
; #define PG8_LDA(dst, b, h) do { _Pragma("unroll") for (int m = 0; m < 4; ++m) _Pragma("unroll") for (int k = 0; k < 2; ++k) dst[m][k] = *(const PG8_LAS bf16x8*)(lds + PG8_SA(b, h) + aoff + m * 2048 + k * 1024); } while (0)
; #define PG8_LDB(dst, b, h) do { _Pragma("unroll") for (int n = 0; n < 2; ++n) _Pragma("unroll") for (int k = 0; k < 2; ++k) dst[n][k] = *(const PG8_LAS bf16x8*)(lds + PG8_SB(b, h) + boff + n * 2048 + k * 1024); } while (0)
; #define PG8_MMA(ai, bj, At, Bt) do { __builtin_amdgcn_s_setprio(1); _Pragma("unroll") for (int m = 0; m < 4; ++m) _Pragma("unroll") for (int n = 0; n < 2; ++n) _Pragma("unroll") for (int k = 0; k < 2; ++k) \
;     acc[ai][bj][m][n] = __builtin_amdgcn_mfma_f32_16x16x32_bf16(Bt[n][k], At[m][k], acc[ai][bj][m][n], 0, 0, 0); __builtin_amdgcn_s_setprio(0); } while (0)
; #define PG8_WAIT_V(n) asm volatile("s_waitcnt vmcnt(" #n ")" ::: "memory")
; #define PG8_WAIT_L(n) asm volatile("s_waitcnt lgkmcnt(" #n ")" ::: "memory")
; #define PG8_BAR __builtin_amdgcn_s_barrier()
; #define PG8_SCHED __builtin_amdgcn_sched_barrier(0)
; template <class Epi, class Sched>
; DI void gemm_phase(PG8_LAS unsigned char* lds, const Gemm g, const Sched& S, const Epi& E) {
;     ...
;     for (int t = 0; t < nt; t += 2) {
;       const bool last = (t == nt - 2);
;       const char* a1 = cA + (size_t)(t + 1) * kstep;
;       const char* a2 = last ? nA : cA + (size_t)(t + 2) * kstep; const char* b2 = last ? nB : cB + (size_t)(t + 2) * kstep;
;       const char* a3 = a2 + kstep; const char* b3 = b2 + kstep;
;       PG8_LDB(B0, 0, 0); PG8_LDB(B1, 0, 1); PG8_SCHED; PG8_LDA(At, 0, 0); PG8_STAGE(PG8_SA(1, 1), a1 + hstepA, voffA);
;       PG8_WAIT_V(8); PG8_WAIT_L(0); PG8_BAR; PG8_MMA(0, 0, At, B0); PG8_MMA(0, 1, At, B1); PG8_BAR; PG8_SCHED;
;       PG8_LDA(At, 0, 1); PG8_STAGE(PG8_SB(0, 0), b2, voffB); PG8_STAGE(PG8_SB(0, 1), b2 + hstepB, voffB); PG8_STAGE(PG8_SA(0, 0), a2, voffA);
;       PG8_WAIT_V(8); PG8_WAIT_L(0); PG8_BAR; PG8_MMA(1, 0, At, B0); PG8_MMA(1, 1, At, B1); PG8_BAR; PG8_SCHED;
.LBB0_721:
	ds_read_b128 v[128:131], v156
	ds_read_b128 v[132:135], v156 offset:1024
	ds_read_b128 v[150:153], v156 offset:2048
	ds_read_b128 v[162:165], v156 offset:3072
	ds_read_b128 v[166:169], v157
	ds_read_b128 v[170:173], v157 offset:1024
	ds_read_b128 v[174:177], v157 offset:2048
	ds_read_b128 v[178:181], v157 offset:3072
	s_add_u32 s26, s24, 0x100
	s_addc_u32 s27, s25, 0
	s_cmp_eq_u32 s65, 40
	s_cselect_b32 s31, s21, s27
	s_cselect_b32 s30, s20, s26
	s_cselect_b32 s29, s23, s64
	s_cselect_b32 s28, s22, s55
	s_add_i32 m0, s3, 0xc000
	ds_read_b128 v[182:185], v158
	ds_read_b128 v[186:189], v158 offset:1024
	ds_read_b128 v[190:193], v158 offset:2048
	ds_read_b128 v[194:197], v158 offset:3072
	ds_read_b128 v[198:201], v158 offset:4096
	ds_read_b128 v[202:205], v158 offset:5120
	ds_read_b128 v[206:209], v158 offset:6144
	ds_read_b128 v[214:217], v158 offset:7168
	global_load_lds_dwordx4 v146, s[24:25]
	s_add_i32 m0, s3, 0xe000
	s_nop 0
	global_load_lds_dwordx4 v148, s[24:25]
	s_waitcnt vmcnt(8)
	s_waitcnt lgkmcnt(0)
	s_barrier
	s_setprio 1
	s_waitcnt lgkmcnt(0)
	v_mfma_f32_16x16x32_bf16 v[124:127], v[128:131], v[182:185], v[124:127]
	v_mfma_f32_16x16x32_bf16 v[120:123], v[150:153], v[182:185], v[120:123]
	v_mfma_f32_16x16x32_bf16 v[108:111], v[128:131], v[190:193], v[108:111]
	v_mfma_f32_16x16x32_bf16 v[104:107], v[150:153], v[190:193], v[104:107]
	v_mfma_f32_16x16x32_bf16 v[92:95], v[128:131], v[198:201], v[92:95]
	v_mfma_f32_16x16x32_bf16 v[88:91], v[150:153], v[198:201], v[88:91]
	v_mfma_f32_16x16x32_bf16 v[76:79], v[128:131], v[206:209], v[76:79]
	v_mfma_f32_16x16x32_bf16 v[72:75], v[150:153], v[206:209], v[72:75]
	v_mfma_f32_16x16x32_bf16 v[124:127], v[132:135], v[186:189], v[124:127]
	v_mfma_f32_16x16x32_bf16 v[120:123], v[162:165], v[186:189], v[120:123]
	v_mfma_f32_16x16x32_bf16 v[108:111], v[132:135], v[194:197], v[108:111]
	v_mfma_f32_16x16x32_bf16 v[104:107], v[162:165], v[194:197], v[104:107]
	v_mfma_f32_16x16x32_bf16 v[92:95], v[132:135], v[202:205], v[92:95]
	v_mfma_f32_16x16x32_bf16 v[88:91], v[162:165], v[202:205], v[88:91]
	v_mfma_f32_16x16x32_bf16 v[76:79], v[132:135], v[214:217], v[76:79]
	v_mfma_f32_16x16x32_bf16 v[72:75], v[162:165], v[214:217], v[72:75]
	s_setprio 0
	s_setprio 1
	v_mfma_f32_16x16x32_bf16 v[116:119], v[166:169], v[182:185], v[116:119]
	v_mfma_f32_16x16x32_bf16 v[112:115], v[174:177], v[182:185], v[112:115]
	v_mfma_f32_16x16x32_bf16 v[100:103], v[166:169], v[190:193], v[100:103]
	v_mfma_f32_16x16x32_bf16 v[96:99], v[174:177], v[190:193], v[96:99]
	v_mfma_f32_16x16x32_bf16 v[84:87], v[166:169], v[198:201], v[84:87]
	v_mfma_f32_16x16x32_bf16 v[80:83], v[174:177], v[198:201], v[80:83]
	v_mfma_f32_16x16x32_bf16 v[68:71], v[166:169], v[206:209], v[68:71]
	v_mfma_f32_16x16x32_bf16 v[64:67], v[174:177], v[206:209], v[64:67]
	v_mfma_f32_16x16x32_bf16 v[116:119], v[170:173], v[186:189], v[116:119]
	v_mfma_f32_16x16x32_bf16 v[112:115], v[178:181], v[186:189], v[112:115]
	v_mfma_f32_16x16x32_bf16 v[100:103], v[170:173], v[194:197], v[100:103]
	v_mfma_f32_16x16x32_bf16 v[96:99], v[178:181], v[194:197], v[96:99]
	v_mfma_f32_16x16x32_bf16 v[84:87], v[170:173], v[202:205], v[84:87]
	v_mfma_f32_16x16x32_bf16 v[80:83], v[178:181], v[202:205], v[80:83]
	v_mfma_f32_16x16x32_bf16 v[68:71], v[170:173], v[214:217], v[68:71]
	v_mfma_f32_16x16x32_bf16 v[64:67], v[178:181], v[214:217], v[64:67]
	s_setprio 0
	s_barrier
	s_add_i32 s16, s37, s2
	v_lshl_add_u64 v[210:211], s[28:29], 0, v[138:139]
	s_mov_b32 m0, s16
	ds_read_b128 v[182:185], v158 offset:16384
	ds_read_b128 v[186:189], v158 offset:17408
	ds_read_b128 v[190:193], v158 offset:18432
	ds_read_b128 v[194:197], v158 offset:19456
	ds_read_b128 v[198:201], v158 offset:20480
	ds_read_b128 v[202:205], v158 offset:21504
	ds_read_b128 v[206:209], v158 offset:22528
	ds_read_b128 v[214:217], v158 offset:23552
	global_load_lds_dwordx4 v[210:211], off
	s_add_i32 m0, s16, 0x2000
	s_add_u32 s16, s28, 0xb0000
	v_lshl_add_u64 v[218:219], s[28:29], 0, v[142:143]
	s_addc_u32 s17, s29, 0
	s_add_i32 s24, s38, s2
	global_load_lds_dwordx4 v[218:219], off
	s_mov_b32 m0, s24
	v_lshl_add_u64 v[222:223], s[30:31], 0, v[140:141]
	global_load_lds_dwordx4 v138, s[16:17]
	s_add_i32 m0, s24, 0x2000
	s_nop 0
	global_load_lds_dwordx4 v142, s[16:17]
	v_lshl_add_u64 v[220:221], s[30:31], 0, v[136:137]
	s_mov_b32 m0, s3
	s_nop 0
	global_load_lds_dwordx4 v[220:221], off
	s_mov_b32 m0, s34
	s_nop 0
	global_load_lds_dwordx4 v[222:223], off
	s_waitcnt vmcnt(8)
	s_waitcnt lgkmcnt(0)
	s_barrier
; #define PG8_STAGE(bufoff, gbase, voff) do { _Pragma("unroll") for (int _i = 0; _i < 2; ++_i) \
;     __builtin_amdgcn_global_load_lds((const unsigned*)((const char*)(gbase) + (voff)[_i]), (PG8_LAS unsigned*)(lds + (bufoff) + ldsw + _i * 8192), 16, 0, 0); } while (0)
; #define PG8_LDA(dst, b, h) do { _Pragma("unroll") for (int m = 0; m < 4; ++m) _Pragma("unroll") for (int k = 0; k < 2; ++k) dst[m][k] = *(const PG8_LAS bf16x8*)(lds + PG8_SA(b, h) + aoff + m * 2048 + k * 1024); } while (0)
; #define PG8_LDB(dst, b, h) do { _Pragma("unroll") for (int n = 0; n < 2; ++n) _Pragma("unroll") for (int k = 0; k < 2; ++k) dst[n][k] = *(const PG8_LAS bf16x8*)(lds + PG8_SB(b, h) + boff + n * 2048 + k * 1024); } while (0)
; #define PG8_MMA(ai, bj, At, Bt) do { __builtin_amdgcn_s_setprio(1); _Pragma("unroll") for (int m = 0; m < 4; ++m) _Pragma("unroll") for (int n = 0; n < 2; ++n) _Pragma("unroll") for (int k = 0; k < 2; ++k) \
;     acc[ai][bj][m][n] = __builtin_amdgcn_mfma_f32_16x16x32_bf16(Bt[n][k], At[m][k], acc[ai][bj][m][n], 0, 0, 0); __builtin_amdgcn_s_setprio(0); } while (0)
; #define PG8_WAIT_V(n) asm volatile("s_waitcnt vmcnt(" #n ")" ::: "memory")
; #define PG8_WAIT_L(n) asm volatile("s_waitcnt lgkmcnt(" #n ")" ::: "memory")
; #define PG8_BAR __builtin_amdgcn_s_barrier()
; #define PG8_SCHED __builtin_amdgcn_sched_barrier(0)
; template <class Epi, class Sched>
; DI void gemm_phase(PG8_LAS unsigned char* lds, const Gemm g, const Sched& S, const Epi& E) {
;     ...
;       PG8_WAIT_V(8); PG8_WAIT_L(0); PG8_BAR; PG8_MMA(1, 0, At, B0); PG8_MMA(1, 1, At, B1); PG8_BAR; PG8_SCHED;
;       PG8_LDB(B0, 1, 0); PG8_LDB(B1, 1, 1); PG8_SCHED; PG8_LDA(At, 1, 0); PG8_STAGE(PG8_SA(0, 1), a2 + hstepA, voffA);
;       PG8_WAIT_V(8); PG8_WAIT_L(0); PG8_BAR; PG8_MMA(0, 0, At, B0); PG8_MMA(0, 1, At, B1); PG8_BAR; PG8_SCHED;
	s_setprio 1
	s_waitcnt lgkmcnt(0)
	v_mfma_f32_16x16x32_bf16 v[60:63], v[128:131], v[182:185], v[60:63]
	v_mfma_f32_16x16x32_bf16 v[56:59], v[150:153], v[182:185], v[56:59]
	v_mfma_f32_16x16x32_bf16 v[44:47], v[128:131], v[190:193], v[44:47]
	v_mfma_f32_16x16x32_bf16 v[40:43], v[150:153], v[190:193], v[40:43]
	v_mfma_f32_16x16x32_bf16 v[28:31], v[128:131], v[198:201], v[28:31]
	v_mfma_f32_16x16x32_bf16 v[24:27], v[150:153], v[198:201], v[24:27]
	v_mfma_f32_16x16x32_bf16 v[12:15], v[128:131], v[206:209], v[12:15]
	v_mfma_f32_16x16x32_bf16 v[8:11], v[150:153], v[206:209], v[8:11]
	v_mfma_f32_16x16x32_bf16 v[60:63], v[132:135], v[186:189], v[60:63]
	v_mfma_f32_16x16x32_bf16 v[56:59], v[162:165], v[186:189], v[56:59]
	v_mfma_f32_16x16x32_bf16 v[44:47], v[132:135], v[194:197], v[44:47]
	v_mfma_f32_16x16x32_bf16 v[40:43], v[162:165], v[194:197], v[40:43]
	v_mfma_f32_16x16x32_bf16 v[28:31], v[132:135], v[202:205], v[28:31]
	v_mfma_f32_16x16x32_bf16 v[24:27], v[162:165], v[202:205], v[24:27]
	v_mfma_f32_16x16x32_bf16 v[12:15], v[132:135], v[214:217], v[12:15]
	v_mfma_f32_16x16x32_bf16 v[8:11], v[162:165], v[214:217], v[8:11]
	s_setprio 0
	s_setprio 1
	v_mfma_f32_16x16x32_bf16 v[52:55], v[166:169], v[182:185], v[52:55]
	v_mfma_f32_16x16x32_bf16 v[48:51], v[174:177], v[182:185], v[48:51]
	v_mfma_f32_16x16x32_bf16 v[36:39], v[166:169], v[190:193], v[36:39]
	v_mfma_f32_16x16x32_bf16 v[32:35], v[174:177], v[190:193], v[32:35]
	v_mfma_f32_16x16x32_bf16 v[20:23], v[166:169], v[198:201], v[20:23]
	v_mfma_f32_16x16x32_bf16 v[16:19], v[174:177], v[198:201], v[16:19]
	v_mfma_f32_16x16x32_bf16 v[4:7], v[166:169], v[206:209], v[4:7]
	v_mfma_f32_16x16x32_bf16 v[0:3], v[174:177], v[206:209], v[0:3]
	v_mfma_f32_16x16x32_bf16 v[52:55], v[170:173], v[186:189], v[52:55]
	v_mfma_f32_16x16x32_bf16 v[48:51], v[178:181], v[186:189], v[48:51]
	v_mfma_f32_16x16x32_bf16 v[36:39], v[170:173], v[194:197], v[36:39]
	v_mfma_f32_16x16x32_bf16 v[32:35], v[178:181], v[194:197], v[32:35]
	v_mfma_f32_16x16x32_bf16 v[20:23], v[170:173], v[202:205], v[20:23]
	v_mfma_f32_16x16x32_bf16 v[16:19], v[178:181], v[202:205], v[16:19]
	v_mfma_f32_16x16x32_bf16 v[4:7], v[170:173], v[214:217], v[4:7]
	v_mfma_f32_16x16x32_bf16 v[0:3], v[178:181], v[214:217], v[0:3]
	s_setprio 0
	s_barrier
	s_mov_b32 s16, 0x18000
	s_add_i32 s24, s16, 0x110
	v_add_u32_e32 v161, s24, v155
	ds_read_b128 v[128:131], v161
	ds_read_b128 v[132:135], v161 offset:1024
	ds_read_b128 v[150:153], v161 offset:2048
	ds_read_b128 v[162:165], v161 offset:3072
	ds_read_b128 v[166:169], v160
	ds_read_b128 v[170:173], v160 offset:1024
	ds_read_b128 v[174:177], v160 offset:2048
	ds_read_b128 v[178:181], v160 offset:3072
	s_add_u32 s16, s30, 0xb0000
	s_addc_u32 s17, s31, 0
	s_mov_b32 m0, s18
	ds_read_b128 v[182:185], v158 offset:32768
	ds_read_b128 v[186:189], v158 offset:33792
	ds_read_b128 v[190:193], v158 offset:34816
	ds_read_b128 v[194:197], v158 offset:35840
	ds_read_b128 v[198:201], v158 offset:36864
	ds_read_b128 v[202:205], v158 offset:37888
	ds_read_b128 v[206:209], v158 offset:38912
	ds_read_b128 v[214:217], v158 offset:39936
	global_load_lds_dwordx4 v136, s[16:17]
	s_mov_b32 m0, s19
	s_nop 0
	global_load_lds_dwordx4 v140, s[16:17]
	s_waitcnt vmcnt(8)
	s_waitcnt lgkmcnt(0)
	s_barrier
	s_setprio 1
	s_waitcnt lgkmcnt(0)
	v_mfma_f32_16x16x32_bf16 v[124:127], v[128:131], v[182:185], v[124:127]
	v_mfma_f32_16x16x32_bf16 v[120:123], v[150:153], v[182:185], v[120:123]
	v_mfma_f32_16x16x32_bf16 v[108:111], v[128:131], v[190:193], v[108:111]
	v_mfma_f32_16x16x32_bf16 v[104:107], v[150:153], v[190:193], v[104:107]
	v_mfma_f32_16x16x32_bf16 v[92:95], v[128:131], v[198:201], v[92:95]
	v_mfma_f32_16x16x32_bf16 v[88:91], v[150:153], v[198:201], v[88:91]
	v_mfma_f32_16x16x32_bf16 v[76:79], v[128:131], v[206:209], v[76:79]
	v_mfma_f32_16x16x32_bf16 v[72:75], v[150:153], v[206:209], v[72:75]
	v_mfma_f32_16x16x32_bf16 v[124:127], v[132:135], v[186:189], v[124:127]
	v_mfma_f32_16x16x32_bf16 v[120:123], v[162:165], v[186:189], v[120:123]
	v_mfma_f32_16x16x32_bf16 v[108:111], v[132:135], v[194:197], v[108:111]
	v_mfma_f32_16x16x32_bf16 v[104:107], v[162:165], v[194:197], v[104:107]
	v_mfma_f32_16x16x32_bf16 v[92:95], v[132:135], v[202:205], v[92:95]
	v_mfma_f32_16x16x32_bf16 v[88:91], v[162:165], v[202:205], v[88:91]
	v_mfma_f32_16x16x32_bf16 v[76:79], v[132:135], v[214:217], v[76:79]
	v_mfma_f32_16x16x32_bf16 v[72:75], v[162:165], v[214:217], v[72:75]
	s_setprio 0
	s_setprio 1
	v_mfma_f32_16x16x32_bf16 v[116:119], v[166:169], v[182:185], v[116:119]
	v_mfma_f32_16x16x32_bf16 v[112:115], v[174:177], v[182:185], v[112:115]
	v_mfma_f32_16x16x32_bf16 v[100:103], v[166:169], v[190:193], v[100:103]
	v_mfma_f32_16x16x32_bf16 v[96:99], v[174:177], v[190:193], v[96:99]
	v_mfma_f32_16x16x32_bf16 v[84:87], v[166:169], v[198:201], v[84:87]
	v_mfma_f32_16x16x32_bf16 v[80:83], v[174:177], v[198:201], v[80:83]
	v_mfma_f32_16x16x32_bf16 v[68:71], v[166:169], v[206:209], v[68:71]
	v_mfma_f32_16x16x32_bf16 v[64:67], v[174:177], v[206:209], v[64:67]
	v_mfma_f32_16x16x32_bf16 v[116:119], v[170:173], v[186:189], v[116:119]
	v_mfma_f32_16x16x32_bf16 v[112:115], v[178:181], v[186:189], v[112:115]
	v_mfma_f32_16x16x32_bf16 v[100:103], v[170:173], v[194:197], v[100:103]
	v_mfma_f32_16x16x32_bf16 v[96:99], v[178:181], v[194:197], v[96:99]
	v_mfma_f32_16x16x32_bf16 v[84:87], v[170:173], v[202:205], v[84:87]
	v_mfma_f32_16x16x32_bf16 v[80:83], v[178:181], v[202:205], v[80:83]
	v_mfma_f32_16x16x32_bf16 v[68:71], v[170:173], v[214:217], v[68:71]
	v_mfma_f32_16x16x32_bf16 v[64:67], v[178:181], v[214:217], v[64:67]
	s_setprio 0
	s_barrier
; #define PG8_STAGE(bufoff, gbase, voff) do { _Pragma("unroll") for (int _i = 0; _i < 2; ++_i) \
;     __builtin_amdgcn_global_load_lds((const unsigned*)((const char*)(gbase) + (voff)[_i]), (PG8_LAS unsigned*)(lds + (bufoff) + ldsw + _i * 8192), 16, 0, 0); } while (0)
; #define PG8_LDA(dst, b, h) do { _Pragma("unroll") for (int m = 0; m < 4; ++m) _Pragma("unroll") for (int k = 0; k < 2; ++k) dst[m][k] = *(const PG8_LAS bf16x8*)(lds + PG8_SA(b, h) + aoff + m * 2048 + k * 1024); } while (0)
; #define PG8_MMA(ai, bj, At, Bt) do { __builtin_amdgcn_s_setprio(1); _Pragma("unroll") for (int m = 0; m < 4; ++m) _Pragma("unroll") for (int n = 0; n < 2; ++n) _Pragma("unroll") for (int k = 0; k < 2; ++k) \
;     acc[ai][bj][m][n] = __builtin_amdgcn_mfma_f32_16x16x32_bf16(Bt[n][k], At[m][k], acc[ai][bj][m][n], 0, 0, 0); __builtin_amdgcn_s_setprio(0); } while (0)
; #define PG8_WAIT_V(n) asm volatile("s_waitcnt vmcnt(" #n ")" ::: "memory")
; #define PG8_WAIT_L(n) asm volatile("s_waitcnt lgkmcnt(" #n ")" ::: "memory")
; #define PG8_BAR __builtin_amdgcn_s_barrier()
; #define PG8_SCHED __builtin_amdgcn_sched_barrier(0)
;   DI void operator()(const f32x4 (&acc)[2][2][4][2], const Unit& u, int wr, int wc, int fr, int fq) const {
;     const int row0 = u.pm * BM + wr * 64 + fr;
;     const size_t base = (size_t)row0 * DM + u.pn * BM + wc * 32 + 8 * fq;
;     f32x4 xv[2][4];
;     u32x4 xh[2][2];
;     ...
;     RES_LD(0)
; #pragma unroll
;     for (int i = 0; i < 8; ++i) {
;       const int ai = i >> 2, m = i & 3;
;       if (i + 1 < 8) RES_LD(i + 1)
; template <class Epi, class Sched>
; DI void gemm_phase(PG8_LAS unsigned char* lds, const Gemm g, const Sched& S, const Epi& E) {
;     ...
;       PG8_LDA(At, 1, 1); PG8_STAGE(PG8_SB(1, 0), b3, voffB); PG8_STAGE(PG8_SB(1, 1), b3 + hstepB, voffB); PG8_STAGE(PG8_SA(1, 0), a3, voffA);
;       PG8_WAIT_V(8); PG8_WAIT_L(0); PG8_BAR; PG8_MMA(1, 0, At, B0); PG8_MMA(1, 1, At, B1); PG8_BAR; PG8_SCHED;
;     }
	s_add_i32 s16, s24, s2
	v_lshl_add_u64 v[210:211], v[210:211], 0, s[10:11]
	s_mov_b32 m0, s16
	ds_read_b128 v[182:185], v158 offset:49152
	ds_read_b128 v[186:189], v158 offset:50176
	ds_read_b128 v[190:193], v158 offset:51200
	ds_read_b128 v[194:197], v158 offset:52224
	ds_read_b128 v[198:201], v158 offset:53248
	ds_read_b128 v[202:205], v158 offset:54272
	ds_read_b128 v[206:209], v158 offset:55296
	ds_read_b128 v[214:217], v158 offset:56320
	global_load_lds_dwordx4 v[210:211], off
	s_add_i32 m0, s16, 0x2000
	s_add_u32 s16, s28, 0xb0080
	v_lshl_add_u64 v[210:211], v[218:219], 0, s[10:11]
	s_addc_u32 s17, s29, 0
	s_add_i32 s24, s39, s2
	global_load_lds_dwordx4 v[210:211], off
	s_mov_b32 m0, s24
	s_nop 0
	global_load_lds_dwordx4 v138, s[16:17]
	s_add_i32 m0, s24, 0x2000
	s_nop 0
	global_load_lds_dwordx4 v142, s[16:17]
	v_lshl_add_u64 v[210:211], v[220:221], 0, s[10:11]
	s_mov_b32 m0, s5
	s_nop 0
	global_load_lds_dwordx4 v[210:211], off
	v_lshl_add_u64 v[210:211], v[222:223], 0, s[10:11]
	s_mov_b32 m0, s35
	s_nop 0
	global_load_lds_dwordx4 v[210:211], off
	s_waitcnt vmcnt(8)
	s_waitcnt lgkmcnt(0)
	s_barrier
	s_setprio 1
	s_waitcnt lgkmcnt(0)
	v_mfma_f32_16x16x32_bf16 v[60:63], v[128:131], v[182:185], v[60:63]
	v_mfma_f32_16x16x32_bf16 v[56:59], v[150:153], v[182:185], v[56:59]
	v_mfma_f32_16x16x32_bf16 v[44:47], v[128:131], v[190:193], v[44:47]
	v_mfma_f32_16x16x32_bf16 v[40:43], v[150:153], v[190:193], v[40:43]
	v_mfma_f32_16x16x32_bf16 v[28:31], v[128:131], v[198:201], v[28:31]
	v_mfma_f32_16x16x32_bf16 v[24:27], v[150:153], v[198:201], v[24:27]
	v_mfma_f32_16x16x32_bf16 v[12:15], v[128:131], v[206:209], v[12:15]
	v_mfma_f32_16x16x32_bf16 v[8:11], v[150:153], v[206:209], v[8:11]
	v_mfma_f32_16x16x32_bf16 v[60:63], v[132:135], v[186:189], v[60:63]
	v_mfma_f32_16x16x32_bf16 v[56:59], v[162:165], v[186:189], v[56:59]
	v_mfma_f32_16x16x32_bf16 v[44:47], v[132:135], v[194:197], v[44:47]
	v_mfma_f32_16x16x32_bf16 v[40:43], v[162:165], v[194:197], v[40:43]
	v_mfma_f32_16x16x32_bf16 v[28:31], v[132:135], v[202:205], v[28:31]
	v_mfma_f32_16x16x32_bf16 v[24:27], v[162:165], v[202:205], v[24:27]
	v_mfma_f32_16x16x32_bf16 v[12:15], v[132:135], v[214:217], v[12:15]
	v_mfma_f32_16x16x32_bf16 v[8:11], v[162:165], v[214:217], v[8:11]
	s_setprio 0
	s_setprio 1
	v_mfma_f32_16x16x32_bf16 v[52:55], v[166:169], v[182:185], v[52:55]
	v_mfma_f32_16x16x32_bf16 v[48:51], v[174:177], v[182:185], v[48:51]
	v_mfma_f32_16x16x32_bf16 v[36:39], v[166:169], v[190:193], v[36:39]
	v_mfma_f32_16x16x32_bf16 v[32:35], v[174:177], v[190:193], v[32:35]
	v_mfma_f32_16x16x32_bf16 v[20:23], v[166:169], v[198:201], v[20:23]
	v_mfma_f32_16x16x32_bf16 v[16:19], v[174:177], v[198:201], v[16:19]
	v_mfma_f32_16x16x32_bf16 v[4:7], v[166:169], v[206:209], v[4:7]
	v_mfma_f32_16x16x32_bf16 v[0:3], v[174:177], v[206:209], v[0:3]
	v_mfma_f32_16x16x32_bf16 v[52:55], v[170:173], v[186:189], v[52:55]
	v_mfma_f32_16x16x32_bf16 v[48:51], v[178:181], v[186:189], v[48:51]
	v_mfma_f32_16x16x32_bf16 v[36:39], v[170:173], v[194:197], v[36:39]
	v_mfma_f32_16x16x32_bf16 v[32:35], v[178:181], v[194:197], v[32:35]
	v_mfma_f32_16x16x32_bf16 v[20:23], v[170:173], v[202:205], v[20:23]
	v_mfma_f32_16x16x32_bf16 v[16:19], v[178:181], v[202:205], v[16:19]
	v_mfma_f32_16x16x32_bf16 v[4:7], v[170:173], v[214:217], v[4:7]
	v_mfma_f32_16x16x32_bf16 v[0:3], v[178:181], v[214:217], v[0:3]
	s_setprio 0
	s_barrier
	s_add_i32 s65, s65, 2
	s_add_u32 s55, s55, 0x100
	s_addc_u32 s64, s64, 0
	s_cmp_gt_u32 s65, 41
	s_mov_b64 s[24:25], s[26:27]
	s_cbranch_scc0 .LBB0_721
	v_lshl_add_u32 v152, s53, 8, v154
	v_ashrrev_i32_e32 v153, 31, v152
	s_lshl_b32 s16, s45, 8
	v_lshlrev_b64 v[128:129], 11, v[152:153]
	s_ashr_i32 s17, s16, 31
	v_lshl_add_u64 v[128:129], s[50:51], 0, v[128:129]
	v_lshl_add_u64 v[128:129], s[16:17], 1, v[128:129]
	v_lshl_add_u64 v[128:129], v[128:129], 0, s[14:15]
	v_lshl_add_u64 v[150:151], v[128:129], 0, v[144:145]
	s_mov_b32 s16, 0x8000
	v_add_co_u32_e32 v128, vcc, s16, v150
	global_load_dwordx4 v[164:167], v[150:151], off
	global_load_dwordx4 v[168:171], v[150:151], off offset:256
	v_addc_co_u32_e32 v129, vcc, 0, v151, vcc
	global_load_dwordx4 v[132:135], v[128:129], off
	s_nop 0
	global_load_dwordx4 v[128:131], v[128:129], off offset:256
	s_and_b64 vcc, exec, s[12:13]
	s_cbranch_vccz .LBB0_724
	s_barrier

; #define PG8_STAGE(bufoff, gbase, voff) do { _Pragma("unroll") for (int _i = 0; _i < 2; ++_i) \
;     __builtin_amdgcn_global_load_lds((const unsigned*)((const char*)(gbase) + (voff)[_i]), (PG8_LAS unsigned*)(lds + (bufoff) + ldsw + _i * 8192), 16, 0, 0); } while (0)
; #define PG8_LDA(dst, b, h) do { _Pragma("unroll") for (int m = 0; m < 4; ++m) _Pragma("unroll") for (int k = 0; k < 2; ++k) dst[m][k] = *(const PG8_LAS bf16x8*)(lds + PG8_SA(b, h) + aoff + m * 2048 + k * 1024); } while (0)
; #define PG8_LDB(dst, b, h) do { _Pragma("unroll") for (int n = 0; n < 2; ++n) _Pragma("unroll") for (int k = 0; k < 2; ++k) dst[n][k] = *(const PG8_LAS bf16x8*)(lds + PG8_SB(b, h) + boff + n * 2048 + k * 1024); } while (0)
; #define PG8_MMA(ai, bj, At, Bt) do { __builtin_amdgcn_s_setprio(1); _Pragma("unroll") for (int m = 0; m < 4; ++m) _Pragma("unroll") for (int n = 0; n < 2; ++n) _Pragma("unroll") for (int k = 0; k < 2; ++k) \
;     acc[ai][bj][m][n] = __builtin_amdgcn_mfma_f32_16x16x32_bf16(Bt[n][k], At[m][k], acc[ai][bj][m][n], 0, 0, 0); __builtin_amdgcn_s_setprio(0); } while (0)
; #define PG8_WAIT_V(n) asm volatile("s_waitcnt vmcnt(" #n ")" ::: "memory")
; #define PG8_WAIT_L(n) asm volatile("s_waitcnt lgkmcnt(" #n ")" ::: "memory")
; #define PG8_BAR __builtin_amdgcn_s_barrier()
; #define PG8_SCHED __builtin_amdgcn_sched_barrier(0)
; template <class Epi, class Sched>
; DI void gemm_phase(PG8_LAS unsigned char* lds, const Gemm g, const Sched& S, const Epi& E) {
;     ...
;     for (int t = 0; t < nt; t += 2) {
;       const bool last = (t == nt - 2);
;       const char* a1 = cA + (size_t)(t + 1) * kstep;
;       const char* a2 = last ? nA : cA + (size_t)(t + 2) * kstep; const char* b2 = last ? nB : cB + (size_t)(t + 2) * kstep;
;       const char* a3 = a2 + kstep; const char* b3 = b2 + kstep;
;       PG8_LDB(B0, 0, 0); PG8_LDB(B1, 0, 1); PG8_SCHED; PG8_LDA(At, 0, 0); PG8_STAGE(PG8_SA(1, 1), a1 + hstepA, voffA);
;       PG8_WAIT_V(8); PG8_WAIT_L(0); PG8_BAR; PG8_MMA(0, 0, At, B0); PG8_MMA(0, 1, At, B1); PG8_BAR; PG8_SCHED;
;       PG8_LDA(At, 0, 1); PG8_STAGE(PG8_SB(0, 0), b2, voffB); PG8_STAGE(PG8_SB(0, 1), b2 + hstepB, voffB); PG8_STAGE(PG8_SA(0, 0), a2, voffA);
;       PG8_WAIT_V(8); PG8_WAIT_L(0); PG8_BAR; PG8_MMA(1, 0, At, B0); PG8_MMA(1, 1, At, B1); PG8_BAR; PG8_SCHED;
.LBB0_807:
	ds_read_b128 v[144:147], v195
	ds_read_b128 v[148:151], v195 offset:1024
	ds_read_b128 v[152:155], v195 offset:2048
	ds_read_b128 v[156:159], v195 offset:3072
	ds_read_b128 v[160:163], v196
	ds_read_b128 v[164:167], v196 offset:1024
	ds_read_b128 v[168:171], v196 offset:2048
	ds_read_b128 v[172:175], v196 offset:3072
	s_add_u32 s16, s10, 0xfffc0080
	s_addc_u32 s17, s11, -1
	s_cmp_eq_u32 s73, 12
	s_cselect_b32 s45, s1, s17
	s_cselect_b32 s44, s9, s16
	s_cselect_b32 s41, s22, s72
	s_cselect_b32 s40, s29, s31
	s_add_i32 m0, s3, 0xc000
	ds_read_b128 v[176:179], v197
	ds_read_b128 v[180:183], v197 offset:1024
	ds_read_b128 v[184:187], v197 offset:2048
	ds_read_b128 v[188:191], v197 offset:3072
	ds_read_b128 v[202:205], v197 offset:4096
	ds_read_b128 v[206:209], v197 offset:5120
	ds_read_b128 v[214:217], v197 offset:6144
	ds_read_b128 v[218:221], v197 offset:7168
	global_load_lds_dwordx4 v138, s[10:11]
	s_add_i32 m0, s3, 0xe000
	s_nop 0
	global_load_lds_dwordx4 v140, s[10:11]
	s_waitcnt vmcnt(8)
	s_waitcnt lgkmcnt(0)
	s_barrier
	s_setprio 1
	s_waitcnt lgkmcnt(0)
	v_mfma_f32_16x16x32_bf16 v[124:127], v[144:147], v[176:179], v[124:127]
	v_mfma_f32_16x16x32_bf16 v[120:123], v[152:155], v[176:179], v[120:123]
	v_mfma_f32_16x16x32_bf16 v[108:111], v[144:147], v[184:187], v[108:111]
	v_mfma_f32_16x16x32_bf16 v[104:107], v[152:155], v[184:187], v[104:107]
	v_mfma_f32_16x16x32_bf16 v[92:95], v[144:147], v[202:205], v[92:95]
	v_mfma_f32_16x16x32_bf16 v[88:91], v[152:155], v[202:205], v[88:91]
	v_mfma_f32_16x16x32_bf16 v[76:79], v[144:147], v[214:217], v[76:79]
	v_mfma_f32_16x16x32_bf16 v[72:75], v[152:155], v[214:217], v[72:75]
	v_mfma_f32_16x16x32_bf16 v[124:127], v[148:151], v[180:183], v[124:127]
	v_mfma_f32_16x16x32_bf16 v[120:123], v[156:159], v[180:183], v[120:123]
	v_mfma_f32_16x16x32_bf16 v[108:111], v[148:151], v[188:191], v[108:111]
	v_mfma_f32_16x16x32_bf16 v[104:107], v[156:159], v[188:191], v[104:107]
	v_mfma_f32_16x16x32_bf16 v[92:95], v[148:151], v[206:209], v[92:95]
	v_mfma_f32_16x16x32_bf16 v[88:91], v[156:159], v[206:209], v[88:91]
	v_mfma_f32_16x16x32_bf16 v[76:79], v[148:151], v[218:221], v[76:79]
	v_mfma_f32_16x16x32_bf16 v[72:75], v[156:159], v[218:221], v[72:75]
	s_setprio 0
	s_setprio 1
	v_mfma_f32_16x16x32_bf16 v[116:119], v[160:163], v[176:179], v[116:119]
	v_mfma_f32_16x16x32_bf16 v[112:115], v[168:171], v[176:179], v[112:115]
	v_mfma_f32_16x16x32_bf16 v[100:103], v[160:163], v[184:187], v[100:103]
	v_mfma_f32_16x16x32_bf16 v[96:99], v[168:171], v[184:187], v[96:99]
	v_mfma_f32_16x16x32_bf16 v[84:87], v[160:163], v[202:205], v[84:87]
	v_mfma_f32_16x16x32_bf16 v[80:83], v[168:171], v[202:205], v[80:83]
	v_mfma_f32_16x16x32_bf16 v[68:71], v[160:163], v[214:217], v[68:71]
	v_mfma_f32_16x16x32_bf16 v[64:67], v[168:171], v[214:217], v[64:67]
	v_mfma_f32_16x16x32_bf16 v[116:119], v[164:167], v[180:183], v[116:119]
	v_mfma_f32_16x16x32_bf16 v[112:115], v[172:175], v[180:183], v[112:115]
	v_mfma_f32_16x16x32_bf16 v[100:103], v[164:167], v[188:191], v[100:103]
	v_mfma_f32_16x16x32_bf16 v[96:99], v[172:175], v[188:191], v[96:99]
	v_mfma_f32_16x16x32_bf16 v[84:87], v[164:167], v[206:209], v[84:87]
	v_mfma_f32_16x16x32_bf16 v[80:83], v[172:175], v[206:209], v[80:83]
	v_mfma_f32_16x16x32_bf16 v[68:71], v[164:167], v[218:221], v[68:71]
	v_mfma_f32_16x16x32_bf16 v[64:67], v[172:175], v[218:221], v[64:67]
	s_setprio 0
	s_barrier
	s_add_i32 s16, s4, s2
	v_lshl_add_u64 v[192:193], s[40:41], 0, v[130:131]
	s_mov_b32 m0, s16
	ds_read_b128 v[176:179], v197 offset:16384
	ds_read_b128 v[180:183], v197 offset:17408
	ds_read_b128 v[184:187], v197 offset:18432
	ds_read_b128 v[188:191], v197 offset:19456
	ds_read_b128 v[202:205], v197 offset:20480
	ds_read_b128 v[206:209], v197 offset:21504
	ds_read_b128 v[214:217], v197 offset:22528
	ds_read_b128 v[218:221], v197 offset:23552
	global_load_lds_dwordx4 v[192:193], off
	s_add_i32 m0, s16, 0x2000
	s_add_u32 s16, s40, 0x40000
	v_lshl_add_u64 v[210:211], s[40:41], 0, v[134:135]
	s_addc_u32 s17, s41, 0
	s_add_i32 s33, s5, s2
	global_load_lds_dwordx4 v[210:211], off
	s_mov_b32 m0, s33
	v_lshl_add_u64 v[224:225], s[44:45], 0, v[132:133]
	global_load_lds_dwordx4 v130, s[16:17]
	s_add_i32 m0, s33, 0x2000
	s_nop 0
	global_load_lds_dwordx4 v134, s[16:17]
	v_lshl_add_u64 v[222:223], s[44:45], 0, v[128:129]
	s_mov_b32 m0, s3
	s_nop 0
	global_load_lds_dwordx4 v[222:223], off
	s_mov_b32 m0, s27
	s_nop 0
	global_load_lds_dwordx4 v[224:225], off
	s_waitcnt vmcnt(8)
	s_waitcnt lgkmcnt(0)
	s_barrier
; #define PG8_STAGE(bufoff, gbase, voff) do { _Pragma("unroll") for (int _i = 0; _i < 2; ++_i) \
;     __builtin_amdgcn_global_load_lds((const unsigned*)((const char*)(gbase) + (voff)[_i]), (PG8_LAS unsigned*)(lds + (bufoff) + ldsw + _i * 8192), 16, 0, 0); } while (0)
; #define PG8_LDA(dst, b, h) do { _Pragma("unroll") for (int m = 0; m < 4; ++m) _Pragma("unroll") for (int k = 0; k < 2; ++k) dst[m][k] = *(const PG8_LAS bf16x8*)(lds + PG8_SA(b, h) + aoff + m * 2048 + k * 1024); } while (0)
; #define PG8_LDB(dst, b, h) do { _Pragma("unroll") for (int n = 0; n < 2; ++n) _Pragma("unroll") for (int k = 0; k < 2; ++k) dst[n][k] = *(const PG8_LAS bf16x8*)(lds + PG8_SB(b, h) + boff + n * 2048 + k * 1024); } while (0)
; #define PG8_MMA(ai, bj, At, Bt) do { __builtin_amdgcn_s_setprio(1); _Pragma("unroll") for (int m = 0; m < 4; ++m) _Pragma("unroll") for (int n = 0; n < 2; ++n) _Pragma("unroll") for (int k = 0; k < 2; ++k) \
;     acc[ai][bj][m][n] = __builtin_amdgcn_mfma_f32_16x16x32_bf16(Bt[n][k], At[m][k], acc[ai][bj][m][n], 0, 0, 0); __builtin_amdgcn_s_setprio(0); } while (0)
; #define PG8_WAIT_V(n) asm volatile("s_waitcnt vmcnt(" #n ")" ::: "memory")
; #define PG8_WAIT_L(n) asm volatile("s_waitcnt lgkmcnt(" #n ")" ::: "memory")
; #define PG8_BAR __builtin_amdgcn_s_barrier()
; #define PG8_SCHED __builtin_amdgcn_sched_barrier(0)
; template <class Epi, class Sched>
; DI void gemm_phase(PG8_LAS unsigned char* lds, const Gemm g, const Sched& S, const Epi& E) {
;     ...
;       PG8_WAIT_V(8); PG8_WAIT_L(0); PG8_BAR; PG8_MMA(1, 0, At, B0); PG8_MMA(1, 1, At, B1); PG8_BAR; PG8_SCHED;
;       PG8_LDB(B0, 1, 0); PG8_LDB(B1, 1, 1); PG8_SCHED; PG8_LDA(At, 1, 0); PG8_STAGE(PG8_SA(0, 1), a2 + hstepA, voffA);
;       PG8_WAIT_V(8); PG8_WAIT_L(0); PG8_BAR; PG8_MMA(0, 0, At, B0); PG8_MMA(0, 1, At, B1); PG8_BAR; PG8_SCHED;
	s_setprio 1
	s_waitcnt lgkmcnt(0)
	v_mfma_f32_16x16x32_bf16 v[60:63], v[144:147], v[176:179], v[60:63]
	v_mfma_f32_16x16x32_bf16 v[56:59], v[152:155], v[176:179], v[56:59]
	v_mfma_f32_16x16x32_bf16 v[44:47], v[144:147], v[184:187], v[44:47]
	v_mfma_f32_16x16x32_bf16 v[40:43], v[152:155], v[184:187], v[40:43]
	v_mfma_f32_16x16x32_bf16 v[28:31], v[144:147], v[202:205], v[28:31]
	v_mfma_f32_16x16x32_bf16 v[24:27], v[152:155], v[202:205], v[24:27]
	v_mfma_f32_16x16x32_bf16 v[12:15], v[144:147], v[214:217], v[12:15]
	v_mfma_f32_16x16x32_bf16 v[8:11], v[152:155], v[214:217], v[8:11]
	v_mfma_f32_16x16x32_bf16 v[60:63], v[148:151], v[180:183], v[60:63]
	v_mfma_f32_16x16x32_bf16 v[56:59], v[156:159], v[180:183], v[56:59]
	v_mfma_f32_16x16x32_bf16 v[44:47], v[148:151], v[188:191], v[44:47]
	v_mfma_f32_16x16x32_bf16 v[40:43], v[156:159], v[188:191], v[40:43]
	v_mfma_f32_16x16x32_bf16 v[28:31], v[148:151], v[206:209], v[28:31]
	v_mfma_f32_16x16x32_bf16 v[24:27], v[156:159], v[206:209], v[24:27]
	v_mfma_f32_16x16x32_bf16 v[12:15], v[148:151], v[218:221], v[12:15]
	v_mfma_f32_16x16x32_bf16 v[8:11], v[156:159], v[218:221], v[8:11]
	s_setprio 0
	s_setprio 1
	v_mfma_f32_16x16x32_bf16 v[52:55], v[160:163], v[176:179], v[52:55]
	v_mfma_f32_16x16x32_bf16 v[48:51], v[168:171], v[176:179], v[48:51]
	v_mfma_f32_16x16x32_bf16 v[36:39], v[160:163], v[184:187], v[36:39]
	v_mfma_f32_16x16x32_bf16 v[32:35], v[168:171], v[184:187], v[32:35]
	v_mfma_f32_16x16x32_bf16 v[20:23], v[160:163], v[202:205], v[20:23]
	v_mfma_f32_16x16x32_bf16 v[16:19], v[168:171], v[202:205], v[16:19]
	v_mfma_f32_16x16x32_bf16 v[4:7], v[160:163], v[214:217], v[4:7]
	v_mfma_f32_16x16x32_bf16 v[0:3], v[168:171], v[214:217], v[0:3]
	v_mfma_f32_16x16x32_bf16 v[52:55], v[164:167], v[180:183], v[52:55]
	v_mfma_f32_16x16x32_bf16 v[48:51], v[172:175], v[180:183], v[48:51]
	v_mfma_f32_16x16x32_bf16 v[36:39], v[164:167], v[188:191], v[36:39]
	v_mfma_f32_16x16x32_bf16 v[32:35], v[172:175], v[188:191], v[32:35]
	v_mfma_f32_16x16x32_bf16 v[20:23], v[164:167], v[206:209], v[20:23]
	v_mfma_f32_16x16x32_bf16 v[16:19], v[172:175], v[206:209], v[16:19]
	v_mfma_f32_16x16x32_bf16 v[4:7], v[164:167], v[218:221], v[4:7]
	v_mfma_f32_16x16x32_bf16 v[0:3], v[172:175], v[218:221], v[0:3]
	s_setprio 0
	s_barrier
	ds_read_b128 v[144:147], v199
	ds_read_b128 v[148:151], v199 offset:1024
	ds_read_b128 v[152:155], v199 offset:2048
	ds_read_b128 v[156:159], v199 offset:3072
	ds_read_b128 v[160:163], v200
	ds_read_b128 v[164:167], v200 offset:1024
	ds_read_b128 v[168:171], v200 offset:2048
	ds_read_b128 v[172:175], v200 offset:3072
	s_add_u32 s16, s44, 0x40000
	s_addc_u32 s17, s45, 0
	s_mov_b32 m0, s53
	ds_read_b128 v[176:179], v197 offset:32768
	ds_read_b128 v[180:183], v197 offset:33792
	ds_read_b128 v[184:187], v197 offset:34816
	ds_read_b128 v[188:191], v197 offset:35840
	ds_read_b128 v[202:205], v197 offset:36864
	ds_read_b128 v[206:209], v197 offset:37888
	ds_read_b128 v[214:217], v197 offset:38912
	ds_read_b128 v[218:221], v197 offset:39936
	global_load_lds_dwordx4 v128, s[16:17]
	s_mov_b32 m0, s55
	s_nop 0
	global_load_lds_dwordx4 v132, s[16:17]
	s_waitcnt vmcnt(8)
	s_waitcnt lgkmcnt(0)
	s_barrier
	s_setprio 1
	s_waitcnt lgkmcnt(0)
	v_mfma_f32_16x16x32_bf16 v[124:127], v[144:147], v[176:179], v[124:127]
	v_mfma_f32_16x16x32_bf16 v[120:123], v[152:155], v[176:179], v[120:123]
	v_mfma_f32_16x16x32_bf16 v[108:111], v[144:147], v[184:187], v[108:111]
	v_mfma_f32_16x16x32_bf16 v[104:107], v[152:155], v[184:187], v[104:107]
	v_mfma_f32_16x16x32_bf16 v[92:95], v[144:147], v[202:205], v[92:95]
	v_mfma_f32_16x16x32_bf16 v[88:91], v[152:155], v[202:205], v[88:91]
	v_mfma_f32_16x16x32_bf16 v[76:79], v[144:147], v[214:217], v[76:79]
	v_mfma_f32_16x16x32_bf16 v[72:75], v[152:155], v[214:217], v[72:75]
	v_mfma_f32_16x16x32_bf16 v[124:127], v[148:151], v[180:183], v[124:127]
	v_mfma_f32_16x16x32_bf16 v[120:123], v[156:159], v[180:183], v[120:123]
	v_mfma_f32_16x16x32_bf16 v[108:111], v[148:151], v[188:191], v[108:111]
	v_mfma_f32_16x16x32_bf16 v[104:107], v[156:159], v[188:191], v[104:107]
	v_mfma_f32_16x16x32_bf16 v[92:95], v[148:151], v[206:209], v[92:95]
	v_mfma_f32_16x16x32_bf16 v[88:91], v[156:159], v[206:209], v[88:91]
	v_mfma_f32_16x16x32_bf16 v[76:79], v[148:151], v[218:221], v[76:79]
	v_mfma_f32_16x16x32_bf16 v[72:75], v[156:159], v[218:221], v[72:75]
	s_setprio 0
	s_setprio 1
	v_mfma_f32_16x16x32_bf16 v[116:119], v[160:163], v[176:179], v[116:119]
	v_mfma_f32_16x16x32_bf16 v[112:115], v[168:171], v[176:179], v[112:115]
	v_mfma_f32_16x16x32_bf16 v[100:103], v[160:163], v[184:187], v[100:103]
	v_mfma_f32_16x16x32_bf16 v[96:99], v[168:171], v[184:187], v[96:99]
	v_mfma_f32_16x16x32_bf16 v[84:87], v[160:163], v[202:205], v[84:87]
	v_mfma_f32_16x16x32_bf16 v[80:83], v[168:171], v[202:205], v[80:83]
	v_mfma_f32_16x16x32_bf16 v[68:71], v[160:163], v[214:217], v[68:71]
	v_mfma_f32_16x16x32_bf16 v[64:67], v[168:171], v[214:217], v[64:67]
	v_mfma_f32_16x16x32_bf16 v[116:119], v[164:167], v[180:183], v[116:119]
	v_mfma_f32_16x16x32_bf16 v[112:115], v[172:175], v[180:183], v[112:115]
	v_mfma_f32_16x16x32_bf16 v[100:103], v[164:167], v[188:191], v[100:103]
	v_mfma_f32_16x16x32_bf16 v[96:99], v[172:175], v[188:191], v[96:99]
	v_mfma_f32_16x16x32_bf16 v[84:87], v[164:167], v[206:209], v[84:87]
	v_mfma_f32_16x16x32_bf16 v[80:83], v[172:175], v[206:209], v[80:83]
	v_mfma_f32_16x16x32_bf16 v[68:71], v[164:167], v[218:221], v[68:71]
	v_mfma_f32_16x16x32_bf16 v[64:67], v[172:175], v[218:221], v[64:67]
	s_setprio 0
	s_barrier
; #define PG8_STAGE(bufoff, gbase, voff) do { _Pragma("unroll") for (int _i = 0; _i < 2; ++_i) \
;     __builtin_amdgcn_global_load_lds((const unsigned*)((const char*)(gbase) + (voff)[_i]), (PG8_LAS unsigned*)(lds + (bufoff) + ldsw + _i * 8192), 16, 0, 0); } while (0)
; #define PG8_LDA(dst, b, h) do { _Pragma("unroll") for (int m = 0; m < 4; ++m) _Pragma("unroll") for (int k = 0; k < 2; ++k) dst[m][k] = *(const PG8_LAS bf16x8*)(lds + PG8_SA(b, h) + aoff + m * 2048 + k * 1024); } while (0)
; #define PG8_MMA(ai, bj, At, Bt) do { __builtin_amdgcn_s_setprio(1); _Pragma("unroll") for (int m = 0; m < 4; ++m) _Pragma("unroll") for (int n = 0; n < 2; ++n) _Pragma("unroll") for (int k = 0; k < 2; ++k) \
;     acc[ai][bj][m][n] = __builtin_amdgcn_mfma_f32_16x16x32_bf16(Bt[n][k], At[m][k], acc[ai][bj][m][n], 0, 0, 0); __builtin_amdgcn_s_setprio(0); } while (0)
; #define PG8_WAIT_V(n) asm volatile("s_waitcnt vmcnt(" #n ")" ::: "memory")
; #define PG8_WAIT_L(n) asm volatile("s_waitcnt lgkmcnt(" #n ")" ::: "memory")
; #define PG8_BAR __builtin_amdgcn_s_barrier()
; #define PG8_SCHED __builtin_amdgcn_sched_barrier(0)
; DI void rows_rstd(float (&rs)[2][4], const float* ps, const Unit& u, int wr, int fr, int fq, int p_lo, int p_hi, float inv_dim) {
;   f32x4 pv[2][4];
; #pragma unroll
;   for (int ai = 0; ai < 2; ++ai)
; #pragma unroll
;     for (int m = 0; m < 4; ++m) pv[ai][m] = *(const f32x4*)(ps + (size_t)(u.pm * BM + ai * HALF + wr * 64 + m * 16 + fr) * 16 + 4 * fq);
; template <class Epi, class Sched>
; DI void gemm_phase(PG8_LAS unsigned char* lds, const Gemm g, const Sched& S, const Epi& E) {
;     ...
;       PG8_LDA(At, 1, 1); PG8_STAGE(PG8_SB(1, 0), b3, voffB); PG8_STAGE(PG8_SB(1, 1), b3 + hstepB, voffB); PG8_STAGE(PG8_SA(1, 0), a3, voffA);
;       PG8_WAIT_V(8); PG8_WAIT_L(0); PG8_BAR; PG8_MMA(1, 0, At, B0); PG8_MMA(1, 1, At, B1); PG8_BAR; PG8_SCHED;
;     }
	s_add_i32 s16, s69, s2
	v_lshl_add_u64 v[192:193], v[192:193], 0, s[14:15]
	s_mov_b32 m0, s16
	ds_read_b128 v[176:179], v197 offset:49152
	ds_read_b128 v[180:183], v197 offset:50176
	ds_read_b128 v[184:187], v197 offset:51200
	ds_read_b128 v[188:191], v197 offset:52224
	ds_read_b128 v[202:205], v197 offset:53248
	ds_read_b128 v[206:209], v197 offset:54272
	ds_read_b128 v[214:217], v197 offset:55296
	ds_read_b128 v[218:221], v197 offset:56320
	global_load_lds_dwordx4 v[192:193], off
	s_add_i32 m0, s16, 0x2000
	s_add_u32 s16, s40, 0x40080
	v_lshl_add_u64 v[192:193], v[210:211], 0, s[14:15]
	s_addc_u32 s17, s41, 0
	s_add_i32 s33, s70, s2
	global_load_lds_dwordx4 v[192:193], off
	s_mov_b32 m0, s33
	s_nop 0
	global_load_lds_dwordx4 v130, s[16:17]
	s_add_i32 m0, s33, 0x2000
	s_nop 0
	global_load_lds_dwordx4 v134, s[16:17]
	v_lshl_add_u64 v[192:193], v[222:223], 0, s[14:15]
	s_mov_b32 m0, s65
	s_nop 0
	global_load_lds_dwordx4 v[192:193], off
	v_lshl_add_u64 v[192:193], v[224:225], 0, s[14:15]
	s_mov_b32 m0, s66
	s_nop 0
	global_load_lds_dwordx4 v[192:193], off
	s_waitcnt vmcnt(8)
	s_waitcnt lgkmcnt(0)
	s_barrier
	s_setprio 1
	s_waitcnt lgkmcnt(0)
	v_mfma_f32_16x16x32_bf16 v[60:63], v[144:147], v[176:179], v[60:63]
	v_mfma_f32_16x16x32_bf16 v[56:59], v[152:155], v[176:179], v[56:59]
	v_mfma_f32_16x16x32_bf16 v[44:47], v[144:147], v[184:187], v[44:47]
	v_mfma_f32_16x16x32_bf16 v[40:43], v[152:155], v[184:187], v[40:43]
	v_mfma_f32_16x16x32_bf16 v[28:31], v[144:147], v[202:205], v[28:31]
	v_mfma_f32_16x16x32_bf16 v[24:27], v[152:155], v[202:205], v[24:27]
	v_mfma_f32_16x16x32_bf16 v[12:15], v[144:147], v[214:217], v[12:15]
	v_mfma_f32_16x16x32_bf16 v[8:11], v[152:155], v[214:217], v[8:11]
	v_mfma_f32_16x16x32_bf16 v[60:63], v[148:151], v[180:183], v[60:63]
	v_mfma_f32_16x16x32_bf16 v[56:59], v[156:159], v[180:183], v[56:59]
	v_mfma_f32_16x16x32_bf16 v[44:47], v[148:151], v[188:191], v[44:47]
	v_mfma_f32_16x16x32_bf16 v[40:43], v[156:159], v[188:191], v[40:43]
	v_mfma_f32_16x16x32_bf16 v[28:31], v[148:151], v[206:209], v[28:31]
	v_mfma_f32_16x16x32_bf16 v[24:27], v[156:159], v[206:209], v[24:27]
	v_mfma_f32_16x16x32_bf16 v[12:15], v[148:151], v[218:221], v[12:15]
	v_mfma_f32_16x16x32_bf16 v[8:11], v[156:159], v[218:221], v[8:11]
	s_setprio 0
	s_setprio 1
	v_mfma_f32_16x16x32_bf16 v[52:55], v[160:163], v[176:179], v[52:55]
	v_mfma_f32_16x16x32_bf16 v[48:51], v[168:171], v[176:179], v[48:51]
	v_mfma_f32_16x16x32_bf16 v[36:39], v[160:163], v[184:187], v[36:39]
	v_mfma_f32_16x16x32_bf16 v[32:35], v[168:171], v[184:187], v[32:35]
	v_mfma_f32_16x16x32_bf16 v[20:23], v[160:163], v[202:205], v[20:23]
	v_mfma_f32_16x16x32_bf16 v[16:19], v[168:171], v[202:205], v[16:19]
	v_mfma_f32_16x16x32_bf16 v[4:7], v[160:163], v[214:217], v[4:7]
	v_mfma_f32_16x16x32_bf16 v[0:3], v[168:171], v[214:217], v[0:3]
	v_mfma_f32_16x16x32_bf16 v[52:55], v[164:167], v[180:183], v[52:55]
	v_mfma_f32_16x16x32_bf16 v[48:51], v[172:175], v[180:183], v[48:51]
	v_mfma_f32_16x16x32_bf16 v[36:39], v[164:167], v[188:191], v[36:39]
	v_mfma_f32_16x16x32_bf16 v[32:35], v[172:175], v[188:191], v[32:35]
	v_mfma_f32_16x16x32_bf16 v[20:23], v[164:167], v[206:209], v[20:23]
	v_mfma_f32_16x16x32_bf16 v[16:19], v[172:175], v[206:209], v[16:19]
	v_mfma_f32_16x16x32_bf16 v[4:7], v[164:167], v[218:221], v[4:7]
	v_mfma_f32_16x16x32_bf16 v[0:3], v[172:175], v[218:221], v[0:3]
	s_setprio 0
	s_barrier
	s_add_i32 s73, s73, 2
	s_add_u32 s10, s10, 0x100
	s_addc_u32 s11, s11, 0
	s_add_u32 s31, s31, 0x100
	s_addc_u32 s72, s72, 0
	s_cmp_gt_u32 s73, 13
	s_cbranch_scc0 .LBB0_807
	v_lshl_add_u32 v184, s8, 8, v143
	v_or_b32_e32 v180, 16, v184
	v_ashrrev_i32_e32 v181, 31, v180
	v_or_b32_e32 v172, 32, v184
	v_lshlrev_b64 v[178:179], 6, v[180:181]
	v_ashrrev_i32_e32 v173, 31, v172
	v_ashrrev_i32_e32 v185, 31, v184
	v_lshl_add_u64 v[144:145], v[136:137], 0, v[178:179]
	v_lshlrev_b64 v[170:171], 6, v[172:173]
	v_lshlrev_b64 v[182:183], 6, v[184:185]
	v_lshl_add_u64 v[146:147], v[136:137], 0, v[170:171]
	global_load_dwordx4 v[162:165], v[144:145], off
	global_load_dwordx4 v[174:177], v[146:147], off
	v_lshl_add_u64 v[144:145], v[136:137], 0, v[182:183]
	global_load_dwordx4 v[186:189], v[144:145], off
	v_or_b32_e32 v168, 48, v184
	v_ashrrev_i32_e32 v169, 31, v168
	v_add_u32_e32 v160, 0x80, v184
	v_add_u32_e32 v156, 0x90, v184
	v_lshlrev_b64 v[166:167], 6, v[168:169]
	v_ashrrev_i32_e32 v161, 31, v160
	v_ashrrev_i32_e32 v157, 31, v156
	v_lshl_add_u64 v[144:145], v[136:137], 0, v[166:167]
	v_lshlrev_b64 v[158:159], 6, v[160:161]
	v_lshlrev_b64 v[154:155], 6, v[156:157]
	v_lshl_add_u64 v[146:147], v[136:137], 0, v[158:159]
	global_load_dwordx4 v[190:193], v[144:145], off
	global_load_dwordx4 v[202:205], v[146:147], off
	v_lshl_add_u64 v[144:145], v[136:137], 0, v[154:155]
	global_load_dwordx4 v[206:209], v[144:145], off
	v_add_u32_e32 v150, 0xa0, v184
	v_ashrrev_i32_e32 v151, 31, v150
	v_lshlrev_b64 v[148:149], 6, v[150:151]
	v_add_u32_e32 v146, 0xb0, v184
	v_lshl_add_u64 v[144:145], v[136:137], 0, v[148:149]
	v_ashrrev_i32_e32 v147, 31, v146
	global_load_dwordx4 v[214:217], v[144:145], off
	v_lshlrev_b64 v[144:145], 6, v[146:147]
	v_lshl_add_u64 v[152:153], v[136:137], 0, v[144:145]
	global_load_dwordx4 v[218:221], v[152:153], off
	s_and_b64 vcc, exec, s[20:21]
	s_cbranch_vccz .LBB0_810
	s_barrier

; #define PG8_STAGE(bufoff, gbase, voff) do { _Pragma("unroll") for (int _i = 0; _i < 2; ++_i) \
;     __builtin_amdgcn_global_load_lds((const unsigned*)((const char*)(gbase) + (voff)[_i]), (PG8_LAS unsigned*)(lds + (bufoff) + ldsw + _i * 8192), 16, 0, 0); } while (0)
; #define PG8_LDA(dst, b, h) do { _Pragma("unroll") for (int m = 0; m < 4; ++m) _Pragma("unroll") for (int k = 0; k < 2; ++k) dst[m][k] = *(const PG8_LAS bf16x8*)(lds + PG8_SA(b, h) + aoff + m * 2048 + k * 1024); } while (0)
; #define PG8_LDB(dst, b, h) do { _Pragma("unroll") for (int n = 0; n < 2; ++n) _Pragma("unroll") for (int k = 0; k < 2; ++k) dst[n][k] = *(const PG8_LAS bf16x8*)(lds + PG8_SB(b, h) + boff + n * 2048 + k * 1024); } while (0)
; #define PG8_MMA(ai, bj, At, Bt) do { __builtin_amdgcn_s_setprio(1); _Pragma("unroll") for (int m = 0; m < 4; ++m) _Pragma("unroll") for (int n = 0; n < 2; ++n) _Pragma("unroll") for (int k = 0; k < 2; ++k) \
;     acc[ai][bj][m][n] = __builtin_amdgcn_mfma_f32_16x16x32_bf16(Bt[n][k], At[m][k], acc[ai][bj][m][n], 0, 0, 0); __builtin_amdgcn_s_setprio(0); } while (0)
; #define PG8_WAIT_V(n) asm volatile("s_waitcnt vmcnt(" #n ")" ::: "memory")
; #define PG8_BAR __builtin_amdgcn_s_barrier()
; template <class Epi, class Sched>
; DI void gemm_phase(PG8_LAS unsigned char* lds, const Gemm g, const Sched& S, const Epi& E) {
;     ...
;     for (int t = 0; t < nt; t += 2) {
;       const bool last = (t == nt - 2);
;       const char* a1 = cA + (size_t)(t + 1) * kstep;
;       const char* a2 = last ? nA : cA + (size_t)(t + 2) * kstep; const char* b2 = last ? nB : cB + (size_t)(t + 2) * kstep;
;       const char* a3 = a2 + kstep; const char* b3 = b2 + kstep;
;       PG8_LDB(B0, 0, 0); PG8_LDB(B1, 0, 1); PG8_SCHED; PG8_LDA(At, 0, 0); PG8_STAGE(PG8_SA(1, 1), a1 + hstepA, voffA);
;       PG8_WAIT_V(8); PG8_WAIT_L(0); PG8_BAR; PG8_MMA(0, 0, At, B0); PG8_MMA(0, 1, At, B1); PG8_BAR; PG8_SCHED;
;       PG8_LDA(At, 0, 1); PG8_STAGE(PG8_SB(0, 0), b2, voffB); PG8_STAGE(PG8_SB(0, 1), b2 + hstepB, voffB); PG8_STAGE(PG8_SA(0, 0), a2, voffA);
;       PG8_WAIT_V(8); PG8_WAIT_L(0); PG8_BAR; PG8_MMA(1, 0, At, B0); PG8_MMA(1, 1, At, B1); PG8_BAR; PG8_SCHED;
;       PG8_LDB(B0, 1, 0); PG8_LDB(B1, 1, 1); PG8_SCHED; PG8_LDA(At, 1, 0); PG8_STAGE(PG8_SA(0, 1), a2 + hstepA, voffA);
;       PG8_WAIT_V(8); PG8_WAIT_L(0); PG8_BAR; PG8_MMA(0, 0, At, B0); PG8_MMA(0, 1, At, B1); PG8_BAR; PG8_SCHED;
.LBB0_930:
	ds_read_b128 v[128:131], v191
	ds_read_b128 v[132:135], v191 offset:1024
	ds_read_b128 v[136:139], v191 offset:2048
	ds_read_b128 v[140:143], v191 offset:3072
	ds_read_b128 v[144:147], v192
	ds_read_b128 v[148:151], v192 offset:1024
	ds_read_b128 v[152:155], v192 offset:2048
	ds_read_b128 v[172:175], v192 offset:3072
	s_add_u32 s12, s0, 0x100
	s_addc_u32 s13, s1, 0
	s_cmp_eq_u32 s74, 8
	s_cselect_b32 s39, s35, s13
	s_cselect_b32 s38, s34, s12
	s_cselect_b32 s15, s37, s73
	s_cselect_b32 s14, s36, s72
	s_mov_b32 m0, s65
	ds_read_b128 v[176:179], v193
	ds_read_b128 v[180:183], v193 offset:1024
	ds_read_b128 v[184:187], v193 offset:2048
	ds_read_b128 v[198:201], v193 offset:3072
	ds_read_b128 v[202:205], v193 offset:4096
	ds_read_b128 v[206:209], v193 offset:5120
	ds_read_b128 v[214:217], v193 offset:6144
	ds_read_b128 v[218:221], v193 offset:7168
	global_load_lds_dwordx4 v166, s[0:1]
	s_add_i32 m0, s3, 0xe000
	s_nop 0
	global_load_lds_dwordx4 v168, s[0:1]
	s_waitcnt vmcnt(8)
	s_waitcnt lgkmcnt(0)
	s_barrier
	s_setprio 1
	s_waitcnt lgkmcnt(0)
	v_mfma_f32_16x16x32_bf16 v[120:123], v[128:131], v[176:179], v[120:123]
	v_mfma_f32_16x16x32_bf16 v[124:127], v[136:139], v[176:179], v[124:127]
	v_mfma_f32_16x16x32_bf16 v[104:107], v[128:131], v[184:187], v[104:107]
	v_mfma_f32_16x16x32_bf16 v[108:111], v[136:139], v[184:187], v[108:111]
	v_mfma_f32_16x16x32_bf16 v[88:91], v[128:131], v[202:205], v[88:91]
	v_mfma_f32_16x16x32_bf16 v[92:95], v[136:139], v[202:205], v[92:95]
	v_mfma_f32_16x16x32_bf16 v[72:75], v[128:131], v[214:217], v[72:75]
	v_mfma_f32_16x16x32_bf16 v[76:79], v[136:139], v[214:217], v[76:79]
	v_mfma_f32_16x16x32_bf16 v[120:123], v[132:135], v[180:183], v[120:123]
	v_mfma_f32_16x16x32_bf16 v[124:127], v[140:143], v[180:183], v[124:127]
	v_mfma_f32_16x16x32_bf16 v[104:107], v[132:135], v[198:201], v[104:107]
	v_mfma_f32_16x16x32_bf16 v[108:111], v[140:143], v[198:201], v[108:111]
	v_mfma_f32_16x16x32_bf16 v[88:91], v[132:135], v[206:209], v[88:91]
	v_mfma_f32_16x16x32_bf16 v[92:95], v[140:143], v[206:209], v[92:95]
	v_mfma_f32_16x16x32_bf16 v[72:75], v[132:135], v[218:221], v[72:75]
	v_mfma_f32_16x16x32_bf16 v[76:79], v[140:143], v[218:221], v[76:79]
	s_setprio 0
	s_setprio 1
	v_mfma_f32_16x16x32_bf16 v[112:115], v[144:147], v[176:179], v[112:115]
	v_mfma_f32_16x16x32_bf16 v[116:119], v[152:155], v[176:179], v[116:119]
	v_mfma_f32_16x16x32_bf16 v[96:99], v[144:147], v[184:187], v[96:99]
	v_mfma_f32_16x16x32_bf16 v[100:103], v[152:155], v[184:187], v[100:103]
	v_mfma_f32_16x16x32_bf16 v[80:83], v[144:147], v[202:205], v[80:83]
	v_mfma_f32_16x16x32_bf16 v[84:87], v[152:155], v[202:205], v[84:87]
	v_mfma_f32_16x16x32_bf16 v[64:67], v[144:147], v[214:217], v[64:67]
	v_mfma_f32_16x16x32_bf16 v[68:71], v[152:155], v[214:217], v[68:71]
	v_mfma_f32_16x16x32_bf16 v[112:115], v[148:151], v[180:183], v[112:115]
	v_mfma_f32_16x16x32_bf16 v[116:119], v[172:175], v[180:183], v[116:119]
	v_mfma_f32_16x16x32_bf16 v[96:99], v[148:151], v[198:201], v[96:99]
	v_mfma_f32_16x16x32_bf16 v[100:103], v[172:175], v[198:201], v[100:103]
	v_mfma_f32_16x16x32_bf16 v[80:83], v[148:151], v[206:209], v[80:83]
	v_mfma_f32_16x16x32_bf16 v[84:87], v[172:175], v[206:209], v[84:87]
	v_mfma_f32_16x16x32_bf16 v[64:67], v[148:151], v[218:221], v[64:67]
	v_mfma_f32_16x16x32_bf16 v[68:71], v[172:175], v[218:221], v[68:71]
	s_setprio 0
	s_barrier
	s_add_i32 s0, s44, s2
	v_lshl_add_u64 v[188:189], s[14:15], 0, v[158:159]
	s_mov_b32 m0, s0
	ds_read_b128 v[176:179], v193 offset:16384
	ds_read_b128 v[180:183], v193 offset:17408
	ds_read_b128 v[184:187], v193 offset:18432
	ds_read_b128 v[198:201], v193 offset:19456
	ds_read_b128 v[202:205], v193 offset:20480
	ds_read_b128 v[206:209], v193 offset:21504
	ds_read_b128 v[214:217], v193 offset:22528
	ds_read_b128 v[218:221], v193 offset:23552
	global_load_lds_dwordx4 v[188:189], off
	s_add_i32 m0, s0, 0x2000
	s_add_u32 s0, s14, 0x30000
	v_lshl_add_u64 v[210:211], s[14:15], 0, v[162:163]
	s_addc_u32 s1, s15, 0
	s_add_i32 s16, s45, s2
	global_load_lds_dwordx4 v[210:211], off
	s_mov_b32 m0, s16
	v_lshl_add_u64 v[224:225], s[38:39], 0, v[160:161]
	global_load_lds_dwordx4 v158, s[0:1]
	s_add_i32 m0, s16, 0x2000
	s_nop 0
	global_load_lds_dwordx4 v162, s[0:1]
	v_lshl_add_u64 v[222:223], s[38:39], 0, v[156:157]
	s_mov_b32 m0, s3
	s_nop 0
	global_load_lds_dwordx4 v[222:223], off
	s_mov_b32 m0, s4
	s_nop 0
	global_load_lds_dwordx4 v[224:225], off
	s_waitcnt vmcnt(8)
	s_waitcnt lgkmcnt(0)
	s_barrier
	s_setprio 1
	s_waitcnt lgkmcnt(0)
	v_mfma_f32_16x16x32_bf16 v[56:59], v[128:131], v[176:179], v[56:59]
	v_mfma_f32_16x16x32_bf16 v[60:63], v[136:139], v[176:179], v[60:63]
	v_mfma_f32_16x16x32_bf16 v[40:43], v[128:131], v[184:187], v[40:43]
	v_mfma_f32_16x16x32_bf16 v[44:47], v[136:139], v[184:187], v[44:47]
	v_mfma_f32_16x16x32_bf16 v[24:27], v[128:131], v[202:205], v[24:27]
	v_mfma_f32_16x16x32_bf16 v[28:31], v[136:139], v[202:205], v[28:31]
	v_mfma_f32_16x16x32_bf16 v[8:11], v[128:131], v[214:217], v[8:11]
	v_mfma_f32_16x16x32_bf16 v[12:15], v[136:139], v[214:217], v[12:15]
	v_mfma_f32_16x16x32_bf16 v[56:59], v[132:135], v[180:183], v[56:59]
	v_mfma_f32_16x16x32_bf16 v[60:63], v[140:143], v[180:183], v[60:63]
	v_mfma_f32_16x16x32_bf16 v[40:43], v[132:135], v[198:201], v[40:43]
	v_mfma_f32_16x16x32_bf16 v[44:47], v[140:143], v[198:201], v[44:47]
	v_mfma_f32_16x16x32_bf16 v[24:27], v[132:135], v[206:209], v[24:27]
	v_mfma_f32_16x16x32_bf16 v[28:31], v[140:143], v[206:209], v[28:31]
	v_mfma_f32_16x16x32_bf16 v[8:11], v[132:135], v[218:221], v[8:11]
	v_mfma_f32_16x16x32_bf16 v[12:15], v[140:143], v[218:221], v[12:15]
	s_setprio 0
	s_setprio 1
	v_mfma_f32_16x16x32_bf16 v[48:51], v[144:147], v[176:179], v[48:51]
	v_mfma_f32_16x16x32_bf16 v[52:55], v[152:155], v[176:179], v[52:55]
	v_mfma_f32_16x16x32_bf16 v[32:35], v[144:147], v[184:187], v[32:35]
	v_mfma_f32_16x16x32_bf16 v[36:39], v[152:155], v[184:187], v[36:39]
	v_mfma_f32_16x16x32_bf16 v[16:19], v[144:147], v[202:205], v[16:19]
	v_mfma_f32_16x16x32_bf16 v[20:23], v[152:155], v[202:205], v[20:23]
	v_mfma_f32_16x16x32_bf16 v[4:7], v[144:147], v[214:217], v[4:7]
	v_mfma_f32_16x16x32_bf16 v[0:3], v[152:155], v[214:217], v[0:3]
	v_mfma_f32_16x16x32_bf16 v[48:51], v[148:151], v[180:183], v[48:51]
	v_mfma_f32_16x16x32_bf16 v[52:55], v[172:175], v[180:183], v[52:55]
	v_mfma_f32_16x16x32_bf16 v[32:35], v[148:151], v[198:201], v[32:35]
	v_mfma_f32_16x16x32_bf16 v[36:39], v[172:175], v[198:201], v[36:39]
	v_mfma_f32_16x16x32_bf16 v[16:19], v[148:151], v[206:209], v[16:19]
	v_mfma_f32_16x16x32_bf16 v[20:23], v[172:175], v[206:209], v[20:23]
	v_mfma_f32_16x16x32_bf16 v[4:7], v[148:151], v[218:221], v[4:7]
	v_mfma_f32_16x16x32_bf16 v[0:3], v[172:175], v[218:221], v[0:3]
	s_setprio 0
	s_barrier
; #define PG8_STAGE(bufoff, gbase, voff) do { _Pragma("unroll") for (int _i = 0; _i < 2; ++_i) \
;     __builtin_amdgcn_global_load_lds((const unsigned*)((const char*)(gbase) + (voff)[_i]), (PG8_LAS unsigned*)(lds + (bufoff) + ldsw + _i * 8192), 16, 0, 0); } while (0)
; #define PG8_LDA(dst, b, h) do { _Pragma("unroll") for (int m = 0; m < 4; ++m) _Pragma("unroll") for (int k = 0; k < 2; ++k) dst[m][k] = *(const PG8_LAS bf16x8*)(lds + PG8_SA(b, h) + aoff + m * 2048 + k * 1024); } while (0)
; #define PG8_LDB(dst, b, h) do { _Pragma("unroll") for (int n = 0; n < 2; ++n) _Pragma("unroll") for (int k = 0; k < 2; ++k) dst[n][k] = *(const PG8_LAS bf16x8*)(lds + PG8_SB(b, h) + boff + n * 2048 + k * 1024); } while (0)
; #define PG8_MMA(ai, bj, At, Bt) do { __builtin_amdgcn_s_setprio(1); _Pragma("unroll") for (int m = 0; m < 4; ++m) _Pragma("unroll") for (int n = 0; n < 2; ++n) _Pragma("unroll") for (int k = 0; k < 2; ++k) \
;     acc[ai][bj][m][n] = __builtin_amdgcn_mfma_f32_16x16x32_bf16(Bt[n][k], At[m][k], acc[ai][bj][m][n], 0, 0, 0); __builtin_amdgcn_s_setprio(0); } while (0)
; #define PG8_WAIT_V(n) asm volatile("s_waitcnt vmcnt(" #n ")" ::: "memory")
; #define PG8_WAIT_L(n) asm volatile("s_waitcnt lgkmcnt(" #n ")" ::: "memory")
; #define PG8_BAR __builtin_amdgcn_s_barrier()
; #define PG8_SCHED __builtin_amdgcn_sched_barrier(0)
; template <class Epi, class Sched>
; DI void gemm_phase(PG8_LAS unsigned char* lds, const Gemm g, const Sched& S, const Epi& E) {
;     ...
;       PG8_LDB(B0, 1, 0); PG8_LDB(B1, 1, 1); PG8_SCHED; PG8_LDA(At, 1, 0); PG8_STAGE(PG8_SA(0, 1), a2 + hstepA, voffA);
;       PG8_WAIT_V(8); PG8_WAIT_L(0); PG8_BAR; PG8_MMA(0, 0, At, B0); PG8_MMA(0, 1, At, B1); PG8_BAR; PG8_SCHED;
;       PG8_LDA(At, 1, 1); PG8_STAGE(PG8_SB(1, 0), b3, voffB); PG8_STAGE(PG8_SB(1, 1), b3 + hstepB, voffB); PG8_STAGE(PG8_SA(1, 0), a3, voffA);
;       PG8_WAIT_V(8); PG8_WAIT_L(0); PG8_BAR; PG8_MMA(1, 0, At, B0); PG8_MMA(1, 1, At, B1); PG8_BAR; PG8_SCHED;
;     }
;     if (wr == 0) PG8_BAR;
;     E(acc, cur, wr, wc, fr, fq);
;     if (!has_next) break;
	ds_read_b128 v[128:131], v195
	ds_read_b128 v[132:135], v195 offset:1024
	ds_read_b128 v[136:139], v195 offset:2048
	ds_read_b128 v[140:143], v195 offset:3072
	ds_read_b128 v[144:147], v196
	ds_read_b128 v[148:151], v196 offset:1024
	ds_read_b128 v[152:155], v196 offset:2048
	ds_read_b128 v[172:175], v196 offset:3072
	s_add_u32 s0, s38, 0x58000
	s_addc_u32 s1, s39, 0
	s_mov_b32 m0, s5
	ds_read_b128 v[176:179], v193 offset:32768
	ds_read_b128 v[180:183], v193 offset:33792
	ds_read_b128 v[184:187], v193 offset:34816
	ds_read_b128 v[198:201], v193 offset:35840
	ds_read_b128 v[202:205], v193 offset:36864
	ds_read_b128 v[206:209], v193 offset:37888
	ds_read_b128 v[214:217], v193 offset:38912
	ds_read_b128 v[218:221], v193 offset:39936
	global_load_lds_dwordx4 v156, s[0:1]
	s_mov_b32 m0, s18
	s_nop 0
	global_load_lds_dwordx4 v160, s[0:1]
	s_waitcnt vmcnt(8)
	s_waitcnt lgkmcnt(0)
	s_barrier
	s_setprio 1
	s_waitcnt lgkmcnt(0)
	v_mfma_f32_16x16x32_bf16 v[120:123], v[128:131], v[176:179], v[120:123]
	v_mfma_f32_16x16x32_bf16 v[124:127], v[136:139], v[176:179], v[124:127]
	v_mfma_f32_16x16x32_bf16 v[104:107], v[128:131], v[184:187], v[104:107]
	v_mfma_f32_16x16x32_bf16 v[108:111], v[136:139], v[184:187], v[108:111]
	v_mfma_f32_16x16x32_bf16 v[88:91], v[128:131], v[202:205], v[88:91]
	v_mfma_f32_16x16x32_bf16 v[92:95], v[136:139], v[202:205], v[92:95]
	v_mfma_f32_16x16x32_bf16 v[72:75], v[128:131], v[214:217], v[72:75]
	v_mfma_f32_16x16x32_bf16 v[76:79], v[136:139], v[214:217], v[76:79]
	v_mfma_f32_16x16x32_bf16 v[120:123], v[132:135], v[180:183], v[120:123]
	v_mfma_f32_16x16x32_bf16 v[124:127], v[140:143], v[180:183], v[124:127]
	v_mfma_f32_16x16x32_bf16 v[104:107], v[132:135], v[198:201], v[104:107]
	v_mfma_f32_16x16x32_bf16 v[108:111], v[140:143], v[198:201], v[108:111]
	v_mfma_f32_16x16x32_bf16 v[88:91], v[132:135], v[206:209], v[88:91]
	v_mfma_f32_16x16x32_bf16 v[92:95], v[140:143], v[206:209], v[92:95]
	v_mfma_f32_16x16x32_bf16 v[72:75], v[132:135], v[218:221], v[72:75]
	v_mfma_f32_16x16x32_bf16 v[76:79], v[140:143], v[218:221], v[76:79]
	s_setprio 0
	s_setprio 1
	v_mfma_f32_16x16x32_bf16 v[112:115], v[144:147], v[176:179], v[112:115]
	v_mfma_f32_16x16x32_bf16 v[116:119], v[152:155], v[176:179], v[116:119]
	v_mfma_f32_16x16x32_bf16 v[96:99], v[144:147], v[184:187], v[96:99]
	v_mfma_f32_16x16x32_bf16 v[100:103], v[152:155], v[184:187], v[100:103]
	v_mfma_f32_16x16x32_bf16 v[80:83], v[144:147], v[202:205], v[80:83]
	v_mfma_f32_16x16x32_bf16 v[84:87], v[152:155], v[202:205], v[84:87]
	v_mfma_f32_16x16x32_bf16 v[64:67], v[144:147], v[214:217], v[64:67]
	v_mfma_f32_16x16x32_bf16 v[68:71], v[152:155], v[214:217], v[68:71]
	v_mfma_f32_16x16x32_bf16 v[112:115], v[148:151], v[180:183], v[112:115]
	v_mfma_f32_16x16x32_bf16 v[116:119], v[172:175], v[180:183], v[116:119]
	v_mfma_f32_16x16x32_bf16 v[96:99], v[148:151], v[198:201], v[96:99]
	v_mfma_f32_16x16x32_bf16 v[100:103], v[172:175], v[198:201], v[100:103]
	v_mfma_f32_16x16x32_bf16 v[80:83], v[148:151], v[206:209], v[80:83]
	v_mfma_f32_16x16x32_bf16 v[84:87], v[172:175], v[206:209], v[84:87]
	v_mfma_f32_16x16x32_bf16 v[64:67], v[148:151], v[218:221], v[64:67]
	v_mfma_f32_16x16x32_bf16 v[68:71], v[172:175], v[218:221], v[68:71]
	s_setprio 0
	s_barrier
	s_add_i32 s0, s66, s2
	v_lshl_add_u64 v[188:189], v[188:189], 0, s[26:27]
	s_mov_b32 m0, s0
	ds_read_b128 v[176:179], v193 offset:49152
	ds_read_b128 v[180:183], v193 offset:50176
	ds_read_b128 v[184:187], v193 offset:51200
	ds_read_b128 v[198:201], v193 offset:52224
	ds_read_b128 v[202:205], v193 offset:53248
	ds_read_b128 v[206:209], v193 offset:54272
	ds_read_b128 v[214:217], v193 offset:55296
	ds_read_b128 v[218:221], v193 offset:56320
	global_load_lds_dwordx4 v[188:189], off
	s_add_i32 m0, s0, 0x2000
	s_add_u32 s0, s14, 0x30080
	v_lshl_add_u64 v[188:189], v[210:211], 0, s[26:27]
	s_addc_u32 s1, s15, 0
	s_add_i32 s14, s67, s2
	global_load_lds_dwordx4 v[188:189], off
	s_mov_b32 m0, s14
	s_nop 0
	global_load_lds_dwordx4 v158, s[0:1]
	s_add_i32 m0, s14, 0x2000
	s_nop 0
	global_load_lds_dwordx4 v162, s[0:1]
	v_lshl_add_u64 v[188:189], v[222:223], 0, s[26:27]
	s_mov_b32 m0, s19
	s_nop 0
	global_load_lds_dwordx4 v[188:189], off
	v_lshl_add_u64 v[188:189], v[224:225], 0, s[26:27]
	s_mov_b32 m0, s31
	s_nop 0
	global_load_lds_dwordx4 v[188:189], off
	s_waitcnt vmcnt(8)
	s_waitcnt lgkmcnt(0)
	s_barrier
	s_setprio 1
	s_waitcnt lgkmcnt(0)
	v_mfma_f32_16x16x32_bf16 v[56:59], v[128:131], v[176:179], v[56:59]
	v_mfma_f32_16x16x32_bf16 v[60:63], v[136:139], v[176:179], v[60:63]
	v_mfma_f32_16x16x32_bf16 v[40:43], v[128:131], v[184:187], v[40:43]
	v_mfma_f32_16x16x32_bf16 v[44:47], v[136:139], v[184:187], v[44:47]
	v_mfma_f32_16x16x32_bf16 v[24:27], v[128:131], v[202:205], v[24:27]
	v_mfma_f32_16x16x32_bf16 v[28:31], v[136:139], v[202:205], v[28:31]
	v_mfma_f32_16x16x32_bf16 v[8:11], v[128:131], v[214:217], v[8:11]
	v_mfma_f32_16x16x32_bf16 v[12:15], v[136:139], v[214:217], v[12:15]
	v_mfma_f32_16x16x32_bf16 v[56:59], v[132:135], v[180:183], v[56:59]
	v_mfma_f32_16x16x32_bf16 v[60:63], v[140:143], v[180:183], v[60:63]
	v_mfma_f32_16x16x32_bf16 v[40:43], v[132:135], v[198:201], v[40:43]
	v_mfma_f32_16x16x32_bf16 v[44:47], v[140:143], v[198:201], v[44:47]
	v_mfma_f32_16x16x32_bf16 v[24:27], v[132:135], v[206:209], v[24:27]
	v_mfma_f32_16x16x32_bf16 v[28:31], v[140:143], v[206:209], v[28:31]
	v_mfma_f32_16x16x32_bf16 v[8:11], v[132:135], v[218:221], v[8:11]
	v_mfma_f32_16x16x32_bf16 v[12:15], v[140:143], v[218:221], v[12:15]
	s_setprio 0
	s_setprio 1
	v_mfma_f32_16x16x32_bf16 v[48:51], v[144:147], v[176:179], v[48:51]
	v_mfma_f32_16x16x32_bf16 v[52:55], v[152:155], v[176:179], v[52:55]
	v_mfma_f32_16x16x32_bf16 v[32:35], v[144:147], v[184:187], v[32:35]
	v_mfma_f32_16x16x32_bf16 v[36:39], v[152:155], v[184:187], v[36:39]
	v_mfma_f32_16x16x32_bf16 v[16:19], v[144:147], v[202:205], v[16:19]
	v_mfma_f32_16x16x32_bf16 v[20:23], v[152:155], v[202:205], v[20:23]
	v_mfma_f32_16x16x32_bf16 v[4:7], v[144:147], v[214:217], v[4:7]
	v_mfma_f32_16x16x32_bf16 v[0:3], v[152:155], v[214:217], v[0:3]
	v_mfma_f32_16x16x32_bf16 v[48:51], v[148:151], v[180:183], v[48:51]
	v_mfma_f32_16x16x32_bf16 v[52:55], v[172:175], v[180:183], v[52:55]
	v_mfma_f32_16x16x32_bf16 v[32:35], v[148:151], v[198:201], v[32:35]
	v_mfma_f32_16x16x32_bf16 v[36:39], v[172:175], v[198:201], v[36:39]
	v_mfma_f32_16x16x32_bf16 v[16:19], v[148:151], v[206:209], v[16:19]
	v_mfma_f32_16x16x32_bf16 v[20:23], v[172:175], v[206:209], v[20:23]
	v_mfma_f32_16x16x32_bf16 v[4:7], v[148:151], v[218:221], v[4:7]
	v_mfma_f32_16x16x32_bf16 v[0:3], v[172:175], v[218:221], v[0:3]
	s_setprio 0
	s_barrier
	s_add_i32 s74, s74, 2
	s_add_u32 s72, s72, 0x100
	s_addc_u32 s73, s73, 0
	s_cmp_gt_u32 s74, 9
	s_mov_b64 s[0:1], s[12:13]
	s_cbranch_scc0 .LBB0_930
	s_and_b64 vcc, exec, s[28:29]
	s_cbranch_vccz .LBB0_933
	s_barrier

; #define PG8_STAGE(bufoff, gbase, voff) do { _Pragma("unroll") for (int _i = 0; _i < 2; ++_i) \
;     __builtin_amdgcn_global_load_lds((const unsigned*)((const char*)(gbase) + (voff)[_i]), (PG8_LAS unsigned*)(lds + (bufoff) + ldsw + _i * 8192), 16, 0, 0); } while (0)
; #define PG8_LDA(dst, b, h) do { _Pragma("unroll") for (int m = 0; m < 4; ++m) _Pragma("unroll") for (int k = 0; k < 2; ++k) dst[m][k] = *(const PG8_LAS bf16x8*)(lds + PG8_SA(b, h) + aoff + m * 2048 + k * 1024); } while (0)
; #define PG8_LDB(dst, b, h) do { _Pragma("unroll") for (int n = 0; n < 2; ++n) _Pragma("unroll") for (int k = 0; k < 2; ++k) dst[n][k] = *(const PG8_LAS bf16x8*)(lds + PG8_SB(b, h) + boff + n * 2048 + k * 1024); } while (0)
; #define PG8_MMA(ai, bj, At, Bt) do { __builtin_amdgcn_s_setprio(1); _Pragma("unroll") for (int m = 0; m < 4; ++m) _Pragma("unroll") for (int n = 0; n < 2; ++n) _Pragma("unroll") for (int k = 0; k < 2; ++k) \
;     acc[ai][bj][m][n] = __builtin_amdgcn_mfma_f32_16x16x32_bf16(Bt[n][k], At[m][k], acc[ai][bj][m][n], 0, 0, 0); __builtin_amdgcn_s_setprio(0); } while (0)
; #define PG8_WAIT_V(n) asm volatile("s_waitcnt vmcnt(" #n ")" ::: "memory")
; #define PG8_WAIT_L(n) asm volatile("s_waitcnt lgkmcnt(" #n ")" ::: "memory")
; #define PG8_BAR __builtin_amdgcn_s_barrier()
; #define PG8_SCHED __builtin_amdgcn_sched_barrier(0)
; template <class Epi, class Sched>
; DI void gemm_phase(PG8_LAS unsigned char* lds, const Gemm g, const Sched& S, const Epi& E) {
;     ...
;     for (int t = 0; t < nt; t += 2) {
;       const bool last = (t == nt - 2);
;       const char* a1 = cA + (size_t)(t + 1) * kstep;
;       const char* a2 = last ? nA : cA + (size_t)(t + 2) * kstep; const char* b2 = last ? nB : cB + (size_t)(t + 2) * kstep;
;       const char* a3 = a2 + kstep; const char* b3 = b2 + kstep;
;       PG8_LDB(B0, 0, 0); PG8_LDB(B1, 0, 1); PG8_SCHED; PG8_LDA(At, 0, 0); PG8_STAGE(PG8_SA(1, 1), a1 + hstepA, voffA);
;       PG8_WAIT_V(8); PG8_WAIT_L(0); PG8_BAR; PG8_MMA(0, 0, At, B0); PG8_MMA(0, 1, At, B1); PG8_BAR; PG8_SCHED;
;       PG8_LDA(At, 0, 1); PG8_STAGE(PG8_SB(0, 0), b2, voffB); PG8_STAGE(PG8_SB(0, 1), b2 + hstepB, voffB); PG8_STAGE(PG8_SA(0, 0), a2, voffA);
;       PG8_WAIT_V(8); PG8_WAIT_L(0); PG8_BAR; PG8_MMA(1, 0, At, B0); PG8_MMA(1, 1, At, B1); PG8_BAR; PG8_SCHED;
.LBB0_984:
	s_add_u32 s33, s12, s70
	s_addc_u32 s56, s13, s71
	s_add_u32 s57, s33, 0x100
	s_addc_u32 s62, s56, 0
	s_and_b64 s[16:17], s[64:65], exec
	s_cselect_b32 s73, s39, s62
	s_cselect_b32 s72, s38, s57
	s_add_u32 s16, s10, s70
	s_addc_u32 s17, s11, s71
	s_add_u32 s57, s16, 0x100
	s_addc_u32 s62, s17, 0
	s_and_b64 s[16:17], s[64:65], exec
	s_cselect_b32 s75, s1, s62
	s_cselect_b32 s74, s37, s57
	s_add_u32 s66, s33, 0x58080
	ds_read_b128 v[128:131], v171
	ds_read_b128 v[132:135], v171 offset:1024
	ds_read_b128 v[136:139], v171 offset:2048
	ds_read_b128 v[140:143], v171 offset:3072
	ds_read_b128 v[144:147], v190
	ds_read_b128 v[148:151], v190 offset:1024
	ds_read_b128 v[152:155], v190 offset:2048
	ds_read_b128 v[172:175], v190 offset:3072
	s_addc_u32 s67, s56, 0
	s_add_i32 s16, s94, s55
	s_add_i32 m0, s68, 0xc000
	s_add_i32 s57, s68, 0xe000
	s_add_i32 s56, s16, 0x2000
	s_add_u32 s76, s74, 0x10000
	s_addc_u32 s77, s75, 0
	s_add_i32 s63, s95, s55
	s_add_i32 s62, s63, 0x2000
	s_add_u32 s70, s72, 0x58000
	s_addc_u32 s71, s73, 0
	s_add_i32 vcc_lo, s18, s55
	s_add_i32 s33, vcc_lo, 0x2000
	s_add_u32 s64, s74, 0x10080
	s_addc_u32 s65, s75, 0
	s_add_i32 vcc_hi, s19, s55
	s_add_i32 s17, vcc_hi, 0x2000
	ds_read_b128 v[176:179], v191
	ds_read_b128 v[180:183], v191 offset:1024
	ds_read_b128 v[184:187], v191 offset:2048
	ds_read_b128 v[196:199], v191 offset:3072
	ds_read_b128 v[200:203], v191 offset:4096
	ds_read_b128 v[204:207], v191 offset:5120
	ds_read_b128 v[208:211], v191 offset:6144
	ds_read_b128 v[214:217], v191 offset:7168
	global_load_lds_dwordx4 v156, s[66:67]
	s_mov_b32 m0, s57
	s_nop 0
	global_load_lds_dwordx4 v160, s[66:67]
	s_waitcnt vmcnt(8)
	s_waitcnt lgkmcnt(0)
	s_barrier
	s_setprio 1
	s_waitcnt lgkmcnt(0)
	v_mfma_f32_16x16x32_bf16 v[124:127], v[128:131], v[176:179], v[124:127]
	v_mfma_f32_16x16x32_bf16 v[120:123], v[136:139], v[176:179], v[120:123]
	v_mfma_f32_16x16x32_bf16 v[108:111], v[128:131], v[184:187], v[108:111]
	v_mfma_f32_16x16x32_bf16 v[104:107], v[136:139], v[184:187], v[104:107]
	v_mfma_f32_16x16x32_bf16 v[92:95], v[128:131], v[200:203], v[92:95]
	v_mfma_f32_16x16x32_bf16 v[88:91], v[136:139], v[200:203], v[88:91]
	v_mfma_f32_16x16x32_bf16 v[76:79], v[128:131], v[208:211], v[76:79]
	v_mfma_f32_16x16x32_bf16 v[72:75], v[136:139], v[208:211], v[72:75]
	v_mfma_f32_16x16x32_bf16 v[124:127], v[132:135], v[180:183], v[124:127]
	v_mfma_f32_16x16x32_bf16 v[120:123], v[140:143], v[180:183], v[120:123]
	v_mfma_f32_16x16x32_bf16 v[108:111], v[132:135], v[196:199], v[108:111]
	v_mfma_f32_16x16x32_bf16 v[104:107], v[140:143], v[196:199], v[104:107]
	v_mfma_f32_16x16x32_bf16 v[92:95], v[132:135], v[204:207], v[92:95]
	v_mfma_f32_16x16x32_bf16 v[88:91], v[140:143], v[204:207], v[88:91]
	v_mfma_f32_16x16x32_bf16 v[76:79], v[132:135], v[214:217], v[76:79]
	v_mfma_f32_16x16x32_bf16 v[72:75], v[140:143], v[214:217], v[72:75]
	s_setprio 0
	s_setprio 1
	v_mfma_f32_16x16x32_bf16 v[116:119], v[144:147], v[176:179], v[116:119]
	v_mfma_f32_16x16x32_bf16 v[112:115], v[152:155], v[176:179], v[112:115]
	v_mfma_f32_16x16x32_bf16 v[100:103], v[144:147], v[184:187], v[100:103]
	v_mfma_f32_16x16x32_bf16 v[96:99], v[152:155], v[184:187], v[96:99]
	v_mfma_f32_16x16x32_bf16 v[84:87], v[144:147], v[200:203], v[84:87]
	v_mfma_f32_16x16x32_bf16 v[80:83], v[152:155], v[200:203], v[80:83]
	v_mfma_f32_16x16x32_bf16 v[68:71], v[144:147], v[208:211], v[68:71]
	v_mfma_f32_16x16x32_bf16 v[64:67], v[152:155], v[208:211], v[64:67]
	v_mfma_f32_16x16x32_bf16 v[116:119], v[148:151], v[180:183], v[116:119]
	v_mfma_f32_16x16x32_bf16 v[112:115], v[172:175], v[180:183], v[112:115]
	v_mfma_f32_16x16x32_bf16 v[100:103], v[148:151], v[196:199], v[100:103]
	v_mfma_f32_16x16x32_bf16 v[96:99], v[172:175], v[196:199], v[96:99]
	v_mfma_f32_16x16x32_bf16 v[84:87], v[148:151], v[204:207], v[84:87]
	v_mfma_f32_16x16x32_bf16 v[80:83], v[172:175], v[204:207], v[80:83]
	v_mfma_f32_16x16x32_bf16 v[68:71], v[148:151], v[214:217], v[68:71]
	v_mfma_f32_16x16x32_bf16 v[64:67], v[172:175], v[214:217], v[64:67]
	s_setprio 0
	s_barrier
	s_mov_b32 m0, s16
	v_lshl_add_u64 v[188:189], s[74:75], 0, v[158:159]
	ds_read_b128 v[176:179], v191 offset:16384
	ds_read_b128 v[180:183], v191 offset:17408
	ds_read_b128 v[184:187], v191 offset:18432
	ds_read_b128 v[196:199], v191 offset:19456
	ds_read_b128 v[200:203], v191 offset:20480
	ds_read_b128 v[204:207], v191 offset:21504
	ds_read_b128 v[208:211], v191 offset:22528
	ds_read_b128 v[214:217], v191 offset:23552
	global_load_lds_dwordx4 v[188:189], off
	v_lshl_add_u64 v[218:219], s[74:75], 0, v[162:163]
	s_mov_b32 m0, s56
	s_nop 0
	global_load_lds_dwordx4 v[218:219], off
	s_mov_b32 m0, s63
	v_lshl_add_u64 v[222:223], s[72:73], 0, v[160:161]
	global_load_lds_dwordx4 v158, s[76:77]
	s_mov_b32 m0, s62
	s_nop 0
	global_load_lds_dwordx4 v162, s[76:77]
	v_lshl_add_u64 v[220:221], s[72:73], 0, v[156:157]
	s_mov_b32 m0, s68
	s_nop 0
	global_load_lds_dwordx4 v[220:221], off
	s_mov_b32 m0, s69
	s_nop 0
	global_load_lds_dwordx4 v[222:223], off
	s_waitcnt vmcnt(8)
	s_waitcnt lgkmcnt(0)
	s_barrier
; #define PG8_STAGE(bufoff, gbase, voff) do { _Pragma("unroll") for (int _i = 0; _i < 2; ++_i) \
;     __builtin_amdgcn_global_load_lds((const unsigned*)((const char*)(gbase) + (voff)[_i]), (PG8_LAS unsigned*)(lds + (bufoff) + ldsw + _i * 8192), 16, 0, 0); } while (0)
; #define PG8_LDA(dst, b, h) do { _Pragma("unroll") for (int m = 0; m < 4; ++m) _Pragma("unroll") for (int k = 0; k < 2; ++k) dst[m][k] = *(const PG8_LAS bf16x8*)(lds + PG8_SA(b, h) + aoff + m * 2048 + k * 1024); } while (0)
; #define PG8_LDB(dst, b, h) do { _Pragma("unroll") for (int n = 0; n < 2; ++n) _Pragma("unroll") for (int k = 0; k < 2; ++k) dst[n][k] = *(const PG8_LAS bf16x8*)(lds + PG8_SB(b, h) + boff + n * 2048 + k * 1024); } while (0)
; #define PG8_MMA(ai, bj, At, Bt) do { __builtin_amdgcn_s_setprio(1); _Pragma("unroll") for (int m = 0; m < 4; ++m) _Pragma("unroll") for (int n = 0; n < 2; ++n) _Pragma("unroll") for (int k = 0; k < 2; ++k) \
;     acc[ai][bj][m][n] = __builtin_amdgcn_mfma_f32_16x16x32_bf16(Bt[n][k], At[m][k], acc[ai][bj][m][n], 0, 0, 0); __builtin_amdgcn_s_setprio(0); } while (0)
; #define PG8_WAIT_V(n) asm volatile("s_waitcnt vmcnt(" #n ")" ::: "memory")
; #define PG8_WAIT_L(n) asm volatile("s_waitcnt lgkmcnt(" #n ")" ::: "memory")
; #define PG8_BAR __builtin_amdgcn_s_barrier()
; #define PG8_SCHED __builtin_amdgcn_sched_barrier(0)
; template <class Epi, class Sched>
; DI void gemm_phase(PG8_LAS unsigned char* lds, const Gemm g, const Sched& S, const Epi& E) {
;     ...
;       PG8_WAIT_V(8); PG8_WAIT_L(0); PG8_BAR; PG8_MMA(1, 0, At, B0); PG8_MMA(1, 1, At, B1); PG8_BAR; PG8_SCHED;
;       PG8_LDB(B0, 1, 0); PG8_LDB(B1, 1, 1); PG8_SCHED; PG8_LDA(At, 1, 0); PG8_STAGE(PG8_SA(0, 1), a2 + hstepA, voffA);
;       PG8_WAIT_V(8); PG8_WAIT_L(0); PG8_BAR; PG8_MMA(0, 0, At, B0); PG8_MMA(0, 1, At, B1); PG8_BAR; PG8_SCHED;
	s_setprio 1
	s_waitcnt lgkmcnt(0)
	v_mfma_f32_16x16x32_bf16 v[60:63], v[128:131], v[176:179], v[60:63]
	v_mfma_f32_16x16x32_bf16 v[56:59], v[136:139], v[176:179], v[56:59]
	v_mfma_f32_16x16x32_bf16 v[44:47], v[128:131], v[184:187], v[44:47]
	v_mfma_f32_16x16x32_bf16 v[40:43], v[136:139], v[184:187], v[40:43]
	v_mfma_f32_16x16x32_bf16 v[28:31], v[128:131], v[200:203], v[28:31]
	v_mfma_f32_16x16x32_bf16 v[24:27], v[136:139], v[200:203], v[24:27]
	v_mfma_f32_16x16x32_bf16 v[12:15], v[128:131], v[208:211], v[12:15]
	v_mfma_f32_16x16x32_bf16 v[8:11], v[136:139], v[208:211], v[8:11]
	v_mfma_f32_16x16x32_bf16 v[60:63], v[132:135], v[180:183], v[60:63]
	v_mfma_f32_16x16x32_bf16 v[56:59], v[140:143], v[180:183], v[56:59]
	v_mfma_f32_16x16x32_bf16 v[44:47], v[132:135], v[196:199], v[44:47]
	v_mfma_f32_16x16x32_bf16 v[40:43], v[140:143], v[196:199], v[40:43]
	v_mfma_f32_16x16x32_bf16 v[28:31], v[132:135], v[204:207], v[28:31]
	v_mfma_f32_16x16x32_bf16 v[24:27], v[140:143], v[204:207], v[24:27]
	v_mfma_f32_16x16x32_bf16 v[12:15], v[132:135], v[214:217], v[12:15]
	v_mfma_f32_16x16x32_bf16 v[8:11], v[140:143], v[214:217], v[8:11]
	s_setprio 0
	s_setprio 1
	v_mfma_f32_16x16x32_bf16 v[52:55], v[144:147], v[176:179], v[52:55]
	v_mfma_f32_16x16x32_bf16 v[48:51], v[152:155], v[176:179], v[48:51]
	v_mfma_f32_16x16x32_bf16 v[36:39], v[144:147], v[184:187], v[36:39]
	v_mfma_f32_16x16x32_bf16 v[32:35], v[152:155], v[184:187], v[32:35]
	v_mfma_f32_16x16x32_bf16 v[20:23], v[144:147], v[200:203], v[20:23]
	v_mfma_f32_16x16x32_bf16 v[16:19], v[152:155], v[200:203], v[16:19]
	v_mfma_f32_16x16x32_bf16 v[4:7], v[144:147], v[208:211], v[4:7]
	v_mfma_f32_16x16x32_bf16 v[0:3], v[152:155], v[208:211], v[0:3]
	v_mfma_f32_16x16x32_bf16 v[52:55], v[148:151], v[180:183], v[52:55]
	v_mfma_f32_16x16x32_bf16 v[48:51], v[172:175], v[180:183], v[48:51]
	v_mfma_f32_16x16x32_bf16 v[36:39], v[148:151], v[196:199], v[36:39]
	v_mfma_f32_16x16x32_bf16 v[32:35], v[172:175], v[196:199], v[32:35]
	v_mfma_f32_16x16x32_bf16 v[20:23], v[148:151], v[204:207], v[20:23]
	v_mfma_f32_16x16x32_bf16 v[16:19], v[172:175], v[204:207], v[16:19]
	v_mfma_f32_16x16x32_bf16 v[4:7], v[148:151], v[214:217], v[4:7]
	v_mfma_f32_16x16x32_bf16 v[0:3], v[172:175], v[214:217], v[0:3]
	s_setprio 0
	s_barrier
	ds_read_b128 v[128:131], v193
	ds_read_b128 v[132:135], v193 offset:1024
	ds_read_b128 v[136:139], v193 offset:2048
	ds_read_b128 v[140:143], v193 offset:3072
	ds_read_b128 v[144:147], v194
	ds_read_b128 v[148:151], v194 offset:1024
	ds_read_b128 v[152:155], v194 offset:2048
	ds_read_b128 v[172:175], v194 offset:3072
	s_mov_b32 m0, s79
	ds_read_b128 v[176:179], v191 offset:32768
	ds_read_b128 v[180:183], v191 offset:33792
	ds_read_b128 v[184:187], v191 offset:34816
	ds_read_b128 v[196:199], v191 offset:35840
	ds_read_b128 v[200:203], v191 offset:36864
	ds_read_b128 v[204:207], v191 offset:37888
	ds_read_b128 v[208:211], v191 offset:38912
	ds_read_b128 v[214:217], v191 offset:39936
	global_load_lds_dwordx4 v156, s[70:71]
	s_mov_b32 m0, s90
	s_nop 0
	global_load_lds_dwordx4 v160, s[70:71]
	s_waitcnt vmcnt(8)
	s_waitcnt lgkmcnt(0)
	s_barrier
	s_setprio 1
	s_waitcnt lgkmcnt(0)
	v_mfma_f32_16x16x32_bf16 v[124:127], v[128:131], v[176:179], v[124:127]
	v_mfma_f32_16x16x32_bf16 v[120:123], v[136:139], v[176:179], v[120:123]
	v_mfma_f32_16x16x32_bf16 v[108:111], v[128:131], v[184:187], v[108:111]
	v_mfma_f32_16x16x32_bf16 v[104:107], v[136:139], v[184:187], v[104:107]
	v_mfma_f32_16x16x32_bf16 v[92:95], v[128:131], v[200:203], v[92:95]
	v_mfma_f32_16x16x32_bf16 v[88:91], v[136:139], v[200:203], v[88:91]
	v_mfma_f32_16x16x32_bf16 v[76:79], v[128:131], v[208:211], v[76:79]
	v_mfma_f32_16x16x32_bf16 v[72:75], v[136:139], v[208:211], v[72:75]
	v_mfma_f32_16x16x32_bf16 v[124:127], v[132:135], v[180:183], v[124:127]
	v_mfma_f32_16x16x32_bf16 v[120:123], v[140:143], v[180:183], v[120:123]
	v_mfma_f32_16x16x32_bf16 v[108:111], v[132:135], v[196:199], v[108:111]
	v_mfma_f32_16x16x32_bf16 v[104:107], v[140:143], v[196:199], v[104:107]
	v_mfma_f32_16x16x32_bf16 v[92:95], v[132:135], v[204:207], v[92:95]
	v_mfma_f32_16x16x32_bf16 v[88:91], v[140:143], v[204:207], v[88:91]
	v_mfma_f32_16x16x32_bf16 v[76:79], v[132:135], v[214:217], v[76:79]
	v_mfma_f32_16x16x32_bf16 v[72:75], v[140:143], v[214:217], v[72:75]
	s_setprio 0
	s_setprio 1
	v_mfma_f32_16x16x32_bf16 v[116:119], v[144:147], v[176:179], v[116:119]
	v_mfma_f32_16x16x32_bf16 v[112:115], v[152:155], v[176:179], v[112:115]
	v_mfma_f32_16x16x32_bf16 v[100:103], v[144:147], v[184:187], v[100:103]
	v_mfma_f32_16x16x32_bf16 v[96:99], v[152:155], v[184:187], v[96:99]
	v_mfma_f32_16x16x32_bf16 v[84:87], v[144:147], v[200:203], v[84:87]
	v_mfma_f32_16x16x32_bf16 v[80:83], v[152:155], v[200:203], v[80:83]
	v_mfma_f32_16x16x32_bf16 v[68:71], v[144:147], v[208:211], v[68:71]
	v_mfma_f32_16x16x32_bf16 v[64:67], v[152:155], v[208:211], v[64:67]
	v_mfma_f32_16x16x32_bf16 v[116:119], v[148:151], v[180:183], v[116:119]
	v_mfma_f32_16x16x32_bf16 v[112:115], v[172:175], v[180:183], v[112:115]
	v_mfma_f32_16x16x32_bf16 v[100:103], v[148:151], v[196:199], v[100:103]
	v_mfma_f32_16x16x32_bf16 v[96:99], v[172:175], v[196:199], v[96:99]
	v_mfma_f32_16x16x32_bf16 v[84:87], v[148:151], v[204:207], v[84:87]
	v_mfma_f32_16x16x32_bf16 v[80:83], v[172:175], v[204:207], v[80:83]
	v_mfma_f32_16x16x32_bf16 v[68:71], v[148:151], v[214:217], v[68:71]
	v_mfma_f32_16x16x32_bf16 v[64:67], v[172:175], v[214:217], v[64:67]
	s_setprio 0
	s_barrier
; #define PG8_STAGE(bufoff, gbase, voff) do { _Pragma("unroll") for (int _i = 0; _i < 2; ++_i) \
;     __builtin_amdgcn_global_load_lds((const unsigned*)((const char*)(gbase) + (voff)[_i]), (PG8_LAS unsigned*)(lds + (bufoff) + ldsw + _i * 8192), 16, 0, 0); } while (0)
; #define PG8_LDA(dst, b, h) do { _Pragma("unroll") for (int m = 0; m < 4; ++m) _Pragma("unroll") for (int k = 0; k < 2; ++k) dst[m][k] = *(const PG8_LAS bf16x8*)(lds + PG8_SA(b, h) + aoff + m * 2048 + k * 1024); } while (0)
; #define PG8_MMA(ai, bj, At, Bt) do { __builtin_amdgcn_s_setprio(1); _Pragma("unroll") for (int m = 0; m < 4; ++m) _Pragma("unroll") for (int n = 0; n < 2; ++n) _Pragma("unroll") for (int k = 0; k < 2; ++k) \
;     acc[ai][bj][m][n] = __builtin_amdgcn_mfma_f32_16x16x32_bf16(Bt[n][k], At[m][k], acc[ai][bj][m][n], 0, 0, 0); __builtin_amdgcn_s_setprio(0); } while (0)
; #define PG8_WAIT_V(n) asm volatile("s_waitcnt vmcnt(" #n ")" ::: "memory")
; #define PG8_WAIT_L(n) asm volatile("s_waitcnt lgkmcnt(" #n ")" ::: "memory")
; #define PG8_BAR __builtin_amdgcn_s_barrier()
; #define PG8_SCHED __builtin_amdgcn_sched_barrier(0)
; template <class Epi, class Sched>
; DI void gemm_phase(PG8_LAS unsigned char* lds, const Gemm g, const Sched& S, const Epi& E) {
;     ...
;       PG8_LDA(At, 1, 1); PG8_STAGE(PG8_SB(1, 0), b3, voffB); PG8_STAGE(PG8_SB(1, 1), b3 + hstepB, voffB); PG8_STAGE(PG8_SA(1, 0), a3, voffA);
;       PG8_WAIT_V(8); PG8_WAIT_L(0); PG8_BAR; PG8_MMA(1, 0, At, B0); PG8_MMA(1, 1, At, B1); PG8_BAR; PG8_SCHED;
;     }
;     if (wr == 0) PG8_BAR;
	s_mov_b32 m0, vcc_lo
	v_lshl_add_u64 v[188:189], v[188:189], 0, s[28:29]
	ds_read_b128 v[176:179], v191 offset:49152
	ds_read_b128 v[180:183], v191 offset:50176
	ds_read_b128 v[184:187], v191 offset:51200
	ds_read_b128 v[196:199], v191 offset:52224
	ds_read_b128 v[200:203], v191 offset:53248
	ds_read_b128 v[204:207], v191 offset:54272
	ds_read_b128 v[208:211], v191 offset:55296
	ds_read_b128 v[214:217], v191 offset:56320
	global_load_lds_dwordx4 v[188:189], off
	v_lshl_add_u64 v[188:189], v[218:219], 0, s[28:29]
	s_mov_b32 m0, s33
	s_nop 0
	global_load_lds_dwordx4 v[188:189], off
	s_mov_b32 m0, vcc_hi
	s_nop 0
	global_load_lds_dwordx4 v158, s[64:65]
	s_mov_b32 m0, s17
	s_nop 0
	global_load_lds_dwordx4 v162, s[64:65]
	v_lshl_add_u64 v[188:189], v[220:221], 0, s[28:29]
	s_mov_b32 m0, s91
	s_nop 0
	global_load_lds_dwordx4 v[188:189], off
	v_lshl_add_u64 v[188:189], v[222:223], 0, s[28:29]
	s_mov_b32 m0, s92
	s_nop 0
	global_load_lds_dwordx4 v[188:189], off
	s_waitcnt vmcnt(8)
	s_waitcnt lgkmcnt(0)
	s_barrier
	s_setprio 1
	s_waitcnt lgkmcnt(0)
	v_mfma_f32_16x16x32_bf16 v[60:63], v[128:131], v[176:179], v[60:63]
	v_mfma_f32_16x16x32_bf16 v[56:59], v[136:139], v[176:179], v[56:59]
	v_mfma_f32_16x16x32_bf16 v[44:47], v[128:131], v[184:187], v[44:47]
	v_mfma_f32_16x16x32_bf16 v[40:43], v[136:139], v[184:187], v[40:43]
	v_mfma_f32_16x16x32_bf16 v[28:31], v[128:131], v[200:203], v[28:31]
	v_mfma_f32_16x16x32_bf16 v[24:27], v[136:139], v[200:203], v[24:27]
	v_mfma_f32_16x16x32_bf16 v[12:15], v[128:131], v[208:211], v[12:15]
	v_mfma_f32_16x16x32_bf16 v[8:11], v[136:139], v[208:211], v[8:11]
	v_mfma_f32_16x16x32_bf16 v[60:63], v[132:135], v[180:183], v[60:63]
	v_mfma_f32_16x16x32_bf16 v[56:59], v[140:143], v[180:183], v[56:59]
	v_mfma_f32_16x16x32_bf16 v[44:47], v[132:135], v[196:199], v[44:47]
	v_mfma_f32_16x16x32_bf16 v[40:43], v[140:143], v[196:199], v[40:43]
	v_mfma_f32_16x16x32_bf16 v[28:31], v[132:135], v[204:207], v[28:31]
	v_mfma_f32_16x16x32_bf16 v[24:27], v[140:143], v[204:207], v[24:27]
	v_mfma_f32_16x16x32_bf16 v[12:15], v[132:135], v[214:217], v[12:15]
	v_mfma_f32_16x16x32_bf16 v[8:11], v[140:143], v[214:217], v[8:11]
	s_setprio 0
	s_setprio 1
	v_mfma_f32_16x16x32_bf16 v[52:55], v[144:147], v[176:179], v[52:55]
	v_mfma_f32_16x16x32_bf16 v[48:51], v[152:155], v[176:179], v[48:51]
	v_mfma_f32_16x16x32_bf16 v[36:39], v[144:147], v[184:187], v[36:39]
	v_mfma_f32_16x16x32_bf16 v[32:35], v[152:155], v[184:187], v[32:35]
	v_mfma_f32_16x16x32_bf16 v[20:23], v[144:147], v[200:203], v[20:23]
	v_mfma_f32_16x16x32_bf16 v[16:19], v[152:155], v[200:203], v[16:19]
	v_mfma_f32_16x16x32_bf16 v[4:7], v[144:147], v[208:211], v[4:7]
	v_mfma_f32_16x16x32_bf16 v[0:3], v[152:155], v[208:211], v[0:3]
	v_mfma_f32_16x16x32_bf16 v[52:55], v[148:151], v[180:183], v[52:55]
	v_mfma_f32_16x16x32_bf16 v[48:51], v[172:175], v[180:183], v[48:51]
	v_mfma_f32_16x16x32_bf16 v[36:39], v[148:151], v[196:199], v[36:39]
	v_mfma_f32_16x16x32_bf16 v[32:35], v[172:175], v[196:199], v[32:35]
	v_mfma_f32_16x16x32_bf16 v[20:23], v[148:151], v[204:207], v[20:23]
	v_mfma_f32_16x16x32_bf16 v[16:19], v[172:175], v[204:207], v[16:19]
	v_mfma_f32_16x16x32_bf16 v[4:7], v[148:151], v[214:217], v[4:7]
	v_mfma_f32_16x16x32_bf16 v[0:3], v[172:175], v[214:217], v[0:3]
	s_setprio 0
	s_barrier
	s_andn2_b64 vcc, exec, s[44:45]
	s_mov_b64 s[64:65], -1
	s_mov_b64 s[44:45], 0
	s_mov_b64 s[70:71], 0x100
	s_cbranch_vccz .LBB0_984
	s_and_b64 vcc, exec, s[30:31]
	s_cbranch_vccz .LBB0_987
	s_barrier

; DI unsigned xb_ld(unsigned* p) { return __hip_atomic_load(p, __ATOMIC_RELAXED, __HIP_MEMORY_SCOPE_AGENT); }
; DI unsigned xb_add(unsigned* p, unsigned v) { return __hip_atomic_fetch_add(p, v, __ATOMIC_RELAXED, __HIP_MEMORY_SCOPE_AGENT); }
; #define XB_SPIN(cond, bar) do { unsigned _sp = 0; while (cond) { __builtin_amdgcn_s_sleep(1); \
;     if ((++_sp & 255u) == 0u) { if (xb_ld(&(bar)[XB_TMO])) break; if (_sp > XB_SPIN_CAP) { atomicAdd(&(bar)[XB_TMO], 1u); break; } } } } while (0)
; DI void xcd_barrier(const XcdBarrier& b) {
;     ...
;   if (threadIdx.x == 0) {
;     unsigned* bar = b.bar;
;     __builtin_amdgcn_s_waitcnt(0);
;     unsigned nloc = b.st[0], nx = b.st[1];
;     if (nloc == 0u) { xcd_barrier_complete(bar, b.x, nloc, nx); b.st[0] = nloc; b.st[1] = nx; }
;     const unsigned old = xb_add(&bar[XB_XSUB(b.x)], 1u);
;     const unsigned gen = old / nloc;
;     if (old + 1u == (gen + 1u) * nloc) {
;       __builtin_amdgcn_fence(__ATOMIC_RELEASE, "agent");
;       asm volatile("s_waitcnt vmcnt(0)" ::: "memory");
;       const unsigned og = xb_add(&bar[XB_TOP], 1u);
;       const unsigned tg = og / nx;
;       if (og + 1u == (tg + 1u) * nx) xb_add(&bar[XB_TOPGEN], 1u);
;       else XB_SPIN(xb_ld(&bar[XB_TOPGEN]) == tg, bar);
;       __builtin_amdgcn_fence(__ATOMIC_ACQUIRE, "agent");
;       xb_add(&bar[XB_XGEN(b.x)], 1u);
;       asm volatile("s_waitcnt vmcnt(0)" ::: "memory");
;     } else {
;       XB_SPIN(xb_ld(&bar[XB_XGEN(b.x)]) == gen, bar);
;       __builtin_amdgcn_fence(__ATOMIC_ACQUIRE, "agent");
;       asm volatile("s_waitcnt vmcnt(0)" ::: "memory");
;     }
.LBB0_1128:
	s_mov_b64 s[6:7], exec
	s_lshl_b32 s2, s78, 8
	v_mbcnt_lo_u32_b32 v0, s6, 0
	s_add_u32 s2, s92, s2
	v_mbcnt_hi_u32_b32 v0, s7, v0
	s_addc_u32 s3, s93, 0
	v_cmp_eq_u32_e32 vcc, 0, v0
	s_and_saveexec_b64 s[8:9], vcc
	s_cbranch_execz .LBB0_1130
	v_mov_b32_e32 v255, 0
	ds_read_b32 v255, v255 offset:264
	s_waitcnt lgkmcnt(0)
	v_readfirstlane_b32 s100, v255
	s_nop 3
	s_cmp_lg_u32 s100, 0
	s_cbranch_scc0 .Lei_a_9
	buffer_inv sc1

; #define PG8_STAGE(bufoff, gbase, voff) do { _Pragma("unroll") for (int _i = 0; _i < 2; ++_i) \
;     __builtin_amdgcn_global_load_lds((const unsigned*)((const char*)(gbase) + (voff)[_i]), (PG8_LAS unsigned*)(lds + (bufoff) + ldsw + _i * 8192), 16, 0, 0); } while (0)
; #define PG8_LDA(dst, b, h) do { _Pragma("unroll") for (int m = 0; m < 4; ++m) _Pragma("unroll") for (int k = 0; k < 2; ++k) dst[m][k] = *(const PG8_LAS bf16x8*)(lds + PG8_SA(b, h) + aoff + m * 2048 + k * 1024); } while (0)
; #define PG8_LDB(dst, b, h) do { _Pragma("unroll") for (int n = 0; n < 2; ++n) _Pragma("unroll") for (int k = 0; k < 2; ++k) dst[n][k] = *(const PG8_LAS bf16x8*)(lds + PG8_SB(b, h) + boff + n * 2048 + k * 1024); } while (0)
; #define PG8_MMA(ai, bj, At, Bt) do { __builtin_amdgcn_s_setprio(1); _Pragma("unroll") for (int m = 0; m < 4; ++m) _Pragma("unroll") for (int n = 0; n < 2; ++n) _Pragma("unroll") for (int k = 0; k < 2; ++k) \
;     acc[ai][bj][m][n] = __builtin_amdgcn_mfma_f32_16x16x32_bf16(Bt[n][k], At[m][k], acc[ai][bj][m][n], 0, 0, 0); __builtin_amdgcn_s_setprio(0); } while (0)
; #define PG8_WAIT_V(n) asm volatile("s_waitcnt vmcnt(" #n ")" ::: "memory")
; #define PG8_WAIT_L(n) asm volatile("s_waitcnt lgkmcnt(" #n ")" ::: "memory")
; #define PG8_BAR __builtin_amdgcn_s_barrier()
; #define PG8_SCHED __builtin_amdgcn_sched_barrier(0)
; template <class Epi, class Sched>
; DI void gemm_phase(PG8_LAS unsigned char* lds, const Gemm g, const Sched& S, const Epi& E) {
;     ...
;     for (int t = 0; t < nt; t += 2) {
;       const bool last = (t == nt - 2);
;       const char* a1 = cA + (size_t)(t + 1) * kstep;
;       const char* a2 = last ? nA : cA + (size_t)(t + 2) * kstep; const char* b2 = last ? nB : cB + (size_t)(t + 2) * kstep;
;       const char* a3 = a2 + kstep; const char* b3 = b2 + kstep;
;       PG8_LDB(B0, 0, 0); PG8_LDB(B1, 0, 1); PG8_SCHED; PG8_LDA(At, 0, 0); PG8_STAGE(PG8_SA(1, 1), a1 + hstepA, voffA);
;       PG8_WAIT_V(8); PG8_WAIT_L(0); PG8_BAR; PG8_MMA(0, 0, At, B0); PG8_MMA(0, 1, At, B1); PG8_BAR; PG8_SCHED;
;       PG8_LDA(At, 0, 1); PG8_STAGE(PG8_SB(0, 0), b2, voffB); PG8_STAGE(PG8_SB(0, 1), b2 + hstepB, voffB); PG8_STAGE(PG8_SA(0, 0), a2, voffA);
;       PG8_WAIT_V(8); PG8_WAIT_L(0); PG8_BAR; PG8_MMA(1, 0, At, B0); PG8_MMA(1, 1, At, B1); PG8_BAR; PG8_SCHED;
.LBB0_1300:
	ds_read_b128 v[128:131], v156
	ds_read_b128 v[132:135], v156 offset:1024
	ds_read_b128 v[150:153], v156 offset:2048
	ds_read_b128 v[162:165], v156 offset:3072
	ds_read_b128 v[166:169], v157
	ds_read_b128 v[170:173], v157 offset:1024
	ds_read_b128 v[174:177], v157 offset:2048
	ds_read_b128 v[178:181], v157 offset:3072
	s_add_u32 s17, s62, 0xfffc0080
	s_addc_u32 s33, s63, -1
	s_cmp_eq_u32 s75, 12
	s_cselect_b32 s67, s39, s33
	s_cselect_b32 s66, s59, s17
	s_cselect_b32 s65, s37, s74
	s_cselect_b32 s64, s61, s73
	s_add_i32 m0, s53, 0xc000
	ds_read_b128 v[182:185], v158
	ds_read_b128 v[186:189], v158 offset:1024
	ds_read_b128 v[190:193], v158 offset:2048
	ds_read_b128 v[194:197], v158 offset:3072
	ds_read_b128 v[198:201], v158 offset:4096
	ds_read_b128 v[202:205], v158 offset:5120
	ds_read_b128 v[206:209], v158 offset:6144
	ds_read_b128 v[214:217], v158 offset:7168
	global_load_lds_dwordx4 v146, s[62:63]
	s_add_i32 m0, s53, 0xe000
	s_nop 0
	global_load_lds_dwordx4 v148, s[62:63]
	s_waitcnt vmcnt(8)
	s_waitcnt lgkmcnt(0)
	s_barrier
	s_setprio 1
	s_waitcnt lgkmcnt(0)
	v_mfma_f32_16x16x32_bf16 v[124:127], v[128:131], v[182:185], v[124:127]
	v_mfma_f32_16x16x32_bf16 v[120:123], v[150:153], v[182:185], v[120:123]
	v_mfma_f32_16x16x32_bf16 v[108:111], v[128:131], v[190:193], v[108:111]
	v_mfma_f32_16x16x32_bf16 v[104:107], v[150:153], v[190:193], v[104:107]
	v_mfma_f32_16x16x32_bf16 v[92:95], v[128:131], v[198:201], v[92:95]
	v_mfma_f32_16x16x32_bf16 v[88:91], v[150:153], v[198:201], v[88:91]
	v_mfma_f32_16x16x32_bf16 v[76:79], v[128:131], v[206:209], v[76:79]
	v_mfma_f32_16x16x32_bf16 v[72:75], v[150:153], v[206:209], v[72:75]
	v_mfma_f32_16x16x32_bf16 v[124:127], v[132:135], v[186:189], v[124:127]
	v_mfma_f32_16x16x32_bf16 v[120:123], v[162:165], v[186:189], v[120:123]
	v_mfma_f32_16x16x32_bf16 v[108:111], v[132:135], v[194:197], v[108:111]
	v_mfma_f32_16x16x32_bf16 v[104:107], v[162:165], v[194:197], v[104:107]
	v_mfma_f32_16x16x32_bf16 v[92:95], v[132:135], v[202:205], v[92:95]
	v_mfma_f32_16x16x32_bf16 v[88:91], v[162:165], v[202:205], v[88:91]
	v_mfma_f32_16x16x32_bf16 v[76:79], v[132:135], v[214:217], v[76:79]
	v_mfma_f32_16x16x32_bf16 v[72:75], v[162:165], v[214:217], v[72:75]
	s_setprio 0
	s_setprio 1
	v_mfma_f32_16x16x32_bf16 v[116:119], v[166:169], v[182:185], v[116:119]
	v_mfma_f32_16x16x32_bf16 v[112:115], v[174:177], v[182:185], v[112:115]
	v_mfma_f32_16x16x32_bf16 v[100:103], v[166:169], v[190:193], v[100:103]
	v_mfma_f32_16x16x32_bf16 v[96:99], v[174:177], v[190:193], v[96:99]
	v_mfma_f32_16x16x32_bf16 v[84:87], v[166:169], v[198:201], v[84:87]
	v_mfma_f32_16x16x32_bf16 v[80:83], v[174:177], v[198:201], v[80:83]
	v_mfma_f32_16x16x32_bf16 v[68:71], v[166:169], v[206:209], v[68:71]
	v_mfma_f32_16x16x32_bf16 v[64:67], v[174:177], v[206:209], v[64:67]
	v_mfma_f32_16x16x32_bf16 v[116:119], v[170:173], v[186:189], v[116:119]
	v_mfma_f32_16x16x32_bf16 v[112:115], v[178:181], v[186:189], v[112:115]
	v_mfma_f32_16x16x32_bf16 v[100:103], v[170:173], v[194:197], v[100:103]
	v_mfma_f32_16x16x32_bf16 v[96:99], v[178:181], v[194:197], v[96:99]
	v_mfma_f32_16x16x32_bf16 v[84:87], v[170:173], v[202:205], v[84:87]
	v_mfma_f32_16x16x32_bf16 v[80:83], v[178:181], v[202:205], v[80:83]
	v_mfma_f32_16x16x32_bf16 v[68:71], v[170:173], v[214:217], v[68:71]
	v_mfma_f32_16x16x32_bf16 v[64:67], v[178:181], v[214:217], v[64:67]
	s_setprio 0
	s_barrier
	s_add_i32 s17, s69, s16
	v_lshl_add_u64 v[210:211], s[64:65], 0, v[138:139]
	s_mov_b32 m0, s17
	ds_read_b128 v[182:185], v158 offset:16384
	ds_read_b128 v[186:189], v158 offset:17408
	ds_read_b128 v[190:193], v158 offset:18432
	ds_read_b128 v[194:197], v158 offset:19456
	ds_read_b128 v[198:201], v158 offset:20480
	ds_read_b128 v[202:205], v158 offset:21504
	ds_read_b128 v[206:209], v158 offset:22528
	ds_read_b128 v[214:217], v158 offset:23552
	global_load_lds_dwordx4 v[210:211], off
	s_add_i32 m0, s17, 0x2000
	s_add_u32 s56, s64, 0x40000
	v_lshl_add_u64 v[218:219], s[64:65], 0, v[142:143]
	s_addc_u32 s57, s65, 0
	s_add_i32 s17, s70, s16
	global_load_lds_dwordx4 v[218:219], off
	s_mov_b32 m0, s17
	v_lshl_add_u64 v[222:223], s[66:67], 0, v[140:141]
	global_load_lds_dwordx4 v138, s[56:57]
	s_add_i32 m0, s17, 0x2000
	s_nop 0
	global_load_lds_dwordx4 v142, s[56:57]
	v_lshl_add_u64 v[220:221], s[66:67], 0, v[136:137]
	s_mov_b32 m0, s53
	s_nop 0
	global_load_lds_dwordx4 v[220:221], off
	s_mov_b32 m0, s18
	s_nop 0
	global_load_lds_dwordx4 v[222:223], off
	s_waitcnt vmcnt(8)
	s_waitcnt lgkmcnt(0)
	s_barrier
; #define PG8_STAGE(bufoff, gbase, voff) do { _Pragma("unroll") for (int _i = 0; _i < 2; ++_i) \
;     __builtin_amdgcn_global_load_lds((const unsigned*)((const char*)(gbase) + (voff)[_i]), (PG8_LAS unsigned*)(lds + (bufoff) + ldsw + _i * 8192), 16, 0, 0); } while (0)
; #define PG8_LDA(dst, b, h) do { _Pragma("unroll") for (int m = 0; m < 4; ++m) _Pragma("unroll") for (int k = 0; k < 2; ++k) dst[m][k] = *(const PG8_LAS bf16x8*)(lds + PG8_SA(b, h) + aoff + m * 2048 + k * 1024); } while (0)
; #define PG8_LDB(dst, b, h) do { _Pragma("unroll") for (int n = 0; n < 2; ++n) _Pragma("unroll") for (int k = 0; k < 2; ++k) dst[n][k] = *(const PG8_LAS bf16x8*)(lds + PG8_SB(b, h) + boff + n * 2048 + k * 1024); } while (0)
; #define PG8_MMA(ai, bj, At, Bt) do { __builtin_amdgcn_s_setprio(1); _Pragma("unroll") for (int m = 0; m < 4; ++m) _Pragma("unroll") for (int n = 0; n < 2; ++n) _Pragma("unroll") for (int k = 0; k < 2; ++k) \
;     acc[ai][bj][m][n] = __builtin_amdgcn_mfma_f32_16x16x32_bf16(Bt[n][k], At[m][k], acc[ai][bj][m][n], 0, 0, 0); __builtin_amdgcn_s_setprio(0); } while (0)
; #define PG8_WAIT_V(n) asm volatile("s_waitcnt vmcnt(" #n ")" ::: "memory")
; #define PG8_WAIT_L(n) asm volatile("s_waitcnt lgkmcnt(" #n ")" ::: "memory")
; #define PG8_BAR __builtin_amdgcn_s_barrier()
; #define PG8_SCHED __builtin_amdgcn_sched_barrier(0)
; template <class Epi, class Sched>
; DI void gemm_phase(PG8_LAS unsigned char* lds, const Gemm g, const Sched& S, const Epi& E) {
;     ...
;       PG8_WAIT_V(8); PG8_WAIT_L(0); PG8_BAR; PG8_MMA(1, 0, At, B0); PG8_MMA(1, 1, At, B1); PG8_BAR; PG8_SCHED;
;       PG8_LDB(B0, 1, 0); PG8_LDB(B1, 1, 1); PG8_SCHED; PG8_LDA(At, 1, 0); PG8_STAGE(PG8_SA(0, 1), a2 + hstepA, voffA);
;       PG8_WAIT_V(8); PG8_WAIT_L(0); PG8_BAR; PG8_MMA(0, 0, At, B0); PG8_MMA(0, 1, At, B1); PG8_BAR; PG8_SCHED;
	s_setprio 1
	s_waitcnt lgkmcnt(0)
	v_mfma_f32_16x16x32_bf16 v[60:63], v[128:131], v[182:185], v[60:63]
	v_mfma_f32_16x16x32_bf16 v[56:59], v[150:153], v[182:185], v[56:59]
	v_mfma_f32_16x16x32_bf16 v[44:47], v[128:131], v[190:193], v[44:47]
	v_mfma_f32_16x16x32_bf16 v[40:43], v[150:153], v[190:193], v[40:43]
	v_mfma_f32_16x16x32_bf16 v[28:31], v[128:131], v[198:201], v[28:31]
	v_mfma_f32_16x16x32_bf16 v[24:27], v[150:153], v[198:201], v[24:27]
	v_mfma_f32_16x16x32_bf16 v[12:15], v[128:131], v[206:209], v[12:15]
	v_mfma_f32_16x16x32_bf16 v[8:11], v[150:153], v[206:209], v[8:11]
	v_mfma_f32_16x16x32_bf16 v[60:63], v[132:135], v[186:189], v[60:63]
	v_mfma_f32_16x16x32_bf16 v[56:59], v[162:165], v[186:189], v[56:59]
	v_mfma_f32_16x16x32_bf16 v[44:47], v[132:135], v[194:197], v[44:47]
	v_mfma_f32_16x16x32_bf16 v[40:43], v[162:165], v[194:197], v[40:43]
	v_mfma_f32_16x16x32_bf16 v[28:31], v[132:135], v[202:205], v[28:31]
	v_mfma_f32_16x16x32_bf16 v[24:27], v[162:165], v[202:205], v[24:27]
	v_mfma_f32_16x16x32_bf16 v[12:15], v[132:135], v[214:217], v[12:15]
	v_mfma_f32_16x16x32_bf16 v[8:11], v[162:165], v[214:217], v[8:11]
	s_setprio 0
	s_setprio 1
	v_mfma_f32_16x16x32_bf16 v[52:55], v[166:169], v[182:185], v[52:55]
	v_mfma_f32_16x16x32_bf16 v[48:51], v[174:177], v[182:185], v[48:51]
	v_mfma_f32_16x16x32_bf16 v[36:39], v[166:169], v[190:193], v[36:39]
	v_mfma_f32_16x16x32_bf16 v[32:35], v[174:177], v[190:193], v[32:35]
	v_mfma_f32_16x16x32_bf16 v[20:23], v[166:169], v[198:201], v[20:23]
	v_mfma_f32_16x16x32_bf16 v[16:19], v[174:177], v[198:201], v[16:19]
	v_mfma_f32_16x16x32_bf16 v[4:7], v[166:169], v[206:209], v[4:7]
	v_mfma_f32_16x16x32_bf16 v[0:3], v[174:177], v[206:209], v[0:3]
	v_mfma_f32_16x16x32_bf16 v[52:55], v[170:173], v[186:189], v[52:55]
	v_mfma_f32_16x16x32_bf16 v[48:51], v[178:181], v[186:189], v[48:51]
	v_mfma_f32_16x16x32_bf16 v[36:39], v[170:173], v[194:197], v[36:39]
	v_mfma_f32_16x16x32_bf16 v[32:35], v[178:181], v[194:197], v[32:35]
	v_mfma_f32_16x16x32_bf16 v[20:23], v[170:173], v[202:205], v[20:23]
	v_mfma_f32_16x16x32_bf16 v[16:19], v[178:181], v[202:205], v[16:19]
	v_mfma_f32_16x16x32_bf16 v[4:7], v[170:173], v[214:217], v[4:7]
	v_mfma_f32_16x16x32_bf16 v[0:3], v[178:181], v[214:217], v[0:3]
	s_setprio 0
	s_barrier
	s_mov_b32 s17, 0x18000
	s_addk_i32 s17, 0x110
	v_add_u32_e32 v161, s17, v155
	ds_read_b128 v[128:131], v161
	ds_read_b128 v[132:135], v161 offset:1024
	ds_read_b128 v[150:153], v161 offset:2048
	ds_read_b128 v[162:165], v161 offset:3072
	ds_read_b128 v[166:169], v160
	ds_read_b128 v[170:173], v160 offset:1024
	ds_read_b128 v[174:177], v160 offset:2048
	ds_read_b128 v[178:181], v160 offset:3072
	s_add_u32 s56, s66, 0x40000
	s_addc_u32 s57, s67, 0
	s_mov_b32 m0, s19
	ds_read_b128 v[182:185], v158 offset:32768
	ds_read_b128 v[186:189], v158 offset:33792
	ds_read_b128 v[190:193], v158 offset:34816
	ds_read_b128 v[194:197], v158 offset:35840
	ds_read_b128 v[198:201], v158 offset:36864
	ds_read_b128 v[202:205], v158 offset:37888
	ds_read_b128 v[206:209], v158 offset:38912
	ds_read_b128 v[214:217], v158 offset:39936
	global_load_lds_dwordx4 v136, s[56:57]
	s_mov_b32 m0, s54
	s_nop 0
	global_load_lds_dwordx4 v140, s[56:57]
	s_waitcnt vmcnt(8)
	s_waitcnt lgkmcnt(0)
	s_barrier
	s_setprio 1
	s_waitcnt lgkmcnt(0)
	v_mfma_f32_16x16x32_bf16 v[124:127], v[128:131], v[182:185], v[124:127]
	v_mfma_f32_16x16x32_bf16 v[120:123], v[150:153], v[182:185], v[120:123]
	v_mfma_f32_16x16x32_bf16 v[108:111], v[128:131], v[190:193], v[108:111]
	v_mfma_f32_16x16x32_bf16 v[104:107], v[150:153], v[190:193], v[104:107]
	v_mfma_f32_16x16x32_bf16 v[92:95], v[128:131], v[198:201], v[92:95]
	v_mfma_f32_16x16x32_bf16 v[88:91], v[150:153], v[198:201], v[88:91]
	v_mfma_f32_16x16x32_bf16 v[76:79], v[128:131], v[206:209], v[76:79]
	v_mfma_f32_16x16x32_bf16 v[72:75], v[150:153], v[206:209], v[72:75]
	v_mfma_f32_16x16x32_bf16 v[124:127], v[132:135], v[186:189], v[124:127]
	v_mfma_f32_16x16x32_bf16 v[120:123], v[162:165], v[186:189], v[120:123]
	v_mfma_f32_16x16x32_bf16 v[108:111], v[132:135], v[194:197], v[108:111]
	v_mfma_f32_16x16x32_bf16 v[104:107], v[162:165], v[194:197], v[104:107]
	v_mfma_f32_16x16x32_bf16 v[92:95], v[132:135], v[202:205], v[92:95]
	v_mfma_f32_16x16x32_bf16 v[88:91], v[162:165], v[202:205], v[88:91]
	v_mfma_f32_16x16x32_bf16 v[76:79], v[132:135], v[214:217], v[76:79]
	v_mfma_f32_16x16x32_bf16 v[72:75], v[162:165], v[214:217], v[72:75]
	s_setprio 0
	s_setprio 1
	v_mfma_f32_16x16x32_bf16 v[116:119], v[166:169], v[182:185], v[116:119]
	v_mfma_f32_16x16x32_bf16 v[112:115], v[174:177], v[182:185], v[112:115]
	v_mfma_f32_16x16x32_bf16 v[100:103], v[166:169], v[190:193], v[100:103]
	v_mfma_f32_16x16x32_bf16 v[96:99], v[174:177], v[190:193], v[96:99]
	v_mfma_f32_16x16x32_bf16 v[84:87], v[166:169], v[198:201], v[84:87]
	v_mfma_f32_16x16x32_bf16 v[80:83], v[174:177], v[198:201], v[80:83]
	v_mfma_f32_16x16x32_bf16 v[68:71], v[166:169], v[206:209], v[68:71]
	v_mfma_f32_16x16x32_bf16 v[64:67], v[174:177], v[206:209], v[64:67]
	v_mfma_f32_16x16x32_bf16 v[116:119], v[170:173], v[186:189], v[116:119]
	v_mfma_f32_16x16x32_bf16 v[112:115], v[178:181], v[186:189], v[112:115]
	v_mfma_f32_16x16x32_bf16 v[100:103], v[170:173], v[194:197], v[100:103]
	v_mfma_f32_16x16x32_bf16 v[96:99], v[178:181], v[194:197], v[96:99]
	v_mfma_f32_16x16x32_bf16 v[84:87], v[170:173], v[202:205], v[84:87]
	v_mfma_f32_16x16x32_bf16 v[80:83], v[178:181], v[202:205], v[80:83]
	v_mfma_f32_16x16x32_bf16 v[68:71], v[170:173], v[214:217], v[68:71]
	v_mfma_f32_16x16x32_bf16 v[64:67], v[178:181], v[214:217], v[64:67]
	s_setprio 0
	s_barrier
; #define PG8_STAGE(bufoff, gbase, voff) do { _Pragma("unroll") for (int _i = 0; _i < 2; ++_i) \
;     __builtin_amdgcn_global_load_lds((const unsigned*)((const char*)(gbase) + (voff)[_i]), (PG8_LAS unsigned*)(lds + (bufoff) + ldsw + _i * 8192), 16, 0, 0); } while (0)
; #define PG8_LDA(dst, b, h) do { _Pragma("unroll") for (int m = 0; m < 4; ++m) _Pragma("unroll") for (int k = 0; k < 2; ++k) dst[m][k] = *(const PG8_LAS bf16x8*)(lds + PG8_SA(b, h) + aoff + m * 2048 + k * 1024); } while (0)
; #define PG8_MMA(ai, bj, At, Bt) do { __builtin_amdgcn_s_setprio(1); _Pragma("unroll") for (int m = 0; m < 4; ++m) _Pragma("unroll") for (int n = 0; n < 2; ++n) _Pragma("unroll") for (int k = 0; k < 2; ++k) \
;     acc[ai][bj][m][n] = __builtin_amdgcn_mfma_f32_16x16x32_bf16(Bt[n][k], At[m][k], acc[ai][bj][m][n], 0, 0, 0); __builtin_amdgcn_s_setprio(0); } while (0)
; #define PG8_WAIT_V(n) asm volatile("s_waitcnt vmcnt(" #n ")" ::: "memory")
; #define PG8_WAIT_L(n) asm volatile("s_waitcnt lgkmcnt(" #n ")" ::: "memory")
; #define PG8_BAR __builtin_amdgcn_s_barrier()
; #define PG8_SCHED __builtin_amdgcn_sched_barrier(0)
;   DI void operator()(const f32x4 (&acc)[2][2][4][2], const Unit& u, int wr, int wc, int fr, int fq) const {
;     const int row0 = u.pm * BM + wr * 64 + fr;
;     const size_t base = (size_t)row0 * DM + u.pn * BM + wc * 32 + 8 * fq;
;     f32x4 xv[2][4];
;     u32x4 xh[2][2];
;     ...
;     RES_LD(0)
; #pragma unroll
;     for (int i = 0; i < 8; ++i) {
;       const int ai = i >> 2, m = i & 3;
;       if (i + 1 < 8) RES_LD(i + 1)
; template <class Epi, class Sched>
; DI void gemm_phase(PG8_LAS unsigned char* lds, const Gemm g, const Sched& S, const Epi& E) {
;     ...
;       PG8_LDA(At, 1, 1); PG8_STAGE(PG8_SB(1, 0), b3, voffB); PG8_STAGE(PG8_SB(1, 1), b3 + hstepB, voffB); PG8_STAGE(PG8_SA(1, 0), a3, voffA);
;       PG8_WAIT_V(8); PG8_WAIT_L(0); PG8_BAR; PG8_MMA(1, 0, At, B0); PG8_MMA(1, 1, At, B1); PG8_BAR; PG8_SCHED;
;     }
;     if (wr == 0) PG8_BAR;
	s_add_i32 s17, s17, s16
	v_lshl_add_u64 v[210:211], v[210:211], 0, s[6:7]
	s_mov_b32 m0, s17
	ds_read_b128 v[182:185], v158 offset:49152
	ds_read_b128 v[186:189], v158 offset:50176
	ds_read_b128 v[190:193], v158 offset:51200
	ds_read_b128 v[194:197], v158 offset:52224
	ds_read_b128 v[198:201], v158 offset:53248
	ds_read_b128 v[202:205], v158 offset:54272
	ds_read_b128 v[206:209], v158 offset:55296
	ds_read_b128 v[214:217], v158 offset:56320
	global_load_lds_dwordx4 v[210:211], off
	s_add_i32 m0, s17, 0x2000
	s_add_u32 s56, s64, 0x40080
	v_lshl_add_u64 v[210:211], v[218:219], 0, s[6:7]
	s_addc_u32 s57, s65, 0
	s_add_i32 s17, s71, s16
	global_load_lds_dwordx4 v[210:211], off
	s_mov_b32 m0, s17
	s_nop 0
	global_load_lds_dwordx4 v138, s[56:57]
	s_add_i32 m0, s17, 0x2000
	s_nop 0
	global_load_lds_dwordx4 v142, s[56:57]
	v_lshl_add_u64 v[210:211], v[220:221], 0, s[6:7]
	s_mov_b32 m0, s5
	s_nop 0
	global_load_lds_dwordx4 v[210:211], off
	v_lshl_add_u64 v[210:211], v[222:223], 0, s[6:7]
	s_mov_b32 m0, s55
	s_nop 0
	global_load_lds_dwordx4 v[210:211], off
	s_waitcnt vmcnt(8)
	s_waitcnt lgkmcnt(0)
	s_barrier
	s_setprio 1
	s_waitcnt lgkmcnt(0)
	v_mfma_f32_16x16x32_bf16 v[60:63], v[128:131], v[182:185], v[60:63]
	v_mfma_f32_16x16x32_bf16 v[56:59], v[150:153], v[182:185], v[56:59]
	v_mfma_f32_16x16x32_bf16 v[44:47], v[128:131], v[190:193], v[44:47]
	v_mfma_f32_16x16x32_bf16 v[40:43], v[150:153], v[190:193], v[40:43]
	v_mfma_f32_16x16x32_bf16 v[28:31], v[128:131], v[198:201], v[28:31]
	v_mfma_f32_16x16x32_bf16 v[24:27], v[150:153], v[198:201], v[24:27]
	v_mfma_f32_16x16x32_bf16 v[12:15], v[128:131], v[206:209], v[12:15]
	v_mfma_f32_16x16x32_bf16 v[8:11], v[150:153], v[206:209], v[8:11]
	v_mfma_f32_16x16x32_bf16 v[60:63], v[132:135], v[186:189], v[60:63]
	v_mfma_f32_16x16x32_bf16 v[56:59], v[162:165], v[186:189], v[56:59]
	v_mfma_f32_16x16x32_bf16 v[44:47], v[132:135], v[194:197], v[44:47]
	v_mfma_f32_16x16x32_bf16 v[40:43], v[162:165], v[194:197], v[40:43]
	v_mfma_f32_16x16x32_bf16 v[28:31], v[132:135], v[202:205], v[28:31]
	v_mfma_f32_16x16x32_bf16 v[24:27], v[162:165], v[202:205], v[24:27]
	v_mfma_f32_16x16x32_bf16 v[12:15], v[132:135], v[214:217], v[12:15]
	v_mfma_f32_16x16x32_bf16 v[8:11], v[162:165], v[214:217], v[8:11]
	s_setprio 0
	s_setprio 1
	v_mfma_f32_16x16x32_bf16 v[52:55], v[166:169], v[182:185], v[52:55]
	v_mfma_f32_16x16x32_bf16 v[48:51], v[174:177], v[182:185], v[48:51]
	v_mfma_f32_16x16x32_bf16 v[36:39], v[166:169], v[190:193], v[36:39]
	v_mfma_f32_16x16x32_bf16 v[32:35], v[174:177], v[190:193], v[32:35]
	v_mfma_f32_16x16x32_bf16 v[20:23], v[166:169], v[198:201], v[20:23]
	v_mfma_f32_16x16x32_bf16 v[16:19], v[174:177], v[198:201], v[16:19]
	v_mfma_f32_16x16x32_bf16 v[4:7], v[166:169], v[206:209], v[4:7]
	v_mfma_f32_16x16x32_bf16 v[0:3], v[174:177], v[206:209], v[0:3]
	v_mfma_f32_16x16x32_bf16 v[52:55], v[170:173], v[186:189], v[52:55]
	v_mfma_f32_16x16x32_bf16 v[48:51], v[178:181], v[186:189], v[48:51]
	v_mfma_f32_16x16x32_bf16 v[36:39], v[170:173], v[194:197], v[36:39]
	v_mfma_f32_16x16x32_bf16 v[32:35], v[178:181], v[194:197], v[32:35]
	v_mfma_f32_16x16x32_bf16 v[20:23], v[170:173], v[202:205], v[20:23]
	v_mfma_f32_16x16x32_bf16 v[16:19], v[178:181], v[202:205], v[16:19]
	v_mfma_f32_16x16x32_bf16 v[4:7], v[170:173], v[214:217], v[4:7]
	v_mfma_f32_16x16x32_bf16 v[0:3], v[178:181], v[214:217], v[0:3]
	s_setprio 0
	s_barrier
	s_add_i32 s75, s75, 2
	s_add_u32 s62, s62, 0x100
	s_addc_u32 s63, s63, 0
	s_add_u32 s73, s73, 0x100
	s_addc_u32 s74, s74, 0
	s_cmp_gt_u32 s75, 13
	s_cbranch_scc0 .LBB0_1300
	v_lshl_add_u32 v152, s60, 8, v154
	v_ashrrev_i32_e32 v153, 31, v152
	s_lshl_b32 s56, s58, 8
	v_lshlrev_b64 v[128:129], 11, v[152:153]
	s_ashr_i32 s57, s56, 31
	v_lshl_add_u64 v[128:129], s[50:51], 0, v[128:129]
	v_lshl_add_u64 v[128:129], s[56:57], 1, v[128:129]
	v_lshl_add_u64 v[128:129], v[128:129], 0, s[10:11]
	v_lshl_add_u64 v[150:151], v[128:129], 0, v[144:145]
	s_mov_b32 s17, 0x8000
	v_add_co_u32_e32 v128, vcc, s17, v150
	global_load_dwordx4 v[164:167], v[150:151], off
	global_load_dwordx4 v[168:171], v[150:151], off offset:256
	v_addc_co_u32_e32 v129, vcc, 0, v151, vcc
	global_load_dwordx4 v[132:135], v[128:129], off
	s_nop 0
	global_load_dwordx4 v[128:131], v[128:129], off offset:256
	s_and_b64 vcc, exec, s[8:9]
	s_cbranch_vccz .LBB0_1303
	s_barrier

; #define PG8_STAGE(bufoff, gbase, voff) do { _Pragma("unroll") for (int _i = 0; _i < 2; ++_i) \
;     __builtin_amdgcn_global_load_lds((const unsigned*)((const char*)(gbase) + (voff)[_i]), (PG8_LAS unsigned*)(lds + (bufoff) + ldsw + _i * 8192), 16, 0, 0); } while (0)
; #define PG8_LDA(dst, b, h) do { _Pragma("unroll") for (int m = 0; m < 4; ++m) _Pragma("unroll") for (int k = 0; k < 2; ++k) dst[m][k] = *(const PG8_LAS bf16x8*)(lds + PG8_SA(b, h) + aoff + m * 2048 + k * 1024); } while (0)
; #define PG8_LDB(dst, b, h) do { _Pragma("unroll") for (int n = 0; n < 2; ++n) _Pragma("unroll") for (int k = 0; k < 2; ++k) dst[n][k] = *(const PG8_LAS bf16x8*)(lds + PG8_SB(b, h) + boff + n * 2048 + k * 1024); } while (0)
; #define PG8_MMA(ai, bj, At, Bt) do { __builtin_amdgcn_s_setprio(1); _Pragma("unroll") for (int m = 0; m < 4; ++m) _Pragma("unroll") for (int n = 0; n < 2; ++n) _Pragma("unroll") for (int k = 0; k < 2; ++k) \
;     acc[ai][bj][m][n] = __builtin_amdgcn_mfma_f32_16x16x32_bf16(Bt[n][k], At[m][k], acc[ai][bj][m][n], 0, 0, 0); __builtin_amdgcn_s_setprio(0); } while (0)
; #define PG8_WAIT_V(n) asm volatile("s_waitcnt vmcnt(" #n ")" ::: "memory")
; #define PG8_WAIT_L(n) asm volatile("s_waitcnt lgkmcnt(" #n ")" ::: "memory")
; #define PG8_BAR __builtin_amdgcn_s_barrier()
; #define PG8_SCHED __builtin_amdgcn_sched_barrier(0)
; template <class Epi, class Sched>
; DI void gemm_phase(PG8_LAS unsigned char* lds, const Gemm g, const Sched& S, const Epi& E) {
;     ...
;     for (int t = 0; t < nt; t += 2) {
;       const bool last = (t == nt - 2);
;       const char* a1 = cA + (size_t)(t + 1) * kstep;
;       const char* a2 = last ? nA : cA + (size_t)(t + 2) * kstep; const char* b2 = last ? nB : cB + (size_t)(t + 2) * kstep;
;       const char* a3 = a2 + kstep; const char* b3 = b2 + kstep;
;       PG8_LDB(B0, 0, 0); PG8_LDB(B1, 0, 1); PG8_SCHED; PG8_LDA(At, 0, 0); PG8_STAGE(PG8_SA(1, 1), a1 + hstepA, voffA);
;       PG8_WAIT_V(8); PG8_WAIT_L(0); PG8_BAR; PG8_MMA(0, 0, At, B0); PG8_MMA(0, 1, At, B1); PG8_BAR; PG8_SCHED;
;       PG8_LDA(At, 0, 1); PG8_STAGE(PG8_SB(0, 0), b2, voffB); PG8_STAGE(PG8_SB(0, 1), b2 + hstepB, voffB); PG8_STAGE(PG8_SA(0, 0), a2, voffA);
;       PG8_WAIT_V(8); PG8_WAIT_L(0); PG8_BAR; PG8_MMA(1, 0, At, B0); PG8_MMA(1, 1, At, B1); PG8_BAR; PG8_SCHED;
.LBB0_1384:
	ds_read_b128 v[144:147], v155
	ds_read_b128 v[156:159], v155 offset:1024
	ds_read_b128 v[174:177], v155 offset:2048
	ds_read_b128 v[178:181], v155 offset:3072
	ds_read_b128 v[182:185], v161
	ds_read_b128 v[186:189], v161 offset:1024
	ds_read_b128 v[190:193], v161 offset:2048
	ds_read_b128 v[194:197], v161 offset:3072
	s_add_u32 s30, s2, 0xfffc0080
	s_addc_u32 s31, s3, -1
	s_cmp_eq_u32 s55, 12
	s_cselect_b32 s35, s1, s31
	s_cselect_b32 s34, s23, s30
	s_cselect_b32 s31, s21, s54
	s_cselect_b32 s30, s49, s53
	s_add_i32 m0, s17, 0xc000
	ds_read_b128 v[198:201], v165
	ds_read_b128 v[202:205], v165 offset:1024
	ds_read_b128 v[206:209], v165 offset:2048
	ds_read_b128 v[214:217], v165 offset:3072
	ds_read_b128 v[218:221], v165 offset:4096
	ds_read_b128 v[222:225], v165 offset:5120
	ds_read_b128 v[226:229], v165 offset:6144
	ds_read_b128 v[230:233], v165 offset:7168
	global_load_lds_dwordx4 v140, s[2:3]
	s_add_i32 m0, s17, 0xe000
	s_nop 0
	global_load_lds_dwordx4 v142, s[2:3]
	s_waitcnt vmcnt(8)
	s_waitcnt lgkmcnt(0)
	s_barrier
	s_setprio 1
	s_waitcnt lgkmcnt(0)
	v_mfma_f32_16x16x32_bf16 v[124:127], v[144:147], v[198:201], v[124:127]
	v_mfma_f32_16x16x32_bf16 v[120:123], v[174:177], v[198:201], v[120:123]
	v_mfma_f32_16x16x32_bf16 v[108:111], v[144:147], v[206:209], v[108:111]
	v_mfma_f32_16x16x32_bf16 v[104:107], v[174:177], v[206:209], v[104:107]
	v_mfma_f32_16x16x32_bf16 v[92:95], v[144:147], v[218:221], v[92:95]
	v_mfma_f32_16x16x32_bf16 v[88:91], v[174:177], v[218:221], v[88:91]
	v_mfma_f32_16x16x32_bf16 v[76:79], v[144:147], v[226:229], v[76:79]
	v_mfma_f32_16x16x32_bf16 v[72:75], v[174:177], v[226:229], v[72:75]
	v_mfma_f32_16x16x32_bf16 v[124:127], v[156:159], v[202:205], v[124:127]
	v_mfma_f32_16x16x32_bf16 v[120:123], v[178:181], v[202:205], v[120:123]
	v_mfma_f32_16x16x32_bf16 v[108:111], v[156:159], v[214:217], v[108:111]
	v_mfma_f32_16x16x32_bf16 v[104:107], v[178:181], v[214:217], v[104:107]
	v_mfma_f32_16x16x32_bf16 v[92:95], v[156:159], v[222:225], v[92:95]
	v_mfma_f32_16x16x32_bf16 v[88:91], v[178:181], v[222:225], v[88:91]
	v_mfma_f32_16x16x32_bf16 v[76:79], v[156:159], v[230:233], v[76:79]
	v_mfma_f32_16x16x32_bf16 v[72:75], v[178:181], v[230:233], v[72:75]
	s_setprio 0
	s_setprio 1
	v_mfma_f32_16x16x32_bf16 v[116:119], v[182:185], v[198:201], v[116:119]
	v_mfma_f32_16x16x32_bf16 v[112:115], v[190:193], v[198:201], v[112:115]
	v_mfma_f32_16x16x32_bf16 v[100:103], v[182:185], v[206:209], v[100:103]
	v_mfma_f32_16x16x32_bf16 v[96:99], v[190:193], v[206:209], v[96:99]
	v_mfma_f32_16x16x32_bf16 v[84:87], v[182:185], v[218:221], v[84:87]
	v_mfma_f32_16x16x32_bf16 v[80:83], v[190:193], v[218:221], v[80:83]
	v_mfma_f32_16x16x32_bf16 v[68:71], v[182:185], v[226:229], v[68:71]
	v_mfma_f32_16x16x32_bf16 v[64:67], v[190:193], v[226:229], v[64:67]
	v_mfma_f32_16x16x32_bf16 v[116:119], v[186:189], v[202:205], v[116:119]
	v_mfma_f32_16x16x32_bf16 v[112:115], v[194:197], v[202:205], v[112:115]
	v_mfma_f32_16x16x32_bf16 v[100:103], v[186:189], v[214:217], v[100:103]
	v_mfma_f32_16x16x32_bf16 v[96:99], v[194:197], v[214:217], v[96:99]
	v_mfma_f32_16x16x32_bf16 v[84:87], v[186:189], v[222:225], v[84:87]
	v_mfma_f32_16x16x32_bf16 v[80:83], v[194:197], v[222:225], v[80:83]
	v_mfma_f32_16x16x32_bf16 v[68:71], v[186:189], v[230:233], v[68:71]
	v_mfma_f32_16x16x32_bf16 v[64:67], v[194:197], v[230:233], v[64:67]
	s_setprio 0
	s_barrier
	s_add_i32 s56, s37, s15
	v_lshl_add_u64 v[148:149], s[30:31], 0, v[132:133]
	s_mov_b32 m0, s56
	ds_read_b128 v[198:201], v165 offset:16384
	ds_read_b128 v[202:205], v165 offset:17408
	ds_read_b128 v[206:209], v165 offset:18432
	ds_read_b128 v[214:217], v165 offset:19456
	ds_read_b128 v[218:221], v165 offset:20480
	ds_read_b128 v[222:225], v165 offset:21504
	ds_read_b128 v[226:229], v165 offset:22528
	ds_read_b128 v[230:233], v165 offset:23552
	global_load_lds_dwordx4 v[148:149], off
	s_add_i32 m0, s56, 0x2000
	s_add_u32 s56, s30, 0x40000
	v_lshl_add_u64 v[152:153], s[30:31], 0, v[128:129]
	s_addc_u32 s57, s31, 0
	s_add_i32 s58, s38, s15
	global_load_lds_dwordx4 v[152:153], off
	s_mov_b32 m0, s58
	v_lshl_add_u64 v[166:167], s[34:35], 0, v[130:131]
	global_load_lds_dwordx4 v132, s[56:57]
	s_add_i32 m0, s58, 0x2000
	s_nop 0
	global_load_lds_dwordx4 v128, s[56:57]
	v_lshl_add_u64 v[162:163], s[34:35], 0, v[134:135]
	s_mov_b32 m0, s17
	s_nop 0
	global_load_lds_dwordx4 v[162:163], off
	s_mov_b32 m0, s4
	s_nop 0
	global_load_lds_dwordx4 v[166:167], off
	s_waitcnt vmcnt(8)
	s_waitcnt lgkmcnt(0)
	s_barrier
; #define PG8_STAGE(bufoff, gbase, voff) do { _Pragma("unroll") for (int _i = 0; _i < 2; ++_i) \
;     __builtin_amdgcn_global_load_lds((const unsigned*)((const char*)(gbase) + (voff)[_i]), (PG8_LAS unsigned*)(lds + (bufoff) + ldsw + _i * 8192), 16, 0, 0); } while (0)
; #define PG8_LDA(dst, b, h) do { _Pragma("unroll") for (int m = 0; m < 4; ++m) _Pragma("unroll") for (int k = 0; k < 2; ++k) dst[m][k] = *(const PG8_LAS bf16x8*)(lds + PG8_SA(b, h) + aoff + m * 2048 + k * 1024); } while (0)
; #define PG8_LDB(dst, b, h) do { _Pragma("unroll") for (int n = 0; n < 2; ++n) _Pragma("unroll") for (int k = 0; k < 2; ++k) dst[n][k] = *(const PG8_LAS bf16x8*)(lds + PG8_SB(b, h) + boff + n * 2048 + k * 1024); } while (0)
; #define PG8_MMA(ai, bj, At, Bt) do { __builtin_amdgcn_s_setprio(1); _Pragma("unroll") for (int m = 0; m < 4; ++m) _Pragma("unroll") for (int n = 0; n < 2; ++n) _Pragma("unroll") for (int k = 0; k < 2; ++k) \
;     acc[ai][bj][m][n] = __builtin_amdgcn_mfma_f32_16x16x32_bf16(Bt[n][k], At[m][k], acc[ai][bj][m][n], 0, 0, 0); __builtin_amdgcn_s_setprio(0); } while (0)
; #define PG8_WAIT_V(n) asm volatile("s_waitcnt vmcnt(" #n ")" ::: "memory")
; #define PG8_WAIT_L(n) asm volatile("s_waitcnt lgkmcnt(" #n ")" ::: "memory")
; #define PG8_BAR __builtin_amdgcn_s_barrier()
; #define PG8_SCHED __builtin_amdgcn_sched_barrier(0)
; template <class Epi, class Sched>
; DI void gemm_phase(PG8_LAS unsigned char* lds, const Gemm g, const Sched& S, const Epi& E) {
;     ...
;       PG8_WAIT_V(8); PG8_WAIT_L(0); PG8_BAR; PG8_MMA(1, 0, At, B0); PG8_MMA(1, 1, At, B1); PG8_BAR; PG8_SCHED;
;       PG8_LDB(B0, 1, 0); PG8_LDB(B1, 1, 1); PG8_SCHED; PG8_LDA(At, 1, 0); PG8_STAGE(PG8_SA(0, 1), a2 + hstepA, voffA);
;       PG8_WAIT_V(8); PG8_WAIT_L(0); PG8_BAR; PG8_MMA(0, 0, At, B0); PG8_MMA(0, 1, At, B1); PG8_BAR; PG8_SCHED;
	s_setprio 1
	s_waitcnt lgkmcnt(0)
	v_mfma_f32_16x16x32_bf16 v[60:63], v[144:147], v[198:201], v[60:63]
	v_mfma_f32_16x16x32_bf16 v[56:59], v[174:177], v[198:201], v[56:59]
	v_mfma_f32_16x16x32_bf16 v[44:47], v[144:147], v[206:209], v[44:47]
	v_mfma_f32_16x16x32_bf16 v[40:43], v[174:177], v[206:209], v[40:43]
	v_mfma_f32_16x16x32_bf16 v[28:31], v[144:147], v[218:221], v[28:31]
	v_mfma_f32_16x16x32_bf16 v[24:27], v[174:177], v[218:221], v[24:27]
	v_mfma_f32_16x16x32_bf16 v[12:15], v[144:147], v[226:229], v[12:15]
	v_mfma_f32_16x16x32_bf16 v[8:11], v[174:177], v[226:229], v[8:11]
	v_mfma_f32_16x16x32_bf16 v[60:63], v[156:159], v[202:205], v[60:63]
	v_mfma_f32_16x16x32_bf16 v[56:59], v[178:181], v[202:205], v[56:59]
	v_mfma_f32_16x16x32_bf16 v[44:47], v[156:159], v[214:217], v[44:47]
	v_mfma_f32_16x16x32_bf16 v[40:43], v[178:181], v[214:217], v[40:43]
	v_mfma_f32_16x16x32_bf16 v[28:31], v[156:159], v[222:225], v[28:31]
	v_mfma_f32_16x16x32_bf16 v[24:27], v[178:181], v[222:225], v[24:27]
	v_mfma_f32_16x16x32_bf16 v[12:15], v[156:159], v[230:233], v[12:15]
	v_mfma_f32_16x16x32_bf16 v[8:11], v[178:181], v[230:233], v[8:11]
	s_setprio 0
	s_setprio 1
	v_mfma_f32_16x16x32_bf16 v[52:55], v[182:185], v[198:201], v[52:55]
	v_mfma_f32_16x16x32_bf16 v[48:51], v[190:193], v[198:201], v[48:51]
	v_mfma_f32_16x16x32_bf16 v[36:39], v[182:185], v[206:209], v[36:39]
	v_mfma_f32_16x16x32_bf16 v[32:35], v[190:193], v[206:209], v[32:35]
	v_mfma_f32_16x16x32_bf16 v[20:23], v[182:185], v[218:221], v[20:23]
	v_mfma_f32_16x16x32_bf16 v[16:19], v[190:193], v[218:221], v[16:19]
	v_mfma_f32_16x16x32_bf16 v[4:7], v[182:185], v[226:229], v[4:7]
	v_mfma_f32_16x16x32_bf16 v[0:3], v[190:193], v[226:229], v[0:3]
	v_mfma_f32_16x16x32_bf16 v[52:55], v[186:189], v[202:205], v[52:55]
	v_mfma_f32_16x16x32_bf16 v[48:51], v[194:197], v[202:205], v[48:51]
	v_mfma_f32_16x16x32_bf16 v[36:39], v[186:189], v[214:217], v[36:39]
	v_mfma_f32_16x16x32_bf16 v[32:35], v[194:197], v[214:217], v[32:35]
	v_mfma_f32_16x16x32_bf16 v[20:23], v[186:189], v[222:225], v[20:23]
	v_mfma_f32_16x16x32_bf16 v[16:19], v[194:197], v[222:225], v[16:19]
	v_mfma_f32_16x16x32_bf16 v[4:7], v[186:189], v[230:233], v[4:7]
	v_mfma_f32_16x16x32_bf16 v[0:3], v[194:197], v[230:233], v[0:3]
	s_setprio 0
	s_barrier
	ds_read_b128 v[144:147], v171
	ds_read_b128 v[156:159], v171 offset:1024
	ds_read_b128 v[174:177], v171 offset:2048
	ds_read_b128 v[178:181], v171 offset:3072
	ds_read_b128 v[182:185], v173
	ds_read_b128 v[186:189], v173 offset:1024
	ds_read_b128 v[190:193], v173 offset:2048
	ds_read_b128 v[194:197], v173 offset:3072
	s_add_u32 s34, s34, 0x40000
	s_addc_u32 s35, s35, 0
	s_mov_b32 m0, s5
	ds_read_b128 v[198:201], v165 offset:32768
	ds_read_b128 v[202:205], v165 offset:33792
	ds_read_b128 v[206:209], v165 offset:34816
	ds_read_b128 v[214:217], v165 offset:35840
	ds_read_b128 v[218:221], v165 offset:36864
	ds_read_b128 v[222:225], v165 offset:37888
	ds_read_b128 v[226:229], v165 offset:38912
	ds_read_b128 v[230:233], v165 offset:39936
	global_load_lds_dwordx4 v134, s[34:35]
	s_mov_b32 m0, s19
	s_nop 0
	global_load_lds_dwordx4 v130, s[34:35]
	s_waitcnt vmcnt(8)
	s_waitcnt lgkmcnt(0)
	s_barrier
	s_setprio 1
	s_waitcnt lgkmcnt(0)
	v_mfma_f32_16x16x32_bf16 v[124:127], v[144:147], v[198:201], v[124:127]
	v_mfma_f32_16x16x32_bf16 v[120:123], v[174:177], v[198:201], v[120:123]
	v_mfma_f32_16x16x32_bf16 v[108:111], v[144:147], v[206:209], v[108:111]
	v_mfma_f32_16x16x32_bf16 v[104:107], v[174:177], v[206:209], v[104:107]
	v_mfma_f32_16x16x32_bf16 v[92:95], v[144:147], v[218:221], v[92:95]
	v_mfma_f32_16x16x32_bf16 v[88:91], v[174:177], v[218:221], v[88:91]
	v_mfma_f32_16x16x32_bf16 v[76:79], v[144:147], v[226:229], v[76:79]
	v_mfma_f32_16x16x32_bf16 v[72:75], v[174:177], v[226:229], v[72:75]
	v_mfma_f32_16x16x32_bf16 v[124:127], v[156:159], v[202:205], v[124:127]
	v_mfma_f32_16x16x32_bf16 v[120:123], v[178:181], v[202:205], v[120:123]
	v_mfma_f32_16x16x32_bf16 v[108:111], v[156:159], v[214:217], v[108:111]
	v_mfma_f32_16x16x32_bf16 v[104:107], v[178:181], v[214:217], v[104:107]
	v_mfma_f32_16x16x32_bf16 v[92:95], v[156:159], v[222:225], v[92:95]
	v_mfma_f32_16x16x32_bf16 v[88:91], v[178:181], v[222:225], v[88:91]
	v_mfma_f32_16x16x32_bf16 v[76:79], v[156:159], v[230:233], v[76:79]
	v_mfma_f32_16x16x32_bf16 v[72:75], v[178:181], v[230:233], v[72:75]
	s_setprio 0
	s_setprio 1
	v_mfma_f32_16x16x32_bf16 v[116:119], v[182:185], v[198:201], v[116:119]
	v_mfma_f32_16x16x32_bf16 v[112:115], v[190:193], v[198:201], v[112:115]
	v_mfma_f32_16x16x32_bf16 v[100:103], v[182:185], v[206:209], v[100:103]
	v_mfma_f32_16x16x32_bf16 v[96:99], v[190:193], v[206:209], v[96:99]
	v_mfma_f32_16x16x32_bf16 v[84:87], v[182:185], v[218:221], v[84:87]
	v_mfma_f32_16x16x32_bf16 v[80:83], v[190:193], v[218:221], v[80:83]
	v_mfma_f32_16x16x32_bf16 v[68:71], v[182:185], v[226:229], v[68:71]
	v_mfma_f32_16x16x32_bf16 v[64:67], v[190:193], v[226:229], v[64:67]
	v_mfma_f32_16x16x32_bf16 v[116:119], v[186:189], v[202:205], v[116:119]
	v_mfma_f32_16x16x32_bf16 v[112:115], v[194:197], v[202:205], v[112:115]
	v_mfma_f32_16x16x32_bf16 v[100:103], v[186:189], v[214:217], v[100:103]
	v_mfma_f32_16x16x32_bf16 v[96:99], v[194:197], v[214:217], v[96:99]
	v_mfma_f32_16x16x32_bf16 v[84:87], v[186:189], v[222:225], v[84:87]
	v_mfma_f32_16x16x32_bf16 v[80:83], v[194:197], v[222:225], v[80:83]
	v_mfma_f32_16x16x32_bf16 v[68:71], v[186:189], v[230:233], v[68:71]
	v_mfma_f32_16x16x32_bf16 v[64:67], v[194:197], v[230:233], v[64:67]
	s_setprio 0
	s_barrier
; #define PG8_STAGE(bufoff, gbase, voff) do { _Pragma("unroll") for (int _i = 0; _i < 2; ++_i) \
;     __builtin_amdgcn_global_load_lds((const unsigned*)((const char*)(gbase) + (voff)[_i]), (PG8_LAS unsigned*)(lds + (bufoff) + ldsw + _i * 8192), 16, 0, 0); } while (0)
; #define PG8_LDA(dst, b, h) do { _Pragma("unroll") for (int m = 0; m < 4; ++m) _Pragma("unroll") for (int k = 0; k < 2; ++k) dst[m][k] = *(const PG8_LAS bf16x8*)(lds + PG8_SA(b, h) + aoff + m * 2048 + k * 1024); } while (0)
; #define PG8_MMA(ai, bj, At, Bt) do { __builtin_amdgcn_s_setprio(1); _Pragma("unroll") for (int m = 0; m < 4; ++m) _Pragma("unroll") for (int n = 0; n < 2; ++n) _Pragma("unroll") for (int k = 0; k < 2; ++k) \
;     acc[ai][bj][m][n] = __builtin_amdgcn_mfma_f32_16x16x32_bf16(Bt[n][k], At[m][k], acc[ai][bj][m][n], 0, 0, 0); __builtin_amdgcn_s_setprio(0); } while (0)
; #define PG8_WAIT_V(n) asm volatile("s_waitcnt vmcnt(" #n ")" ::: "memory")
; #define PG8_WAIT_L(n) asm volatile("s_waitcnt lgkmcnt(" #n ")" ::: "memory")
; #define PG8_BAR __builtin_amdgcn_s_barrier()
; #define PG8_SCHED __builtin_amdgcn_sched_barrier(0)
; DI void rows_rstd(float (&rs)[2][4], const float* ps, const Unit& u, int wr, int fr, int fq, int p_lo, int p_hi, float inv_dim) {
;   f32x4 pv[2][4];
; #pragma unroll
;   for (int ai = 0; ai < 2; ++ai)
; #pragma unroll
;     for (int m = 0; m < 4; ++m) pv[ai][m] = *(const f32x4*)(ps + (size_t)(u.pm * BM + ai * HALF + wr * 64 + m * 16 + fr) * 16 + 4 * fq);
;   const bool use = (4 * fq >= p_lo) && (4 * fq < p_hi);
; template <class Epi, class Sched>
; DI void gemm_phase(PG8_LAS unsigned char* lds, const Gemm g, const Sched& S, const Epi& E) {
;     ...
;       PG8_LDA(At, 1, 1); PG8_STAGE(PG8_SB(1, 0), b3, voffB); PG8_STAGE(PG8_SB(1, 1), b3 + hstepB, voffB); PG8_STAGE(PG8_SA(1, 0), a3, voffA);
;       PG8_WAIT_V(8); PG8_WAIT_L(0); PG8_BAR; PG8_MMA(1, 0, At, B0); PG8_MMA(1, 1, At, B1); PG8_BAR; PG8_SCHED;
;     }
;     if (wr == 0) PG8_BAR;
	s_add_i32 s34, s41, s15
	v_lshl_add_u64 v[148:149], v[148:149], 0, s[8:9]
	s_mov_b32 m0, s34
	ds_read_b128 v[198:201], v165 offset:49152
	ds_read_b128 v[202:205], v165 offset:50176
	ds_read_b128 v[206:209], v165 offset:51200
	ds_read_b128 v[214:217], v165 offset:52224
	ds_read_b128 v[218:221], v165 offset:53248
	ds_read_b128 v[222:225], v165 offset:54272
	ds_read_b128 v[226:229], v165 offset:55296
	ds_read_b128 v[230:233], v165 offset:56320
	global_load_lds_dwordx4 v[148:149], off
	s_add_i32 m0, s34, 0x2000
	s_add_u32 s30, s30, 0x40080
	v_lshl_add_u64 v[148:149], v[152:153], 0, s[8:9]
	s_addc_u32 s31, s31, 0
	s_add_i32 s34, s44, s15
	global_load_lds_dwordx4 v[148:149], off
	s_mov_b32 m0, s34
	s_nop 0
	global_load_lds_dwordx4 v132, s[30:31]
	s_add_i32 m0, s34, 0x2000
	s_nop 0
	global_load_lds_dwordx4 v128, s[30:31]
	v_lshl_add_u64 v[148:149], v[162:163], 0, s[8:9]
	s_mov_b32 m0, s33
	s_nop 0
	global_load_lds_dwordx4 v[148:149], off
	v_lshl_add_u64 v[148:149], v[166:167], 0, s[8:9]
	s_mov_b32 m0, s36
	s_nop 0
	global_load_lds_dwordx4 v[148:149], off
	s_waitcnt vmcnt(8)
	s_waitcnt lgkmcnt(0)
	s_barrier
	s_setprio 1
	s_waitcnt lgkmcnt(0)
	v_mfma_f32_16x16x32_bf16 v[60:63], v[144:147], v[198:201], v[60:63]
	v_mfma_f32_16x16x32_bf16 v[56:59], v[174:177], v[198:201], v[56:59]
	v_mfma_f32_16x16x32_bf16 v[44:47], v[144:147], v[206:209], v[44:47]
	v_mfma_f32_16x16x32_bf16 v[40:43], v[174:177], v[206:209], v[40:43]
	v_mfma_f32_16x16x32_bf16 v[28:31], v[144:147], v[218:221], v[28:31]
	v_mfma_f32_16x16x32_bf16 v[24:27], v[174:177], v[218:221], v[24:27]
	v_mfma_f32_16x16x32_bf16 v[12:15], v[144:147], v[226:229], v[12:15]
	v_mfma_f32_16x16x32_bf16 v[8:11], v[174:177], v[226:229], v[8:11]
	v_mfma_f32_16x16x32_bf16 v[60:63], v[156:159], v[202:205], v[60:63]
	v_mfma_f32_16x16x32_bf16 v[56:59], v[178:181], v[202:205], v[56:59]
	v_mfma_f32_16x16x32_bf16 v[44:47], v[156:159], v[214:217], v[44:47]
	v_mfma_f32_16x16x32_bf16 v[40:43], v[178:181], v[214:217], v[40:43]
	v_mfma_f32_16x16x32_bf16 v[28:31], v[156:159], v[222:225], v[28:31]
	v_mfma_f32_16x16x32_bf16 v[24:27], v[178:181], v[222:225], v[24:27]
	v_mfma_f32_16x16x32_bf16 v[12:15], v[156:159], v[230:233], v[12:15]
	v_mfma_f32_16x16x32_bf16 v[8:11], v[178:181], v[230:233], v[8:11]
	s_setprio 0
	s_setprio 1
	v_mfma_f32_16x16x32_bf16 v[52:55], v[182:185], v[198:201], v[52:55]
	v_mfma_f32_16x16x32_bf16 v[48:51], v[190:193], v[198:201], v[48:51]
	v_mfma_f32_16x16x32_bf16 v[36:39], v[182:185], v[206:209], v[36:39]
	v_mfma_f32_16x16x32_bf16 v[32:35], v[190:193], v[206:209], v[32:35]
	v_mfma_f32_16x16x32_bf16 v[20:23], v[182:185], v[218:221], v[20:23]
	v_mfma_f32_16x16x32_bf16 v[16:19], v[190:193], v[218:221], v[16:19]
	v_mfma_f32_16x16x32_bf16 v[4:7], v[182:185], v[226:229], v[4:7]
	v_mfma_f32_16x16x32_bf16 v[0:3], v[190:193], v[226:229], v[0:3]
	v_mfma_f32_16x16x32_bf16 v[52:55], v[186:189], v[202:205], v[52:55]
	v_mfma_f32_16x16x32_bf16 v[48:51], v[194:197], v[202:205], v[48:51]
	v_mfma_f32_16x16x32_bf16 v[36:39], v[186:189], v[214:217], v[36:39]
	v_mfma_f32_16x16x32_bf16 v[32:35], v[194:197], v[214:217], v[32:35]
	v_mfma_f32_16x16x32_bf16 v[20:23], v[186:189], v[222:225], v[20:23]
	v_mfma_f32_16x16x32_bf16 v[16:19], v[194:197], v[222:225], v[16:19]
	v_mfma_f32_16x16x32_bf16 v[4:7], v[186:189], v[230:233], v[4:7]
	v_mfma_f32_16x16x32_bf16 v[0:3], v[194:197], v[230:233], v[0:3]
	s_setprio 0
	s_barrier
	s_add_i32 s55, s55, 2
	s_add_u32 s2, s2, 0x100
	s_addc_u32 s3, s3, 0
	s_add_u32 s53, s53, 0x100
	s_addc_u32 s54, s54, 0
	s_cmp_gt_u32 s55, 13
	s_cbranch_scc0 .LBB0_1384
	v_lshl_add_u32 v166, s0, 8, v151
	v_or_b32_e32 v162, 16, v166
	v_ashrrev_i32_e32 v167, 31, v166
	v_ashrrev_i32_e32 v163, 31, v162
	v_or_b32_e32 v158, 32, v166
	v_lshlrev_b64 v[146:147], 6, v[166:167]
	v_lshlrev_b64 v[144:145], 6, v[162:163]
	v_ashrrev_i32_e32 v159, 31, v158
	v_lshl_add_u64 v[146:147], v[138:139], 0, v[146:147]
	v_or_b32_e32 v156, 48, v166
	v_lshl_add_u64 v[144:145], v[138:139], 0, v[144:145]
	global_load_dwordx4 v[174:177], v[146:147], off
	v_lshlrev_b64 v[146:147], 6, v[158:159]
	v_ashrrev_i32_e32 v157, 31, v156
	v_lshl_add_u64 v[146:147], v[138:139], 0, v[146:147]
	global_load_dwordx4 v[178:181], v[144:145], off
	global_load_dwordx4 v[182:185], v[146:147], off
	v_lshlrev_b64 v[144:145], 6, v[156:157]
	v_lshl_add_u64 v[144:145], v[138:139], 0, v[144:145]
	global_load_dwordx4 v[186:189], v[144:145], off
	v_add_u32_e32 v152, 0x80, v166
	v_ashrrev_i32_e32 v153, 31, v152
	v_lshlrev_b64 v[144:145], 6, v[152:153]
	v_add_u32_e32 v148, 0x90, v166
	v_lshl_add_u64 v[144:145], v[138:139], 0, v[144:145]
	v_ashrrev_i32_e32 v149, 31, v148
	global_load_dwordx4 v[190:193], v[144:145], off
	v_lshlrev_b64 v[144:145], 6, v[148:149]
	v_lshl_add_u64 v[144:145], v[138:139], 0, v[144:145]
	global_load_dwordx4 v[194:197], v[144:145], off
	v_add_u32_e32 v144, 0xb0, v166
	v_ashrrev_i32_e32 v145, 31, v144
	v_lshlrev_b64 v[146:147], 6, v[144:145]
	v_lshl_add_u64 v[146:147], v[138:139], 0, v[146:147]
	global_load_dwordx4 v[198:201], v[146:147], off
	v_and_b32_e32 v147, 64, v169
	v_add_u32_e32 v146, 0xa0, v166
	v_add_u32_e32 v150, 64, v147
	v_ashrrev_i32_e32 v147, 31, v146
	v_lshlrev_b64 v[202:203], 6, v[146:147]
	v_lshl_add_u64 v[202:203], v[138:139], 0, v[202:203]
	global_load_dwordx4 v[202:205], v[202:203], off
	s_and_b64 vcc, exec, s[10:11]
	s_cbranch_vccz .LBB0_1387
	s_barrier

; #define PG8_STAGE(bufoff, gbase, voff) do { _Pragma("unroll") for (int _i = 0; _i < 2; ++_i) \
;     __builtin_amdgcn_global_load_lds((const unsigned*)((const char*)(gbase) + (voff)[_i]), (PG8_LAS unsigned*)(lds + (bufoff) + ldsw + _i * 8192), 16, 0, 0); } while (0)
; #define PG8_LDA(dst, b, h) do { _Pragma("unroll") for (int m = 0; m < 4; ++m) _Pragma("unroll") for (int k = 0; k < 2; ++k) dst[m][k] = *(const PG8_LAS bf16x8*)(lds + PG8_SA(b, h) + aoff + m * 2048 + k * 1024); } while (0)
; #define PG8_LDB(dst, b, h) do { _Pragma("unroll") for (int n = 0; n < 2; ++n) _Pragma("unroll") for (int k = 0; k < 2; ++k) dst[n][k] = *(const PG8_LAS bf16x8*)(lds + PG8_SB(b, h) + boff + n * 2048 + k * 1024); } while (0)
; #define PG8_MMA(ai, bj, At, Bt) do { __builtin_amdgcn_s_setprio(1); _Pragma("unroll") for (int m = 0; m < 4; ++m) _Pragma("unroll") for (int n = 0; n < 2; ++n) _Pragma("unroll") for (int k = 0; k < 2; ++k) \
;     acc[ai][bj][m][n] = __builtin_amdgcn_mfma_f32_16x16x32_bf16(Bt[n][k], At[m][k], acc[ai][bj][m][n], 0, 0, 0); __builtin_amdgcn_s_setprio(0); } while (0)
; #define PG8_WAIT_V(n) asm volatile("s_waitcnt vmcnt(" #n ")" ::: "memory")
; #define PG8_WAIT_L(n) asm volatile("s_waitcnt lgkmcnt(" #n ")" ::: "memory")
; #define PG8_BAR __builtin_amdgcn_s_barrier()
; #define PG8_SCHED __builtin_amdgcn_sched_barrier(0)
; template <class Epi, class Sched>
; DI void gemm_phase(PG8_LAS unsigned char* lds, const Gemm g, const Sched& S, const Epi& E) {
;     ...
;     for (int t = 0; t < nt; t += 2) {
;       const bool last = (t == nt - 2);
;       const char* a1 = cA + (size_t)(t + 1) * kstep;
;       const char* a2 = last ? nA : cA + (size_t)(t + 2) * kstep; const char* b2 = last ? nB : cB + (size_t)(t + 2) * kstep;
;       const char* a3 = a2 + kstep; const char* b3 = b2 + kstep;
;       PG8_LDB(B0, 0, 0); PG8_LDB(B1, 0, 1); PG8_SCHED; PG8_LDA(At, 0, 0); PG8_STAGE(PG8_SA(1, 1), a1 + hstepA, voffA);
;       PG8_WAIT_V(8); PG8_WAIT_L(0); PG8_BAR; PG8_MMA(0, 0, At, B0); PG8_MMA(0, 1, At, B1); PG8_BAR; PG8_SCHED;
;       PG8_LDA(At, 0, 1); PG8_STAGE(PG8_SB(0, 0), b2, voffB); PG8_STAGE(PG8_SB(0, 1), b2 + hstepB, voffB); PG8_STAGE(PG8_SA(0, 0), a2, voffA);
;       PG8_WAIT_V(8); PG8_WAIT_L(0); PG8_BAR; PG8_MMA(1, 0, At, B0); PG8_MMA(1, 1, At, B1); PG8_BAR; PG8_SCHED;
.LBB0_1456:
	ds_read_b128 v[150:153], v145
	ds_read_b128 v[154:157], v145 offset:1024
	ds_read_b128 v[158:161], v145 offset:2048
	ds_read_b128 v[162:165], v145 offset:3072
	ds_read_b128 v[166:169], v146
	ds_read_b128 v[170:173], v146 offset:1024
	ds_read_b128 v[174:177], v146 offset:2048
	ds_read_b128 v[178:181], v146 offset:3072
	s_add_u32 s14, s12, 0x100
	s_addc_u32 s15, s13, 0
	s_cmp_eq_u32 s60, 40
	s_cselect_b32 s19, s9, s15
	s_cselect_b32 s18, s8, s14
	s_cselect_b32 s17, s11, s59
	s_cselect_b32 s16, s10, s58
	s_mov_b32 m0, s49
	ds_read_b128 v[182:185], v147
	ds_read_b128 v[186:189], v147 offset:1024
	ds_read_b128 v[190:193], v147 offset:2048
	ds_read_b128 v[194:197], v147 offset:3072
	ds_read_b128 v[198:201], v147 offset:4096
	ds_read_b128 v[202:205], v147 offset:5120
	ds_read_b128 v[206:209], v147 offset:6144
	ds_read_b128 v[210:213], v147 offset:7168
	global_load_lds_dwordx4 v138, s[12:13]
	s_mov_b32 m0, s52
	s_nop 0
	global_load_lds_dwordx4 v140, s[12:13]
	s_waitcnt vmcnt(8)
	s_waitcnt lgkmcnt(0)
	s_barrier
	s_setprio 1
	s_waitcnt lgkmcnt(0)
	v_mfma_f32_16x16x32_bf16 v[124:127], v[150:153], v[182:185], v[124:127]
	v_mfma_f32_16x16x32_bf16 v[120:123], v[158:161], v[182:185], v[120:123]
	v_mfma_f32_16x16x32_bf16 v[108:111], v[150:153], v[190:193], v[108:111]
	v_mfma_f32_16x16x32_bf16 v[104:107], v[158:161], v[190:193], v[104:107]
	v_mfma_f32_16x16x32_bf16 v[92:95], v[150:153], v[198:201], v[92:95]
	v_mfma_f32_16x16x32_bf16 v[88:91], v[158:161], v[198:201], v[88:91]
	v_mfma_f32_16x16x32_bf16 v[76:79], v[150:153], v[206:209], v[76:79]
	v_mfma_f32_16x16x32_bf16 v[72:75], v[158:161], v[206:209], v[72:75]
	v_mfma_f32_16x16x32_bf16 v[124:127], v[154:157], v[186:189], v[124:127]
	v_mfma_f32_16x16x32_bf16 v[120:123], v[162:165], v[186:189], v[120:123]
	v_mfma_f32_16x16x32_bf16 v[108:111], v[154:157], v[194:197], v[108:111]
	v_mfma_f32_16x16x32_bf16 v[104:107], v[162:165], v[194:197], v[104:107]
	v_mfma_f32_16x16x32_bf16 v[92:95], v[154:157], v[202:205], v[92:95]
	v_mfma_f32_16x16x32_bf16 v[88:91], v[162:165], v[202:205], v[88:91]
	v_mfma_f32_16x16x32_bf16 v[76:79], v[154:157], v[210:213], v[76:79]
	v_mfma_f32_16x16x32_bf16 v[72:75], v[162:165], v[210:213], v[72:75]
	s_setprio 0
	s_setprio 1
	v_mfma_f32_16x16x32_bf16 v[116:119], v[166:169], v[182:185], v[116:119]
	v_mfma_f32_16x16x32_bf16 v[112:115], v[174:177], v[182:185], v[112:115]
	v_mfma_f32_16x16x32_bf16 v[100:103], v[166:169], v[190:193], v[100:103]
	v_mfma_f32_16x16x32_bf16 v[96:99], v[174:177], v[190:193], v[96:99]
	v_mfma_f32_16x16x32_bf16 v[84:87], v[166:169], v[198:201], v[84:87]
	v_mfma_f32_16x16x32_bf16 v[80:83], v[174:177], v[198:201], v[80:83]
	v_mfma_f32_16x16x32_bf16 v[68:71], v[166:169], v[206:209], v[68:71]
	v_mfma_f32_16x16x32_bf16 v[64:67], v[174:177], v[206:209], v[64:67]
	v_mfma_f32_16x16x32_bf16 v[116:119], v[170:173], v[186:189], v[116:119]
	v_mfma_f32_16x16x32_bf16 v[112:115], v[178:181], v[186:189], v[112:115]
	v_mfma_f32_16x16x32_bf16 v[100:103], v[170:173], v[194:197], v[100:103]
	v_mfma_f32_16x16x32_bf16 v[96:99], v[178:181], v[194:197], v[96:99]
	v_mfma_f32_16x16x32_bf16 v[84:87], v[170:173], v[202:205], v[84:87]
	v_mfma_f32_16x16x32_bf16 v[80:83], v[178:181], v[202:205], v[80:83]
	v_mfma_f32_16x16x32_bf16 v[68:71], v[170:173], v[210:213], v[68:71]
	v_mfma_f32_16x16x32_bf16 v[64:67], v[178:181], v[210:213], v[64:67]
	s_setprio 0
	s_barrier
	s_add_i32 s12, s33, s20
	v_lshl_add_u64 v[142:143], s[16:17], 0, v[132:133]
	s_mov_b32 m0, s12
	ds_read_b128 v[182:185], v147 offset:16384
	ds_read_b128 v[186:189], v147 offset:17408
	ds_read_b128 v[190:193], v147 offset:18432
	ds_read_b128 v[194:197], v147 offset:19456
	ds_read_b128 v[198:201], v147 offset:20480
	ds_read_b128 v[202:205], v147 offset:21504
	ds_read_b128 v[206:209], v147 offset:22528
	ds_read_b128 v[210:213], v147 offset:23552
	global_load_lds_dwordx4 v[142:143], off
	s_add_i32 m0, s12, 0x2000
	s_add_u32 s12, s16, 0xb0000
	v_lshl_add_u64 v[214:215], s[16:17], 0, v[128:129]
	s_addc_u32 s13, s17, 0
	s_add_i32 s61, s34, s20
	global_load_lds_dwordx4 v[214:215], off
	s_mov_b32 m0, s61
	v_lshl_add_u64 v[218:219], s[18:19], 0, v[130:131]
	global_load_lds_dwordx4 v132, s[12:13]
	s_add_i32 m0, s61, 0x2000
	s_nop 0
	global_load_lds_dwordx4 v128, s[12:13]
	v_lshl_add_u64 v[216:217], s[18:19], 0, v[134:135]
	s_mov_b32 m0, s22
	s_nop 0
	global_load_lds_dwordx4 v[216:217], off
	s_mov_b32 m0, s23
	s_nop 0
	global_load_lds_dwordx4 v[218:219], off
	s_waitcnt vmcnt(8)
	s_waitcnt lgkmcnt(0)
	s_barrier
	s_setprio 1
	s_waitcnt lgkmcnt(0)
	v_mfma_f32_16x16x32_bf16 v[60:63], v[150:153], v[182:185], v[60:63]
	v_mfma_f32_16x16x32_bf16 v[56:59], v[158:161], v[182:185], v[56:59]
	v_mfma_f32_16x16x32_bf16 v[44:47], v[150:153], v[190:193], v[44:47]
	v_mfma_f32_16x16x32_bf16 v[40:43], v[158:161], v[190:193], v[40:43]
	v_mfma_f32_16x16x32_bf16 v[28:31], v[150:153], v[198:201], v[28:31]
	v_mfma_f32_16x16x32_bf16 v[24:27], v[158:161], v[198:201], v[24:27]
	v_mfma_f32_16x16x32_bf16 v[16:19], v[150:153], v[206:209], v[16:19]
	v_mfma_f32_16x16x32_bf16 v[8:11], v[158:161], v[206:209], v[8:11]
	v_mfma_f32_16x16x32_bf16 v[60:63], v[154:157], v[186:189], v[60:63]
	v_mfma_f32_16x16x32_bf16 v[56:59], v[162:165], v[186:189], v[56:59]
	v_mfma_f32_16x16x32_bf16 v[44:47], v[154:157], v[194:197], v[44:47]
	v_mfma_f32_16x16x32_bf16 v[40:43], v[162:165], v[194:197], v[40:43]
	v_mfma_f32_16x16x32_bf16 v[28:31], v[154:157], v[202:205], v[28:31]
	v_mfma_f32_16x16x32_bf16 v[24:27], v[162:165], v[202:205], v[24:27]
	v_mfma_f32_16x16x32_bf16 v[16:19], v[154:157], v[210:213], v[16:19]
	v_mfma_f32_16x16x32_bf16 v[8:11], v[162:165], v[210:213], v[8:11]
	s_setprio 0
	s_setprio 1
	v_mfma_f32_16x16x32_bf16 v[52:55], v[166:169], v[182:185], v[52:55]
	v_mfma_f32_16x16x32_bf16 v[48:51], v[174:177], v[182:185], v[48:51]
	v_mfma_f32_16x16x32_bf16 v[36:39], v[166:169], v[190:193], v[36:39]
	v_mfma_f32_16x16x32_bf16 v[32:35], v[174:177], v[190:193], v[32:35]
	v_mfma_f32_16x16x32_bf16 v[20:23], v[166:169], v[198:201], v[20:23]
	v_mfma_f32_16x16x32_bf16 v[12:15], v[174:177], v[198:201], v[12:15]
	v_mfma_f32_16x16x32_bf16 v[4:7], v[166:169], v[206:209], v[4:7]
	v_mfma_f32_16x16x32_bf16 v[0:3], v[174:177], v[206:209], v[0:3]
	v_mfma_f32_16x16x32_bf16 v[52:55], v[170:173], v[186:189], v[52:55]
	v_mfma_f32_16x16x32_bf16 v[48:51], v[178:181], v[186:189], v[48:51]
	v_mfma_f32_16x16x32_bf16 v[36:39], v[170:173], v[194:197], v[36:39]
	v_mfma_f32_16x16x32_bf16 v[32:35], v[178:181], v[194:197], v[32:35]
	v_mfma_f32_16x16x32_bf16 v[20:23], v[170:173], v[202:205], v[20:23]
	v_mfma_f32_16x16x32_bf16 v[12:15], v[178:181], v[202:205], v[12:15]
	v_mfma_f32_16x16x32_bf16 v[4:7], v[170:173], v[210:213], v[4:7]
	v_mfma_f32_16x16x32_bf16 v[0:3], v[178:181], v[210:213], v[0:3]
	s_setprio 0
	s_barrier
; #define PG8_STAGE(bufoff, gbase, voff) do { _Pragma("unroll") for (int _i = 0; _i < 2; ++_i) \
;     __builtin_amdgcn_global_load_lds((const unsigned*)((const char*)(gbase) + (voff)[_i]), (PG8_LAS unsigned*)(lds + (bufoff) + ldsw + _i * 8192), 16, 0, 0); } while (0)
; #define PG8_LDA(dst, b, h) do { _Pragma("unroll") for (int m = 0; m < 4; ++m) _Pragma("unroll") for (int k = 0; k < 2; ++k) dst[m][k] = *(const PG8_LAS bf16x8*)(lds + PG8_SA(b, h) + aoff + m * 2048 + k * 1024); } while (0)
; #define PG8_LDB(dst, b, h) do { _Pragma("unroll") for (int n = 0; n < 2; ++n) _Pragma("unroll") for (int k = 0; k < 2; ++k) dst[n][k] = *(const PG8_LAS bf16x8*)(lds + PG8_SB(b, h) + boff + n * 2048 + k * 1024); } while (0)
; #define PG8_MMA(ai, bj, At, Bt) do { __builtin_amdgcn_s_setprio(1); _Pragma("unroll") for (int m = 0; m < 4; ++m) _Pragma("unroll") for (int n = 0; n < 2; ++n) _Pragma("unroll") for (int k = 0; k < 2; ++k) \
;     acc[ai][bj][m][n] = __builtin_amdgcn_mfma_f32_16x16x32_bf16(Bt[n][k], At[m][k], acc[ai][bj][m][n], 0, 0, 0); __builtin_amdgcn_s_setprio(0); } while (0)
; #define PG8_WAIT_V(n) asm volatile("s_waitcnt vmcnt(" #n ")" ::: "memory")
; #define PG8_WAIT_L(n) asm volatile("s_waitcnt lgkmcnt(" #n ")" ::: "memory")
; #define PG8_BAR __builtin_amdgcn_s_barrier()
; #define PG8_SCHED __builtin_amdgcn_sched_barrier(0)
; template <class Epi, class Sched>
; DI void gemm_phase(PG8_LAS unsigned char* lds, const Gemm g, const Sched& S, const Epi& E) {
;     ...
;       PG8_LDB(B0, 1, 0); PG8_LDB(B1, 1, 1); PG8_SCHED; PG8_LDA(At, 1, 0); PG8_STAGE(PG8_SA(0, 1), a2 + hstepA, voffA);
;       PG8_WAIT_V(8); PG8_WAIT_L(0); PG8_BAR; PG8_MMA(0, 0, At, B0); PG8_MMA(0, 1, At, B1); PG8_BAR; PG8_SCHED;
	s_add_i32 s61, s30, 0x110
	v_add_u32_e32 v149, s61, v144
	ds_read_b128 v[150:153], v149
	ds_read_b128 v[154:157], v149 offset:1024
	ds_read_b128 v[158:161], v149 offset:2048
	ds_read_b128 v[162:165], v149 offset:3072
	ds_read_b128 v[166:169], v148
	ds_read_b128 v[170:173], v148 offset:1024
	ds_read_b128 v[174:177], v148 offset:2048
	ds_read_b128 v[178:181], v148 offset:3072
	s_add_u32 s12, s18, 0xb0000
	s_addc_u32 s13, s19, 0
	s_mov_b32 m0, s24
	ds_read_b128 v[182:185], v147 offset:32768
	ds_read_b128 v[186:189], v147 offset:33792
	ds_read_b128 v[190:193], v147 offset:34816
	ds_read_b128 v[194:197], v147 offset:35840
	ds_read_b128 v[198:201], v147 offset:36864
	ds_read_b128 v[202:205], v147 offset:37888
	ds_read_b128 v[206:209], v147 offset:38912
	ds_read_b128 v[210:213], v147 offset:39936
	global_load_lds_dwordx4 v134, s[12:13]
	s_mov_b32 m0, s25
	s_nop 0
	global_load_lds_dwordx4 v130, s[12:13]
	s_waitcnt vmcnt(8)
	s_waitcnt lgkmcnt(0)
	s_barrier
	s_setprio 1
	s_waitcnt lgkmcnt(0)
	v_mfma_f32_16x16x32_bf16 v[124:127], v[150:153], v[182:185], v[124:127]
	v_mfma_f32_16x16x32_bf16 v[120:123], v[158:161], v[182:185], v[120:123]
	v_mfma_f32_16x16x32_bf16 v[108:111], v[150:153], v[190:193], v[108:111]
	v_mfma_f32_16x16x32_bf16 v[104:107], v[158:161], v[190:193], v[104:107]
	v_mfma_f32_16x16x32_bf16 v[92:95], v[150:153], v[198:201], v[92:95]
	v_mfma_f32_16x16x32_bf16 v[88:91], v[158:161], v[198:201], v[88:91]
	v_mfma_f32_16x16x32_bf16 v[76:79], v[150:153], v[206:209], v[76:79]
	v_mfma_f32_16x16x32_bf16 v[72:75], v[158:161], v[206:209], v[72:75]
	v_mfma_f32_16x16x32_bf16 v[124:127], v[154:157], v[186:189], v[124:127]
	v_mfma_f32_16x16x32_bf16 v[120:123], v[162:165], v[186:189], v[120:123]
	v_mfma_f32_16x16x32_bf16 v[108:111], v[154:157], v[194:197], v[108:111]
	v_mfma_f32_16x16x32_bf16 v[104:107], v[162:165], v[194:197], v[104:107]
	v_mfma_f32_16x16x32_bf16 v[92:95], v[154:157], v[202:205], v[92:95]
	v_mfma_f32_16x16x32_bf16 v[88:91], v[162:165], v[202:205], v[88:91]
	v_mfma_f32_16x16x32_bf16 v[76:79], v[154:157], v[210:213], v[76:79]
	v_mfma_f32_16x16x32_bf16 v[72:75], v[162:165], v[210:213], v[72:75]
	s_setprio 0
	s_setprio 1
	v_mfma_f32_16x16x32_bf16 v[116:119], v[166:169], v[182:185], v[116:119]
	v_mfma_f32_16x16x32_bf16 v[112:115], v[174:177], v[182:185], v[112:115]
	v_mfma_f32_16x16x32_bf16 v[100:103], v[166:169], v[190:193], v[100:103]
	v_mfma_f32_16x16x32_bf16 v[96:99], v[174:177], v[190:193], v[96:99]
	v_mfma_f32_16x16x32_bf16 v[84:87], v[166:169], v[198:201], v[84:87]
	v_mfma_f32_16x16x32_bf16 v[80:83], v[174:177], v[198:201], v[80:83]
	v_mfma_f32_16x16x32_bf16 v[68:71], v[166:169], v[206:209], v[68:71]
	v_mfma_f32_16x16x32_bf16 v[64:67], v[174:177], v[206:209], v[64:67]
	v_mfma_f32_16x16x32_bf16 v[116:119], v[170:173], v[186:189], v[116:119]
	v_mfma_f32_16x16x32_bf16 v[112:115], v[178:181], v[186:189], v[112:115]
	v_mfma_f32_16x16x32_bf16 v[100:103], v[170:173], v[194:197], v[100:103]
	v_mfma_f32_16x16x32_bf16 v[96:99], v[178:181], v[194:197], v[96:99]
	v_mfma_f32_16x16x32_bf16 v[84:87], v[170:173], v[202:205], v[84:87]
	v_mfma_f32_16x16x32_bf16 v[80:83], v[178:181], v[202:205], v[80:83]
	v_mfma_f32_16x16x32_bf16 v[68:71], v[170:173], v[210:213], v[68:71]
	v_mfma_f32_16x16x32_bf16 v[64:67], v[178:181], v[210:213], v[64:67]
	s_setprio 0
	s_barrier
; #define PG8_STAGE(bufoff, gbase, voff) do { _Pragma("unroll") for (int _i = 0; _i < 2; ++_i) \
;     __builtin_amdgcn_global_load_lds((const unsigned*)((const char*)(gbase) + (voff)[_i]), (PG8_LAS unsigned*)(lds + (bufoff) + ldsw + _i * 8192), 16, 0, 0); } while (0)
; #define PG8_LDA(dst, b, h) do { _Pragma("unroll") for (int m = 0; m < 4; ++m) _Pragma("unroll") for (int k = 0; k < 2; ++k) dst[m][k] = *(const PG8_LAS bf16x8*)(lds + PG8_SA(b, h) + aoff + m * 2048 + k * 1024); } while (0)
; #define PG8_MMA(ai, bj, At, Bt) do { __builtin_amdgcn_s_setprio(1); _Pragma("unroll") for (int m = 0; m < 4; ++m) _Pragma("unroll") for (int n = 0; n < 2; ++n) _Pragma("unroll") for (int k = 0; k < 2; ++k) \
;     acc[ai][bj][m][n] = __builtin_amdgcn_mfma_f32_16x16x32_bf16(Bt[n][k], At[m][k], acc[ai][bj][m][n], 0, 0, 0); __builtin_amdgcn_s_setprio(0); } while (0)
; #define PG8_WAIT_V(n) asm volatile("s_waitcnt vmcnt(" #n ")" ::: "memory")
; #define PG8_WAIT_L(n) asm volatile("s_waitcnt lgkmcnt(" #n ")" ::: "memory")
; #define PG8_BAR __builtin_amdgcn_s_barrier()
; #define PG8_SCHED __builtin_amdgcn_sched_barrier(0)
;   DI void operator()(const f32x4 (&acc)[2][2][4][2], const Unit& u, int wr, int wc, int fr, int fq) const {
;     const int row0 = u.pm * BM + wr * 64 + fr;
;     const size_t base = (size_t)row0 * DM + u.pn * BM + wc * 32 + 8 * fq;
;     f32x4 xv[2][4];
;     u32x4 xh[2][2];
;     ...
;     RES_LD(0)
; #pragma unroll
;     for (int i = 0; i < 8; ++i) {
;       const int ai = i >> 2, m = i & 3;
;       if (i + 1 < 8) RES_LD(i + 1)
; template <class Epi, class Sched>
; DI void gemm_phase(PG8_LAS unsigned char* lds, const Gemm g, const Sched& S, const Epi& E) {
;     ...
;       PG8_LDA(At, 1, 1); PG8_STAGE(PG8_SB(1, 0), b3, voffB); PG8_STAGE(PG8_SB(1, 1), b3 + hstepB, voffB); PG8_STAGE(PG8_SA(1, 0), a3, voffA);
;       PG8_WAIT_V(8); PG8_WAIT_L(0); PG8_BAR; PG8_MMA(1, 0, At, B0); PG8_MMA(1, 1, At, B1); PG8_BAR; PG8_SCHED;
;     }
;     if (wr == 0) PG8_BAR;
	s_add_i32 s12, s61, s20
	v_lshl_add_u64 v[142:143], v[142:143], 0, s[4:5]
	s_mov_b32 m0, s12
	ds_read_b128 v[182:185], v147 offset:49152
	ds_read_b128 v[186:189], v147 offset:50176
	ds_read_b128 v[190:193], v147 offset:51200
	ds_read_b128 v[194:197], v147 offset:52224
	ds_read_b128 v[198:201], v147 offset:53248
	ds_read_b128 v[202:205], v147 offset:54272
	ds_read_b128 v[206:209], v147 offset:55296
	ds_read_b128 v[210:213], v147 offset:56320
	global_load_lds_dwordx4 v[142:143], off
	s_add_i32 m0, s12, 0x2000
	s_add_u32 s12, s16, 0xb0080
	v_lshl_add_u64 v[142:143], v[214:215], 0, s[4:5]
	s_addc_u32 s13, s17, 0
	s_add_i32 s16, s53, s20
	global_load_lds_dwordx4 v[142:143], off
	s_mov_b32 m0, s16
	s_nop 0
	global_load_lds_dwordx4 v132, s[12:13]
	s_add_i32 m0, s16, 0x2000
	s_nop 0
	global_load_lds_dwordx4 v128, s[12:13]
	v_lshl_add_u64 v[142:143], v[216:217], 0, s[4:5]
	s_mov_b32 m0, s28
	s_nop 0
	global_load_lds_dwordx4 v[142:143], off
	v_lshl_add_u64 v[142:143], v[218:219], 0, s[4:5]
	s_mov_b32 m0, s29
	s_nop 0
	global_load_lds_dwordx4 v[142:143], off
	s_waitcnt vmcnt(8)
	s_waitcnt lgkmcnt(0)
	s_barrier
	s_setprio 1
	s_waitcnt lgkmcnt(0)
	v_mfma_f32_16x16x32_bf16 v[60:63], v[150:153], v[182:185], v[60:63]
	v_mfma_f32_16x16x32_bf16 v[56:59], v[158:161], v[182:185], v[56:59]
	v_mfma_f32_16x16x32_bf16 v[44:47], v[150:153], v[190:193], v[44:47]
	v_mfma_f32_16x16x32_bf16 v[40:43], v[158:161], v[190:193], v[40:43]
	v_mfma_f32_16x16x32_bf16 v[28:31], v[150:153], v[198:201], v[28:31]
	v_mfma_f32_16x16x32_bf16 v[24:27], v[158:161], v[198:201], v[24:27]
	v_mfma_f32_16x16x32_bf16 v[16:19], v[150:153], v[206:209], v[16:19]
	v_mfma_f32_16x16x32_bf16 v[8:11], v[158:161], v[206:209], v[8:11]
	v_mfma_f32_16x16x32_bf16 v[60:63], v[154:157], v[186:189], v[60:63]
	v_mfma_f32_16x16x32_bf16 v[56:59], v[162:165], v[186:189], v[56:59]
	v_mfma_f32_16x16x32_bf16 v[44:47], v[154:157], v[194:197], v[44:47]
	v_mfma_f32_16x16x32_bf16 v[40:43], v[162:165], v[194:197], v[40:43]
	v_mfma_f32_16x16x32_bf16 v[28:31], v[154:157], v[202:205], v[28:31]
	v_mfma_f32_16x16x32_bf16 v[24:27], v[162:165], v[202:205], v[24:27]
	v_mfma_f32_16x16x32_bf16 v[16:19], v[154:157], v[210:213], v[16:19]
	v_mfma_f32_16x16x32_bf16 v[8:11], v[162:165], v[210:213], v[8:11]
	s_setprio 0
	s_setprio 1
	v_mfma_f32_16x16x32_bf16 v[52:55], v[166:169], v[182:185], v[52:55]
	v_mfma_f32_16x16x32_bf16 v[48:51], v[174:177], v[182:185], v[48:51]
	v_mfma_f32_16x16x32_bf16 v[36:39], v[166:169], v[190:193], v[36:39]
	v_mfma_f32_16x16x32_bf16 v[32:35], v[174:177], v[190:193], v[32:35]
	v_mfma_f32_16x16x32_bf16 v[20:23], v[166:169], v[198:201], v[20:23]
	v_mfma_f32_16x16x32_bf16 v[12:15], v[174:177], v[198:201], v[12:15]
	v_mfma_f32_16x16x32_bf16 v[4:7], v[166:169], v[206:209], v[4:7]
	v_mfma_f32_16x16x32_bf16 v[0:3], v[174:177], v[206:209], v[0:3]
	v_mfma_f32_16x16x32_bf16 v[52:55], v[170:173], v[186:189], v[52:55]
	v_mfma_f32_16x16x32_bf16 v[48:51], v[178:181], v[186:189], v[48:51]
	v_mfma_f32_16x16x32_bf16 v[36:39], v[170:173], v[194:197], v[36:39]
	v_mfma_f32_16x16x32_bf16 v[32:35], v[178:181], v[194:197], v[32:35]
	v_mfma_f32_16x16x32_bf16 v[20:23], v[170:173], v[202:205], v[20:23]
	v_mfma_f32_16x16x32_bf16 v[12:15], v[178:181], v[202:205], v[12:15]
	v_mfma_f32_16x16x32_bf16 v[4:7], v[170:173], v[210:213], v[4:7]
	v_mfma_f32_16x16x32_bf16 v[0:3], v[178:181], v[210:213], v[0:3]
	s_setprio 0
	s_barrier
	s_add_i32 s60, s60, 2
	s_add_u32 s58, s58, 0x100
	s_addc_u32 s59, s59, 0
	s_cmp_gt_u32 s60, 41
	s_mov_b64 s[12:13], s[14:15]
	s_cbranch_scc0 .LBB0_1456
	v_lshl_add_u32 v142, s57, 8, v137
	v_ashrrev_i32_e32 v143, 31, v142
	s_lshl_b32 s12, s56, 8
	v_lshlrev_b64 v[142:143], 10, v[142:143]
	s_ashr_i32 s13, s12, 31
	v_lshl_add_u64 v[166:167], v[142:143], 0, s[12:13]
	v_or_b32_e32 v166, v166, v136
	v_lshl_add_u64 v[142:143], v[166:167], 1, s[50:51]
	v_add_co_u32_e32 v162, vcc, s31, v142
	global_load_dwordx4 v[150:153], v[142:143], off
	global_load_dwordx4 v[154:157], v[142:143], off offset:256
	v_addc_co_u32_e32 v163, vcc, 0, v143, vcc
	global_load_dwordx4 v[158:161], v[162:163], off
	s_nop 0
	global_load_dwordx4 v[162:165], v[162:163], off offset:256
	s_and_b64 vcc, exec, s[6:7]
	s_cbranch_vccz .LBB0_1459
	s_barrier
